# GEMM K-loops: 38 redundant lgkmcnt(0) waits after the segment barrier removed (the wait right before each barrier already covers them)
# speedup vs baseline: 1.0044x; 1.0026x over previous
; #define PG8_STAGE(bufoff, gbase, voff) do { _Pragma("unroll") for (int _i = 0; _i < 2; ++_i) \
;         __builtin_amdgcn_global_load_lds((const unsigned*)((const char*)(gbase) + (voff)[_i]), (LAS unsigned*)(lds + (bufoff) + ldsw + _i * 8192), 16, 0, 0); } while (0)
; #define PG8_LDA(dst, b, h) do { _Pragma("unroll") for (int m = 0; m < 4; ++m) _Pragma("unroll") for (int k = 0; k < 2; ++k) dst[m][k] = *(const LAS bf16x8*)(lds + PG8_SA(b, h) + aoff + m * 2048 + k * 1024); } while (0)
; #define PG8_LDB(dst, b, h) do { _Pragma("unroll") for (int n = 0; n < 2; ++n) _Pragma("unroll") for (int k = 0; k < 2; ++k) dst[n][k] = *(const LAS bf16x8*)(lds + PG8_SB(b, h) + boff + n * 2048 + k * 1024); } while (0)
; #define PG8_WAIT_V(n) asm volatile("s_waitcnt vmcnt(" #n ")" ::: "memory")
; #define PG8_WAIT_L(n) asm volatile("s_waitcnt lgkmcnt(" #n ")" ::: "memory")
; template <class Epi>
; DI void gemm_phase(LAS unsigned char* lds, const Gemm g, const Order& S, const Epi& E) {
;     ...
;         for (int t = 0; t < nt; t += 2) {
;             const bool last = (t == nt - 2);
;             const char* a1 = cA + (size_t)(t + 1) * kstep;
;             const char* a2 = last ? nA : cA + (size_t)(t + 2) * kstep; const char* b2 = last ? nB : cB + (size_t)(t + 2) * kstep;
;             const char* a3 = a2 + kstep; const char* b3 = b2 + kstep;
;             PG8_LDB(B0, 0, 0); PG8_LDB(B1, 0, 1); PG8_SCHED; PG8_LDA(At, 0, 0); PG8_STAGE(PG8_SA(1, 1), a1 + hstepA, voffA);
;             PG8_WAIT_V(8); PG8_WAIT_L(0); PG8_BAR; PG8_MMA(0, 0, At, B0); PG8_MMA(0, 1, At, B1); PG8_BAR; PG8_SCHED;
;             PG8_LDA(At, 0, 1); PG8_STAGE(PG8_SB(0, 0), b2, voffB); PG8_STAGE(PG8_SB(0, 1), b2 + hstepB, voffB); PG8_STAGE(PG8_SA(0, 0), a2, voffA);
;             PG8_WAIT_V(8); PG8_WAIT_L(0); PG8_BAR; PG8_MMA(1, 0, At, B0); PG8_MMA(1, 1, At, B1); PG8_BAR; PG8_SCHED;
;             PG8_LDB(B0, 1, 0); PG8_LDB(B1, 1, 1); PG8_SCHED; PG8_LDA(At, 1, 0); PG8_STAGE(PG8_SA(0, 1), a2 + hstepA, voffA);
;             PG8_WAIT_V(8); PG8_WAIT_L(0); PG8_BAR; PG8_MMA(0, 0, At, B0); PG8_MMA(0, 1, At, B1); PG8_BAR; PG8_SCHED;
;             PG8_LDA(At, 1, 1); PG8_STAGE(PG8_SB(1, 0), b3, voffB); PG8_STAGE(PG8_SB(1, 1), b3 + hstepB, voffB); PG8_STAGE(PG8_SA(1, 0), a3, voffA);
;             PG8_WAIT_V(8); PG8_WAIT_L(0); PG8_BAR; PG8_MMA(1, 0, At, B0); PG8_MMA(1, 1, At, B1); PG8_BAR; PG8_SCHED;
;         }
.LBB0_261:
	s_add_i32 s82, s24, 2
	s_add_u32 s25, s22, 0xfff80080
	s_addc_u32 s26, s23, -1
	s_add_i32 s83, 0, 0x10000
	s_cmp_eq_u32 s79, s24
	s_cselect_b32 s27, s19, s26
	s_cselect_b32 s26, s18, s25
	s_cselect_b32 s25, s21, s17
	s_cselect_b32 s24, s20, s15
	s_add_i32 s86, 0, 0x14000
	v_add_u32_e32 v154, s83, v140
	v_add_u32_e32 v170, s86, v140
	ds_read_b128 v[142:145], v154
	ds_read_b128 v[146:149], v154 offset:1024
	ds_read_b128 v[150:153], v154 offset:2048
	ds_read_b128 v[154:157], v154 offset:3072
	ds_read_b128 v[158:161], v170
	ds_read_b128 v[162:165], v170 offset:1024
	ds_read_b128 v[166:169], v170 offset:2048
	ds_read_b128 v[170:173], v170 offset:3072
	v_lshl_add_u64 v[174:175], s[22:23], 0, v[136:137]
	s_add_i32 m0, s63, 0xc000
	ds_read_b128 v[178:181], v141
	ds_read_b128 v[182:185], v141 offset:1024
	ds_read_b128 v[186:189], v141 offset:2048
	ds_read_b128 v[190:193], v141 offset:3072
	ds_read_b128 v[194:197], v141 offset:4096
	ds_read_b128 v[198:201], v141 offset:5120
	ds_read_b128 v[202:205], v141 offset:6144
	ds_read_b128 v[206:209], v141 offset:7168
	global_load_lds_dwordx4 v[174:175], off
	v_lshl_add_u64 v[174:175], s[22:23], 0, v[134:135]
	s_add_i32 m0, s63, 0xe000
	s_nop 0
	global_load_lds_dwordx4 v[174:175], off
	s_waitcnt vmcnt(8)
	s_waitcnt lgkmcnt(0)
	s_barrier
	s_setprio 1
	v_mfma_f32_16x16x32_bf16 v[120:123], v[142:145], v[178:181], v[120:123]
	v_mfma_f32_16x16x32_bf16 v[124:127], v[150:153], v[178:181], v[124:127]
	v_mfma_f32_16x16x32_bf16 v[108:111], v[142:145], v[186:189], v[108:111]
	v_mfma_f32_16x16x32_bf16 v[104:107], v[150:153], v[186:189], v[104:107]
	v_mfma_f32_16x16x32_bf16 v[92:95], v[142:145], v[194:197], v[92:95]
	v_mfma_f32_16x16x32_bf16 v[88:91], v[150:153], v[194:197], v[88:91]
	v_mfma_f32_16x16x32_bf16 v[76:79], v[142:145], v[202:205], v[76:79]
	v_mfma_f32_16x16x32_bf16 v[72:75], v[150:153], v[202:205], v[72:75]
	v_mfma_f32_16x16x32_bf16 v[120:123], v[146:149], v[182:185], v[120:123]
	v_mfma_f32_16x16x32_bf16 v[124:127], v[154:157], v[182:185], v[124:127]
	v_mfma_f32_16x16x32_bf16 v[108:111], v[146:149], v[190:193], v[108:111]
	v_mfma_f32_16x16x32_bf16 v[104:107], v[154:157], v[190:193], v[104:107]
	v_mfma_f32_16x16x32_bf16 v[92:95], v[146:149], v[198:201], v[92:95]
	v_mfma_f32_16x16x32_bf16 v[88:91], v[154:157], v[198:201], v[88:91]
	v_mfma_f32_16x16x32_bf16 v[76:79], v[146:149], v[206:209], v[76:79]
	v_mfma_f32_16x16x32_bf16 v[72:75], v[154:157], v[206:209], v[72:75]
	s_setprio 0
	s_setprio 1
	v_mfma_f32_16x16x32_bf16 v[116:119], v[158:161], v[178:181], v[116:119]
	v_mfma_f32_16x16x32_bf16 v[112:115], v[166:169], v[178:181], v[112:115]
	v_mfma_f32_16x16x32_bf16 v[100:103], v[158:161], v[186:189], v[100:103]
	v_mfma_f32_16x16x32_bf16 v[96:99], v[166:169], v[186:189], v[96:99]
	v_mfma_f32_16x16x32_bf16 v[84:87], v[158:161], v[194:197], v[84:87]
	v_mfma_f32_16x16x32_bf16 v[80:83], v[166:169], v[194:197], v[80:83]
	v_mfma_f32_16x16x32_bf16 v[68:71], v[158:161], v[202:205], v[68:71]
	v_mfma_f32_16x16x32_bf16 v[64:67], v[166:169], v[202:205], v[64:67]
	v_mfma_f32_16x16x32_bf16 v[116:119], v[162:165], v[182:185], v[116:119]
	v_mfma_f32_16x16x32_bf16 v[112:115], v[170:173], v[182:185], v[112:115]
	v_mfma_f32_16x16x32_bf16 v[100:103], v[162:165], v[190:193], v[100:103]
	v_mfma_f32_16x16x32_bf16 v[96:99], v[170:173], v[190:193], v[96:99]
	v_mfma_f32_16x16x32_bf16 v[84:87], v[162:165], v[198:201], v[84:87]
	v_mfma_f32_16x16x32_bf16 v[80:83], v[170:173], v[198:201], v[80:83]
	v_mfma_f32_16x16x32_bf16 v[68:71], v[162:165], v[206:209], v[68:71]
	v_mfma_f32_16x16x32_bf16 v[64:67], v[170:173], v[206:209], v[64:67]
	s_setprio 0
	s_barrier
	s_add_i32 s83, s83, s37
	v_lshl_add_u64 v[174:175], s[24:25], 0, v[176:177]
	s_mov_b32 m0, s83
	ds_read_b128 v[178:181], v141 offset:16384
	ds_read_b128 v[182:185], v141 offset:17408
	ds_read_b128 v[186:189], v141 offset:18432
	ds_read_b128 v[190:193], v141 offset:19456
	ds_read_b128 v[194:197], v141 offset:20480
	ds_read_b128 v[198:201], v141 offset:21504
	ds_read_b128 v[202:205], v141 offset:22528
	ds_read_b128 v[206:209], v141 offset:23552
	global_load_lds_dwordx4 v[174:175], off
	s_add_i32 m0, s83, 0x2000
	s_add_u32 s84, s24, 0x80000
	v_lshl_add_u64 v[210:211], s[24:25], 0, v[132:133]
	s_addc_u32 s85, s25, 0
	s_add_i32 s83, s86, s37
	global_load_lds_dwordx4 v[210:211], off
	v_lshl_add_u64 v[212:213], s[84:85], 0, v[176:177]
	s_mov_b32 m0, s83
	v_lshl_add_u64 v[214:215], s[26:27], 0, v[130:131]
	global_load_lds_dwordx4 v[212:213], off
	v_lshl_add_u64 v[212:213], s[84:85], 0, v[132:133]
	s_add_i32 m0, s83, 0x2000
	s_nop 0
	global_load_lds_dwordx4 v[212:213], off
	v_lshl_add_u64 v[212:213], s[26:27], 0, v[128:129]
	s_mov_b32 m0, s63
	s_nop 0
	global_load_lds_dwordx4 v[212:213], off
	s_mov_b32 m0, s65
	s_nop 0
	global_load_lds_dwordx4 v[214:215], off
	s_waitcnt vmcnt(8)
	s_waitcnt lgkmcnt(0)
	s_barrier
; #define PG8_STAGE(bufoff, gbase, voff) do { _Pragma("unroll") for (int _i = 0; _i < 2; ++_i) \
;         __builtin_amdgcn_global_load_lds((const unsigned*)((const char*)(gbase) + (voff)[_i]), (LAS unsigned*)(lds + (bufoff) + ldsw + _i * 8192), 16, 0, 0); } while (0)
; #define PG8_LDA(dst, b, h) do { _Pragma("unroll") for (int m = 0; m < 4; ++m) _Pragma("unroll") for (int k = 0; k < 2; ++k) dst[m][k] = *(const LAS bf16x8*)(lds + PG8_SA(b, h) + aoff + m * 2048 + k * 1024); } while (0)
; #define PG8_LDB(dst, b, h) do { _Pragma("unroll") for (int n = 0; n < 2; ++n) _Pragma("unroll") for (int k = 0; k < 2; ++k) dst[n][k] = *(const LAS bf16x8*)(lds + PG8_SB(b, h) + boff + n * 2048 + k * 1024); } while (0)
; #define PG8_MMA(ai, bj, At, Bt) do { __builtin_amdgcn_s_setprio(1); _Pragma("unroll") for (int m = 0; m < 4; ++m) _Pragma("unroll") for (int n = 0; n < 2; ++n) _Pragma("unroll") for (int k = 0; k < 2; ++k) \
;         acc[ai][bj][m][n] = __builtin_amdgcn_mfma_f32_16x16x32_bf16(Bt[n][k], At[m][k], acc[ai][bj][m][n], 0, 0, 0); __builtin_amdgcn_s_setprio(0); } while (0)
; #define PG8_WAIT_V(n) asm volatile("s_waitcnt vmcnt(" #n ")" ::: "memory")
; #define PG8_WAIT_L(n) asm volatile("s_waitcnt lgkmcnt(" #n ")" ::: "memory")
; #define PG8_BAR __builtin_amdgcn_s_barrier()
; #define PG8_SCHED __builtin_amdgcn_sched_barrier(0)
; template <class Epi>
; DI void gemm_phase(LAS unsigned char* lds, const Gemm g, const Order& S, const Epi& E) {
;     ...
;             PG8_WAIT_V(8); PG8_WAIT_L(0); PG8_BAR; PG8_MMA(0, 0, At, B0); PG8_MMA(0, 1, At, B1); PG8_BAR; PG8_SCHED;
;             PG8_LDA(At, 0, 1); PG8_STAGE(PG8_SB(0, 0), b2, voffB); PG8_STAGE(PG8_SB(0, 1), b2 + hstepB, voffB); PG8_STAGE(PG8_SA(0, 0), a2, voffA);
;             PG8_WAIT_V(8); PG8_WAIT_L(0); PG8_BAR; PG8_MMA(1, 0, At, B0); PG8_MMA(1, 1, At, B1); PG8_BAR; PG8_SCHED;
;             PG8_LDB(B0, 1, 0); PG8_LDB(B1, 1, 1); PG8_SCHED; PG8_LDA(At, 1, 0); PG8_STAGE(PG8_SA(0, 1), a2 + hstepA, voffA);
;             PG8_WAIT_V(8); PG8_WAIT_L(0); PG8_BAR; PG8_MMA(0, 0, At, B0); PG8_MMA(0, 1, At, B1); PG8_BAR; PG8_SCHED;
;             PG8_LDA(At, 1, 1); PG8_STAGE(PG8_SB(1, 0), b3, voffB); PG8_STAGE(PG8_SB(1, 1), b3 + hstepB, voffB); PG8_STAGE(PG8_SA(1, 0), a3, voffA);
	s_setprio 1
	v_mfma_f32_16x16x32_bf16 v[60:63], v[142:145], v[178:181], v[60:63]
	v_mfma_f32_16x16x32_bf16 v[56:59], v[150:153], v[178:181], v[56:59]
	v_mfma_f32_16x16x32_bf16 v[44:47], v[142:145], v[186:189], v[44:47]
	v_mfma_f32_16x16x32_bf16 v[40:43], v[150:153], v[186:189], v[40:43]
	v_mfma_f32_16x16x32_bf16 v[28:31], v[142:145], v[194:197], v[28:31]
	v_mfma_f32_16x16x32_bf16 v[24:27], v[150:153], v[194:197], v[24:27]
	v_mfma_f32_16x16x32_bf16 v[12:15], v[142:145], v[202:205], v[12:15]
	v_mfma_f32_16x16x32_bf16 v[8:11], v[150:153], v[202:205], v[8:11]
	v_mfma_f32_16x16x32_bf16 v[60:63], v[146:149], v[182:185], v[60:63]
	v_mfma_f32_16x16x32_bf16 v[56:59], v[154:157], v[182:185], v[56:59]
	v_mfma_f32_16x16x32_bf16 v[44:47], v[146:149], v[190:193], v[44:47]
	v_mfma_f32_16x16x32_bf16 v[40:43], v[154:157], v[190:193], v[40:43]
	v_mfma_f32_16x16x32_bf16 v[28:31], v[146:149], v[198:201], v[28:31]
	v_mfma_f32_16x16x32_bf16 v[24:27], v[154:157], v[198:201], v[24:27]
	v_mfma_f32_16x16x32_bf16 v[12:15], v[146:149], v[206:209], v[12:15]
	v_mfma_f32_16x16x32_bf16 v[8:11], v[154:157], v[206:209], v[8:11]
	s_setprio 0
	s_setprio 1
	v_mfma_f32_16x16x32_bf16 v[52:55], v[158:161], v[178:181], v[52:55]
	v_mfma_f32_16x16x32_bf16 v[48:51], v[166:169], v[178:181], v[48:51]
	v_mfma_f32_16x16x32_bf16 v[36:39], v[158:161], v[186:189], v[36:39]
	v_mfma_f32_16x16x32_bf16 v[32:35], v[166:169], v[186:189], v[32:35]
	v_mfma_f32_16x16x32_bf16 v[20:23], v[158:161], v[194:197], v[20:23]
	v_mfma_f32_16x16x32_bf16 v[16:19], v[166:169], v[194:197], v[16:19]
	v_mfma_f32_16x16x32_bf16 v[4:7], v[158:161], v[202:205], v[4:7]
	v_mfma_f32_16x16x32_bf16 v[0:3], v[166:169], v[202:205], v[0:3]
	v_mfma_f32_16x16x32_bf16 v[52:55], v[162:165], v[182:185], v[52:55]
	v_mfma_f32_16x16x32_bf16 v[48:51], v[170:173], v[182:185], v[48:51]
	v_mfma_f32_16x16x32_bf16 v[36:39], v[162:165], v[190:193], v[36:39]
	v_mfma_f32_16x16x32_bf16 v[32:35], v[170:173], v[190:193], v[32:35]
	v_mfma_f32_16x16x32_bf16 v[20:23], v[162:165], v[198:201], v[20:23]
	v_mfma_f32_16x16x32_bf16 v[16:19], v[170:173], v[198:201], v[16:19]
	v_mfma_f32_16x16x32_bf16 v[4:7], v[162:165], v[206:209], v[4:7]
	v_mfma_f32_16x16x32_bf16 v[0:3], v[170:173], v[206:209], v[0:3]
	s_setprio 0
	s_barrier
	s_add_i32 s83, 0, 0x18000
	s_add_i32 s84, 0, 0x1c000
	v_add_u32_e32 v154, s83, v140
	v_add_u32_e32 v170, s84, v140
	ds_read_b128 v[142:145], v154
	ds_read_b128 v[146:149], v154 offset:1024
	ds_read_b128 v[150:153], v154 offset:2048
	ds_read_b128 v[154:157], v154 offset:3072
	ds_read_b128 v[158:161], v170
	ds_read_b128 v[162:165], v170 offset:1024
	ds_read_b128 v[166:169], v170 offset:2048
	ds_read_b128 v[170:173], v170 offset:3072
	s_add_u32 s26, s26, 0x80000
	s_addc_u32 s27, s27, 0
	s_mov_b32 m0, s70
	v_lshl_add_u64 v[216:217], s[26:27], 0, v[128:129]
	ds_read_b128 v[178:181], v141 offset:32768
	ds_read_b128 v[182:185], v141 offset:33792
	ds_read_b128 v[186:189], v141 offset:34816
	ds_read_b128 v[190:193], v141 offset:35840
	ds_read_b128 v[194:197], v141 offset:36864
	ds_read_b128 v[198:201], v141 offset:37888
	ds_read_b128 v[202:205], v141 offset:38912
	ds_read_b128 v[206:209], v141 offset:39936
	global_load_lds_dwordx4 v[216:217], off
	v_lshl_add_u64 v[216:217], s[26:27], 0, v[130:131]
	s_mov_b32 m0, s71
	s_nop 0
	global_load_lds_dwordx4 v[216:217], off
	s_waitcnt vmcnt(8)
	s_waitcnt lgkmcnt(0)
	s_barrier
	s_setprio 1
	v_mfma_f32_16x16x32_bf16 v[120:123], v[142:145], v[178:181], v[120:123]
	v_mfma_f32_16x16x32_bf16 v[124:127], v[150:153], v[178:181], v[124:127]
	v_mfma_f32_16x16x32_bf16 v[108:111], v[142:145], v[186:189], v[108:111]
	v_mfma_f32_16x16x32_bf16 v[104:107], v[150:153], v[186:189], v[104:107]
	v_mfma_f32_16x16x32_bf16 v[92:95], v[142:145], v[194:197], v[92:95]
	v_mfma_f32_16x16x32_bf16 v[88:91], v[150:153], v[194:197], v[88:91]
	v_mfma_f32_16x16x32_bf16 v[76:79], v[142:145], v[202:205], v[76:79]
	v_mfma_f32_16x16x32_bf16 v[72:75], v[150:153], v[202:205], v[72:75]
	v_mfma_f32_16x16x32_bf16 v[120:123], v[146:149], v[182:185], v[120:123]
	v_mfma_f32_16x16x32_bf16 v[124:127], v[154:157], v[182:185], v[124:127]
	v_mfma_f32_16x16x32_bf16 v[108:111], v[146:149], v[190:193], v[108:111]
	v_mfma_f32_16x16x32_bf16 v[104:107], v[154:157], v[190:193], v[104:107]
	v_mfma_f32_16x16x32_bf16 v[92:95], v[146:149], v[198:201], v[92:95]
	v_mfma_f32_16x16x32_bf16 v[88:91], v[154:157], v[198:201], v[88:91]
	v_mfma_f32_16x16x32_bf16 v[76:79], v[146:149], v[206:209], v[76:79]
	v_mfma_f32_16x16x32_bf16 v[72:75], v[154:157], v[206:209], v[72:75]
	s_setprio 0
	s_setprio 1
	v_mfma_f32_16x16x32_bf16 v[116:119], v[158:161], v[178:181], v[116:119]
	v_mfma_f32_16x16x32_bf16 v[112:115], v[166:169], v[178:181], v[112:115]
	v_mfma_f32_16x16x32_bf16 v[100:103], v[158:161], v[186:189], v[100:103]
	v_mfma_f32_16x16x32_bf16 v[96:99], v[166:169], v[186:189], v[96:99]
	v_mfma_f32_16x16x32_bf16 v[84:87], v[158:161], v[194:197], v[84:87]
	v_mfma_f32_16x16x32_bf16 v[80:83], v[166:169], v[194:197], v[80:83]
	v_mfma_f32_16x16x32_bf16 v[68:71], v[158:161], v[202:205], v[68:71]
	v_mfma_f32_16x16x32_bf16 v[64:67], v[166:169], v[202:205], v[64:67]
	v_mfma_f32_16x16x32_bf16 v[116:119], v[162:165], v[182:185], v[116:119]
	v_mfma_f32_16x16x32_bf16 v[112:115], v[170:173], v[182:185], v[112:115]
	v_mfma_f32_16x16x32_bf16 v[100:103], v[162:165], v[190:193], v[100:103]
	v_mfma_f32_16x16x32_bf16 v[96:99], v[170:173], v[190:193], v[96:99]
	v_mfma_f32_16x16x32_bf16 v[84:87], v[162:165], v[198:201], v[84:87]
	v_mfma_f32_16x16x32_bf16 v[80:83], v[170:173], v[198:201], v[80:83]
	v_mfma_f32_16x16x32_bf16 v[68:71], v[162:165], v[206:209], v[68:71]
	v_mfma_f32_16x16x32_bf16 v[64:67], v[170:173], v[206:209], v[64:67]
	s_setprio 0
	s_barrier
; #define PG8_STAGE(bufoff, gbase, voff) do { _Pragma("unroll") for (int _i = 0; _i < 2; ++_i) \
;         __builtin_amdgcn_global_load_lds((const unsigned*)((const char*)(gbase) + (voff)[_i]), (LAS unsigned*)(lds + (bufoff) + ldsw + _i * 8192), 16, 0, 0); } while (0)
; #define PG8_LDA(dst, b, h) do { _Pragma("unroll") for (int m = 0; m < 4; ++m) _Pragma("unroll") for (int k = 0; k < 2; ++k) dst[m][k] = *(const LAS bf16x8*)(lds + PG8_SA(b, h) + aoff + m * 2048 + k * 1024); } while (0)
; #define PG8_LDB(dst, b, h) do { _Pragma("unroll") for (int n = 0; n < 2; ++n) _Pragma("unroll") for (int k = 0; k < 2; ++k) dst[n][k] = *(const LAS bf16x8*)(lds + PG8_SB(b, h) + boff + n * 2048 + k * 1024); } while (0)
; #define PG8_MMA(ai, bj, At, Bt) do { __builtin_amdgcn_s_setprio(1); _Pragma("unroll") for (int m = 0; m < 4; ++m) _Pragma("unroll") for (int n = 0; n < 2; ++n) _Pragma("unroll") for (int k = 0; k < 2; ++k) \
;         acc[ai][bj][m][n] = __builtin_amdgcn_mfma_f32_16x16x32_bf16(Bt[n][k], At[m][k], acc[ai][bj][m][n], 0, 0, 0); __builtin_amdgcn_s_setprio(0); } while (0)
; #define PG8_WAIT_V(n) asm volatile("s_waitcnt vmcnt(" #n ")" ::: "memory")
; #define PG8_WAIT_L(n) asm volatile("s_waitcnt lgkmcnt(" #n ")" ::: "memory")
; #define PG8_BAR __builtin_amdgcn_s_barrier()
; #define PG8_SCHED __builtin_amdgcn_sched_barrier(0)
; template <class Epi>
; DI void gemm_phase(LAS unsigned char* lds, const Gemm g, const Order& S, const Epi& E) {
;     ...
;             PG8_LDB(B0, 1, 0); PG8_LDB(B1, 1, 1); PG8_SCHED; PG8_LDA(At, 1, 0); PG8_STAGE(PG8_SA(0, 1), a2 + hstepA, voffA);
;             PG8_WAIT_V(8); PG8_WAIT_L(0); PG8_BAR; PG8_MMA(0, 0, At, B0); PG8_MMA(0, 1, At, B1); PG8_BAR; PG8_SCHED;
;             PG8_LDA(At, 1, 1); PG8_STAGE(PG8_SB(1, 0), b3, voffB); PG8_STAGE(PG8_SB(1, 1), b3 + hstepB, voffB); PG8_STAGE(PG8_SA(1, 0), a3, voffA);
;             PG8_WAIT_V(8); PG8_WAIT_L(0); PG8_BAR; PG8_MMA(1, 0, At, B0); PG8_MMA(1, 1, At, B1); PG8_BAR; PG8_SCHED;
;         }
	s_add_i32 s26, s83, s37
	v_lshl_add_u64 v[174:175], v[174:175], 0, s[56:57]
	s_mov_b32 m0, s26
	ds_read_b128 v[178:181], v141 offset:49152
	ds_read_b128 v[182:185], v141 offset:50176
	ds_read_b128 v[186:189], v141 offset:51200
	ds_read_b128 v[190:193], v141 offset:52224
	ds_read_b128 v[194:197], v141 offset:53248
	ds_read_b128 v[198:201], v141 offset:54272
	ds_read_b128 v[202:205], v141 offset:55296
	ds_read_b128 v[206:209], v141 offset:56320
	global_load_lds_dwordx4 v[174:175], off
	s_add_i32 m0, s26, 0x2000
	s_add_u32 s24, s24, 0x80080
	v_lshl_add_u64 v[174:175], v[210:211], 0, s[56:57]
	s_addc_u32 s25, s25, 0
	s_add_i32 s26, s84, s37
	global_load_lds_dwordx4 v[174:175], off
	v_lshl_add_u64 v[174:175], s[24:25], 0, v[176:177]
	s_mov_b32 m0, s26
	s_nop 0
	global_load_lds_dwordx4 v[174:175], off
	v_lshl_add_u64 v[174:175], s[24:25], 0, v[132:133]
	s_add_i32 m0, s26, 0x2000
	s_nop 0
	global_load_lds_dwordx4 v[174:175], off
	v_lshl_add_u64 v[174:175], v[212:213], 0, s[56:57]
	s_mov_b32 m0, s77
	s_nop 0
	global_load_lds_dwordx4 v[174:175], off
	v_lshl_add_u64 v[174:175], v[214:215], 0, s[56:57]
	s_mov_b32 m0, s78
	s_nop 0
	global_load_lds_dwordx4 v[174:175], off
	s_waitcnt vmcnt(8)
	s_waitcnt lgkmcnt(0)
	s_barrier
	s_setprio 1
	v_mfma_f32_16x16x32_bf16 v[60:63], v[142:145], v[178:181], v[60:63]
	v_mfma_f32_16x16x32_bf16 v[56:59], v[150:153], v[178:181], v[56:59]
	v_mfma_f32_16x16x32_bf16 v[44:47], v[142:145], v[186:189], v[44:47]
	v_mfma_f32_16x16x32_bf16 v[40:43], v[150:153], v[186:189], v[40:43]
	v_mfma_f32_16x16x32_bf16 v[28:31], v[142:145], v[194:197], v[28:31]
	v_mfma_f32_16x16x32_bf16 v[24:27], v[150:153], v[194:197], v[24:27]
	v_mfma_f32_16x16x32_bf16 v[12:15], v[142:145], v[202:205], v[12:15]
	v_mfma_f32_16x16x32_bf16 v[8:11], v[150:153], v[202:205], v[8:11]
	v_mfma_f32_16x16x32_bf16 v[60:63], v[146:149], v[182:185], v[60:63]
	v_mfma_f32_16x16x32_bf16 v[56:59], v[154:157], v[182:185], v[56:59]
	v_mfma_f32_16x16x32_bf16 v[44:47], v[146:149], v[190:193], v[44:47]
	v_mfma_f32_16x16x32_bf16 v[40:43], v[154:157], v[190:193], v[40:43]
	v_mfma_f32_16x16x32_bf16 v[28:31], v[146:149], v[198:201], v[28:31]
	v_mfma_f32_16x16x32_bf16 v[24:27], v[154:157], v[198:201], v[24:27]
	v_mfma_f32_16x16x32_bf16 v[12:15], v[146:149], v[206:209], v[12:15]
	v_mfma_f32_16x16x32_bf16 v[8:11], v[154:157], v[206:209], v[8:11]
	s_setprio 0
	s_setprio 1
	v_mfma_f32_16x16x32_bf16 v[52:55], v[158:161], v[178:181], v[52:55]
	v_mfma_f32_16x16x32_bf16 v[48:51], v[166:169], v[178:181], v[48:51]
	v_mfma_f32_16x16x32_bf16 v[36:39], v[158:161], v[186:189], v[36:39]
	v_mfma_f32_16x16x32_bf16 v[32:35], v[166:169], v[186:189], v[32:35]
	v_mfma_f32_16x16x32_bf16 v[20:23], v[158:161], v[194:197], v[20:23]
	v_mfma_f32_16x16x32_bf16 v[16:19], v[166:169], v[194:197], v[16:19]
	v_mfma_f32_16x16x32_bf16 v[4:7], v[158:161], v[202:205], v[4:7]
	v_mfma_f32_16x16x32_bf16 v[0:3], v[166:169], v[202:205], v[0:3]
	v_mfma_f32_16x16x32_bf16 v[52:55], v[162:165], v[182:185], v[52:55]
	v_mfma_f32_16x16x32_bf16 v[48:51], v[170:173], v[182:185], v[48:51]
	v_mfma_f32_16x16x32_bf16 v[36:39], v[162:165], v[190:193], v[36:39]
	v_mfma_f32_16x16x32_bf16 v[32:35], v[170:173], v[190:193], v[32:35]
	v_mfma_f32_16x16x32_bf16 v[20:23], v[162:165], v[198:201], v[20:23]
	v_mfma_f32_16x16x32_bf16 v[16:19], v[170:173], v[198:201], v[16:19]
	v_mfma_f32_16x16x32_bf16 v[4:7], v[162:165], v[206:209], v[4:7]
	v_mfma_f32_16x16x32_bf16 v[0:3], v[170:173], v[206:209], v[0:3]
	s_setprio 0
	s_barrier
	s_add_u32 s15, s15, 0x100
	s_addc_u32 s17, s17, 0
	s_add_u32 s22, s22, 0x100
	s_addc_u32 s23, s23, 0
	s_cmp_ge_i32 s82, s74
	s_mov_b32 s24, s82
	s_cbranch_scc0 .LBB0_261
	s_mov_b32 s82, 0x3a490fdb
	s_mov_b32 s84, 0x3bb504f3

; #define PG8_STAGE(bufoff, gbase, voff) do { _Pragma("unroll") for (int _i = 0; _i < 2; ++_i) \
;         __builtin_amdgcn_global_load_lds((const unsigned*)((const char*)(gbase) + (voff)[_i]), (LAS unsigned*)(lds + (bufoff) + ldsw + _i * 8192), 16, 0, 0); } while (0)
; #define PG8_LDA(dst, b, h) do { _Pragma("unroll") for (int m = 0; m < 4; ++m) _Pragma("unroll") for (int k = 0; k < 2; ++k) dst[m][k] = *(const LAS bf16x8*)(lds + PG8_SA(b, h) + aoff + m * 2048 + k * 1024); } while (0)
; #define PG8_LDB(dst, b, h) do { _Pragma("unroll") for (int n = 0; n < 2; ++n) _Pragma("unroll") for (int k = 0; k < 2; ++k) dst[n][k] = *(const LAS bf16x8*)(lds + PG8_SB(b, h) + boff + n * 2048 + k * 1024); } while (0)
; #define PG8_MMA(ai, bj, At, Bt) do { __builtin_amdgcn_s_setprio(1); _Pragma("unroll") for (int m = 0; m < 4; ++m) _Pragma("unroll") for (int n = 0; n < 2; ++n) _Pragma("unroll") for (int k = 0; k < 2; ++k) \
;         acc[ai][bj][m][n] = __builtin_amdgcn_mfma_f32_16x16x32_bf16(Bt[n][k], At[m][k], acc[ai][bj][m][n], 0, 0, 0); __builtin_amdgcn_s_setprio(0); } while (0)
; #define PG8_WAIT_V(n) asm volatile("s_waitcnt vmcnt(" #n ")" ::: "memory")
; #define PG8_WAIT_L(n) asm volatile("s_waitcnt lgkmcnt(" #n ")" ::: "memory")
; #define PG8_BAR __builtin_amdgcn_s_barrier()
; #define PG8_SCHED __builtin_amdgcn_sched_barrier(0)
; template <class Epi>
; DI void gemm_phase(LAS unsigned char* lds, const Gemm g, const Order& S, const Epi& E) {
;     ...
;         for (int t = 0; t < nt; t += 2) {
;             const bool last = (t == nt - 2);
;             const char* a1 = cA + (size_t)(t + 1) * kstep;
;             const char* a2 = last ? nA : cA + (size_t)(t + 2) * kstep; const char* b2 = last ? nB : cB + (size_t)(t + 2) * kstep;
;             const char* a3 = a2 + kstep; const char* b3 = b2 + kstep;
;             PG8_LDB(B0, 0, 0); PG8_LDB(B1, 0, 1); PG8_SCHED; PG8_LDA(At, 0, 0); PG8_STAGE(PG8_SA(1, 1), a1 + hstepA, voffA);
;             PG8_WAIT_V(8); PG8_WAIT_L(0); PG8_BAR; PG8_MMA(0, 0, At, B0); PG8_MMA(0, 1, At, B1); PG8_BAR; PG8_SCHED;
;             PG8_LDA(At, 0, 1); PG8_STAGE(PG8_SB(0, 0), b2, voffB); PG8_STAGE(PG8_SB(0, 1), b2 + hstepB, voffB); PG8_STAGE(PG8_SA(0, 0), a2, voffA);
;             PG8_WAIT_V(8); PG8_WAIT_L(0); PG8_BAR; PG8_MMA(1, 0, At, B0); PG8_MMA(1, 1, At, B1); PG8_BAR; PG8_SCHED;
.LBB0_435:
	s_add_i32 s84, s26, 2
	s_add_u32 s24, s22, 0x100
	s_addc_u32 s25, s23, 0
	s_add_u32 s27, s82, s22
	s_addc_u32 s28, s83, s23
	s_cmp_eq_u32 s78, s26
	s_cselect_b32 s85, 0, s24
	s_cselect_b32 s29, 0, s25
	s_cselect_b32 s26, s81, s27
	s_cselect_b32 s27, s19, s28
	s_add_u32 s28, s4, s85
	s_addc_u32 s29, s5, s29
	s_add_i32 s85, 0, 0x10000
	s_add_i32 s86, 0, 0x14000
	v_add_u32_e32 v152, s85, v146
	v_add_u32_e32 v168, s86, v146
	ds_read_b128 v[136:139], v152
	ds_read_b128 v[140:143], v152 offset:1024
	ds_read_b128 v[148:151], v152 offset:2048
	ds_read_b128 v[152:155], v152 offset:3072
	ds_read_b128 v[156:159], v168
	ds_read_b128 v[160:163], v168 offset:1024
	ds_read_b128 v[164:167], v168 offset:2048
	ds_read_b128 v[168:171], v168 offset:3072
	v_lshl_add_u64 v[206:207], v[134:135], 0, s[22:23]
	s_add_i32 m0, s37, 0xc000
	ds_read_b128 v[172:175], v147
	ds_read_b128 v[178:181], v147 offset:1024
	ds_read_b128 v[182:185], v147 offset:2048
	ds_read_b128 v[186:189], v147 offset:3072
	ds_read_b128 v[190:193], v147 offset:4096
	ds_read_b128 v[194:197], v147 offset:5120
	ds_read_b128 v[198:201], v147 offset:6144
	ds_read_b128 v[202:205], v147 offset:7168
	global_load_lds_dwordx4 v[206:207], off
	v_lshl_add_u64 v[206:207], v[132:133], 0, s[22:23]
	s_add_i32 m0, s37, 0xe000
	s_nop 0
	global_load_lds_dwordx4 v[206:207], off
	s_waitcnt vmcnt(8)
	s_waitcnt lgkmcnt(0)
	s_barrier
	s_setprio 1
	v_mfma_f32_16x16x32_bf16 v[120:123], v[136:139], v[172:175], v[120:123]
	v_mfma_f32_16x16x32_bf16 v[112:115], v[148:151], v[172:175], v[112:115]
	v_mfma_f32_16x16x32_bf16 v[88:91], v[136:139], v[182:185], v[88:91]
	v_mfma_f32_16x16x32_bf16 v[80:83], v[148:151], v[182:185], v[80:83]
	v_mfma_f32_16x16x32_bf16 v[56:59], v[136:139], v[190:193], v[56:59]
	v_mfma_f32_16x16x32_bf16 v[48:51], v[148:151], v[190:193], v[48:51]
	v_mfma_f32_16x16x32_bf16 v[24:27], v[136:139], v[198:201], v[24:27]
	v_mfma_f32_16x16x32_bf16 v[16:19], v[148:151], v[198:201], v[16:19]
	v_mfma_f32_16x16x32_bf16 v[120:123], v[140:143], v[178:181], v[120:123]
	v_mfma_f32_16x16x32_bf16 v[112:115], v[152:155], v[178:181], v[112:115]
	v_mfma_f32_16x16x32_bf16 v[88:91], v[140:143], v[186:189], v[88:91]
	v_mfma_f32_16x16x32_bf16 v[80:83], v[152:155], v[186:189], v[80:83]
	v_mfma_f32_16x16x32_bf16 v[56:59], v[140:143], v[194:197], v[56:59]
	v_mfma_f32_16x16x32_bf16 v[48:51], v[152:155], v[194:197], v[48:51]
	v_mfma_f32_16x16x32_bf16 v[24:27], v[140:143], v[202:205], v[24:27]
	v_mfma_f32_16x16x32_bf16 v[16:19], v[152:155], v[202:205], v[16:19]
	s_setprio 0
	s_setprio 1
	v_mfma_f32_16x16x32_bf16 v[104:107], v[156:159], v[172:175], v[104:107]
	v_mfma_f32_16x16x32_bf16 v[96:99], v[164:167], v[172:175], v[96:99]
	v_mfma_f32_16x16x32_bf16 v[72:75], v[156:159], v[182:185], v[72:75]
	v_mfma_f32_16x16x32_bf16 v[64:67], v[164:167], v[182:185], v[64:67]
	v_mfma_f32_16x16x32_bf16 v[40:43], v[156:159], v[190:193], v[40:43]
	v_mfma_f32_16x16x32_bf16 v[32:35], v[164:167], v[190:193], v[32:35]
	v_mfma_f32_16x16x32_bf16 v[8:11], v[156:159], v[198:201], v[8:11]
	v_mfma_f32_16x16x32_bf16 v[4:7], v[164:167], v[198:201], v[4:7]
	v_mfma_f32_16x16x32_bf16 v[104:107], v[160:163], v[178:181], v[104:107]
	v_mfma_f32_16x16x32_bf16 v[96:99], v[168:171], v[178:181], v[96:99]
	v_mfma_f32_16x16x32_bf16 v[72:75], v[160:163], v[186:189], v[72:75]
	v_mfma_f32_16x16x32_bf16 v[64:67], v[168:171], v[186:189], v[64:67]
	v_mfma_f32_16x16x32_bf16 v[40:43], v[160:163], v[194:197], v[40:43]
	v_mfma_f32_16x16x32_bf16 v[32:35], v[168:171], v[194:197], v[32:35]
	v_mfma_f32_16x16x32_bf16 v[8:11], v[160:163], v[202:205], v[8:11]
	v_mfma_f32_16x16x32_bf16 v[4:7], v[168:171], v[202:205], v[4:7]
	s_setprio 0
	s_barrier
	s_add_i32 s22, s85, s36
	v_lshl_add_u64 v[206:207], s[26:27], 0, v[130:131]
	s_mov_b32 m0, s22
	ds_read_b128 v[172:175], v147 offset:16384
	ds_read_b128 v[178:181], v147 offset:17408
	ds_read_b128 v[182:185], v147 offset:18432
	ds_read_b128 v[186:189], v147 offset:19456
	ds_read_b128 v[190:193], v147 offset:20480
	ds_read_b128 v[194:197], v147 offset:21504
	ds_read_b128 v[198:201], v147 offset:22528
	ds_read_b128 v[202:205], v147 offset:23552
	global_load_lds_dwordx4 v[206:207], off
	s_add_i32 m0, s22, 0x2000
	s_add_u32 s22, s26, 0x8000
	v_lshl_add_u64 v[208:209], s[26:27], 0, v[128:129]
	s_addc_u32 s23, s27, 0
	s_add_i32 s85, s86, s36
	global_load_lds_dwordx4 v[208:209], off
	v_lshl_add_u64 v[210:211], s[22:23], 0, v[130:131]
	s_mov_b32 m0, s85
	v_lshl_add_u64 v[212:213], s[28:29], 0, v[128:129]
	global_load_lds_dwordx4 v[210:211], off
	v_lshl_add_u64 v[210:211], s[22:23], 0, v[128:129]
	s_add_i32 m0, s85, 0x2000
	s_nop 0
	global_load_lds_dwordx4 v[210:211], off
	v_lshl_add_u64 v[210:211], s[28:29], 0, v[130:131]
	s_mov_b32 m0, s37
	s_nop 0
	global_load_lds_dwordx4 v[210:211], off
	s_mov_b32 m0, s40
	s_nop 0
	global_load_lds_dwordx4 v[212:213], off
	s_waitcnt vmcnt(8)
	s_waitcnt lgkmcnt(0)
	s_barrier
; #define PG8_STAGE(bufoff, gbase, voff) do { _Pragma("unroll") for (int _i = 0; _i < 2; ++_i) \
;         __builtin_amdgcn_global_load_lds((const unsigned*)((const char*)(gbase) + (voff)[_i]), (LAS unsigned*)(lds + (bufoff) + ldsw + _i * 8192), 16, 0, 0); } while (0)
; #define PG8_LDA(dst, b, h) do { _Pragma("unroll") for (int m = 0; m < 4; ++m) _Pragma("unroll") for (int k = 0; k < 2; ++k) dst[m][k] = *(const LAS bf16x8*)(lds + PG8_SA(b, h) + aoff + m * 2048 + k * 1024); } while (0)
; #define PG8_LDB(dst, b, h) do { _Pragma("unroll") for (int n = 0; n < 2; ++n) _Pragma("unroll") for (int k = 0; k < 2; ++k) dst[n][k] = *(const LAS bf16x8*)(lds + PG8_SB(b, h) + boff + n * 2048 + k * 1024); } while (0)
; #define PG8_MMA(ai, bj, At, Bt) do { __builtin_amdgcn_s_setprio(1); _Pragma("unroll") for (int m = 0; m < 4; ++m) _Pragma("unroll") for (int n = 0; n < 2; ++n) _Pragma("unroll") for (int k = 0; k < 2; ++k) \
;         acc[ai][bj][m][n] = __builtin_amdgcn_mfma_f32_16x16x32_bf16(Bt[n][k], At[m][k], acc[ai][bj][m][n], 0, 0, 0); __builtin_amdgcn_s_setprio(0); } while (0)
; #define PG8_WAIT_V(n) asm volatile("s_waitcnt vmcnt(" #n ")" ::: "memory")
; #define PG8_WAIT_L(n) asm volatile("s_waitcnt lgkmcnt(" #n ")" ::: "memory")
; #define PG8_BAR __builtin_amdgcn_s_barrier()
; #define PG8_SCHED __builtin_amdgcn_sched_barrier(0)
; template <class Epi>
; DI void gemm_phase(LAS unsigned char* lds, const Gemm g, const Order& S, const Epi& E) {
;     ...
;             PG8_WAIT_V(8); PG8_WAIT_L(0); PG8_BAR; PG8_MMA(1, 0, At, B0); PG8_MMA(1, 1, At, B1); PG8_BAR; PG8_SCHED;
;             PG8_LDB(B0, 1, 0); PG8_LDB(B1, 1, 1); PG8_SCHED; PG8_LDA(At, 1, 0); PG8_STAGE(PG8_SA(0, 1), a2 + hstepA, voffA);
;             PG8_WAIT_V(8); PG8_WAIT_L(0); PG8_BAR; PG8_MMA(0, 0, At, B0); PG8_MMA(0, 1, At, B1); PG8_BAR; PG8_SCHED;
;             PG8_LDA(At, 1, 1); PG8_STAGE(PG8_SB(1, 0), b3, voffB); PG8_STAGE(PG8_SB(1, 1), b3 + hstepB, voffB); PG8_STAGE(PG8_SA(1, 0), a3, voffA);
;             PG8_WAIT_V(8); PG8_WAIT_L(0); PG8_BAR; PG8_MMA(1, 0, At, B0); PG8_MMA(1, 1, At, B1); PG8_BAR; PG8_SCHED;
	s_setprio 1
	v_mfma_f32_16x16x32_bf16 v[124:127], v[136:139], v[172:175], v[124:127]
	v_mfma_f32_16x16x32_bf16 v[116:119], v[148:151], v[172:175], v[116:119]
	v_mfma_f32_16x16x32_bf16 v[92:95], v[136:139], v[182:185], v[92:95]
	v_mfma_f32_16x16x32_bf16 v[84:87], v[148:151], v[182:185], v[84:87]
	v_mfma_f32_16x16x32_bf16 v[60:63], v[136:139], v[190:193], v[60:63]
	v_mfma_f32_16x16x32_bf16 v[52:55], v[148:151], v[190:193], v[52:55]
	v_mfma_f32_16x16x32_bf16 v[28:31], v[136:139], v[198:201], v[28:31]
	v_mfma_f32_16x16x32_bf16 v[20:23], v[148:151], v[198:201], v[20:23]
	v_mfma_f32_16x16x32_bf16 v[124:127], v[140:143], v[178:181], v[124:127]
	v_mfma_f32_16x16x32_bf16 v[116:119], v[152:155], v[178:181], v[116:119]
	v_mfma_f32_16x16x32_bf16 v[92:95], v[140:143], v[186:189], v[92:95]
	v_mfma_f32_16x16x32_bf16 v[84:87], v[152:155], v[186:189], v[84:87]
	v_mfma_f32_16x16x32_bf16 v[60:63], v[140:143], v[194:197], v[60:63]
	v_mfma_f32_16x16x32_bf16 v[52:55], v[152:155], v[194:197], v[52:55]
	v_mfma_f32_16x16x32_bf16 v[28:31], v[140:143], v[202:205], v[28:31]
	v_mfma_f32_16x16x32_bf16 v[20:23], v[152:155], v[202:205], v[20:23]
	s_setprio 0
	s_setprio 1
	v_mfma_f32_16x16x32_bf16 v[108:111], v[156:159], v[172:175], v[108:111]
	v_mfma_f32_16x16x32_bf16 v[100:103], v[164:167], v[172:175], v[100:103]
	v_mfma_f32_16x16x32_bf16 v[76:79], v[156:159], v[182:185], v[76:79]
	v_mfma_f32_16x16x32_bf16 v[68:71], v[164:167], v[182:185], v[68:71]
	v_mfma_f32_16x16x32_bf16 v[44:47], v[156:159], v[190:193], v[44:47]
	v_mfma_f32_16x16x32_bf16 v[36:39], v[164:167], v[190:193], v[36:39]
	v_mfma_f32_16x16x32_bf16 v[12:15], v[156:159], v[198:201], v[12:15]
	v_mfma_f32_16x16x32_bf16 v[0:3], v[164:167], v[198:201], v[0:3]
	v_mfma_f32_16x16x32_bf16 v[108:111], v[160:163], v[178:181], v[108:111]
	v_mfma_f32_16x16x32_bf16 v[100:103], v[168:171], v[178:181], v[100:103]
	v_mfma_f32_16x16x32_bf16 v[76:79], v[160:163], v[186:189], v[76:79]
	v_mfma_f32_16x16x32_bf16 v[68:71], v[168:171], v[186:189], v[68:71]
	v_mfma_f32_16x16x32_bf16 v[44:47], v[160:163], v[194:197], v[44:47]
	v_mfma_f32_16x16x32_bf16 v[36:39], v[168:171], v[194:197], v[36:39]
	v_mfma_f32_16x16x32_bf16 v[12:15], v[160:163], v[202:205], v[12:15]
	v_mfma_f32_16x16x32_bf16 v[0:3], v[168:171], v[202:205], v[0:3]
	s_setprio 0
	s_barrier
	s_add_i32 s85, 0, 0x18000
	s_add_i32 s86, 0, 0x1c000
	v_add_u32_e32 v152, s85, v146
	v_add_u32_e32 v168, s86, v146
	ds_read_b128 v[136:139], v152
	ds_read_b128 v[140:143], v152 offset:1024
	ds_read_b128 v[148:151], v152 offset:2048
	ds_read_b128 v[152:155], v152 offset:3072
	ds_read_b128 v[156:159], v168
	ds_read_b128 v[160:163], v168 offset:1024
	ds_read_b128 v[164:167], v168 offset:2048
	ds_read_b128 v[168:171], v168 offset:3072
	s_add_u32 s22, s28, 0x8000
	s_addc_u32 s23, s29, 0
	s_mov_b32 m0, s65
	v_lshl_add_u64 v[214:215], s[22:23], 0, v[130:131]
	ds_read_b128 v[172:175], v147 offset:32768
	ds_read_b128 v[178:181], v147 offset:33792
	ds_read_b128 v[182:185], v147 offset:34816
	ds_read_b128 v[186:189], v147 offset:35840
	ds_read_b128 v[190:193], v147 offset:36864
	ds_read_b128 v[194:197], v147 offset:37888
	ds_read_b128 v[198:201], v147 offset:38912
	ds_read_b128 v[202:205], v147 offset:39936
	global_load_lds_dwordx4 v[214:215], off
	v_lshl_add_u64 v[214:215], s[22:23], 0, v[128:129]
	s_mov_b32 m0, s72
	s_nop 0
	global_load_lds_dwordx4 v[214:215], off
	s_waitcnt vmcnt(8)
	s_waitcnt lgkmcnt(0)
	s_barrier
	s_setprio 1
	v_mfma_f32_16x16x32_bf16 v[120:123], v[136:139], v[172:175], v[120:123]
	v_mfma_f32_16x16x32_bf16 v[112:115], v[148:151], v[172:175], v[112:115]
	v_mfma_f32_16x16x32_bf16 v[88:91], v[136:139], v[182:185], v[88:91]
	v_mfma_f32_16x16x32_bf16 v[80:83], v[148:151], v[182:185], v[80:83]
	v_mfma_f32_16x16x32_bf16 v[56:59], v[136:139], v[190:193], v[56:59]
	v_mfma_f32_16x16x32_bf16 v[48:51], v[148:151], v[190:193], v[48:51]
	v_mfma_f32_16x16x32_bf16 v[24:27], v[136:139], v[198:201], v[24:27]
	v_mfma_f32_16x16x32_bf16 v[16:19], v[148:151], v[198:201], v[16:19]
	v_mfma_f32_16x16x32_bf16 v[120:123], v[140:143], v[178:181], v[120:123]
	v_mfma_f32_16x16x32_bf16 v[112:115], v[152:155], v[178:181], v[112:115]
	v_mfma_f32_16x16x32_bf16 v[88:91], v[140:143], v[186:189], v[88:91]
	v_mfma_f32_16x16x32_bf16 v[80:83], v[152:155], v[186:189], v[80:83]
	v_mfma_f32_16x16x32_bf16 v[56:59], v[140:143], v[194:197], v[56:59]
	v_mfma_f32_16x16x32_bf16 v[48:51], v[152:155], v[194:197], v[48:51]
	v_mfma_f32_16x16x32_bf16 v[24:27], v[140:143], v[202:205], v[24:27]
	v_mfma_f32_16x16x32_bf16 v[16:19], v[152:155], v[202:205], v[16:19]
	s_setprio 0
	s_setprio 1
	v_mfma_f32_16x16x32_bf16 v[104:107], v[156:159], v[172:175], v[104:107]
	v_mfma_f32_16x16x32_bf16 v[96:99], v[164:167], v[172:175], v[96:99]
	v_mfma_f32_16x16x32_bf16 v[72:75], v[156:159], v[182:185], v[72:75]
	v_mfma_f32_16x16x32_bf16 v[64:67], v[164:167], v[182:185], v[64:67]
	v_mfma_f32_16x16x32_bf16 v[40:43], v[156:159], v[190:193], v[40:43]
	v_mfma_f32_16x16x32_bf16 v[32:35], v[164:167], v[190:193], v[32:35]
	v_mfma_f32_16x16x32_bf16 v[8:11], v[156:159], v[198:201], v[8:11]
	v_mfma_f32_16x16x32_bf16 v[4:7], v[164:167], v[198:201], v[4:7]
	v_mfma_f32_16x16x32_bf16 v[104:107], v[160:163], v[178:181], v[104:107]
	v_mfma_f32_16x16x32_bf16 v[96:99], v[168:171], v[178:181], v[96:99]
	v_mfma_f32_16x16x32_bf16 v[72:75], v[160:163], v[186:189], v[72:75]
	v_mfma_f32_16x16x32_bf16 v[64:67], v[168:171], v[186:189], v[64:67]
	v_mfma_f32_16x16x32_bf16 v[40:43], v[160:163], v[194:197], v[40:43]
	v_mfma_f32_16x16x32_bf16 v[32:35], v[168:171], v[194:197], v[32:35]
	v_mfma_f32_16x16x32_bf16 v[8:11], v[160:163], v[202:205], v[8:11]
	v_mfma_f32_16x16x32_bf16 v[4:7], v[168:171], v[202:205], v[4:7]
	s_setprio 0
	s_barrier
; #define PG8_STAGE(bufoff, gbase, voff) do { _Pragma("unroll") for (int _i = 0; _i < 2; ++_i) \
;         __builtin_amdgcn_global_load_lds((const unsigned*)((const char*)(gbase) + (voff)[_i]), (LAS unsigned*)(lds + (bufoff) + ldsw + _i * 8192), 16, 0, 0); } while (0)
; #define PG8_LDA(dst, b, h) do { _Pragma("unroll") for (int m = 0; m < 4; ++m) _Pragma("unroll") for (int k = 0; k < 2; ++k) dst[m][k] = *(const LAS bf16x8*)(lds + PG8_SA(b, h) + aoff + m * 2048 + k * 1024); } while (0)
; #define PG8_MMA(ai, bj, At, Bt) do { __builtin_amdgcn_s_setprio(1); _Pragma("unroll") for (int m = 0; m < 4; ++m) _Pragma("unroll") for (int n = 0; n < 2; ++n) _Pragma("unroll") for (int k = 0; k < 2; ++k) \
;         acc[ai][bj][m][n] = __builtin_amdgcn_mfma_f32_16x16x32_bf16(Bt[n][k], At[m][k], acc[ai][bj][m][n], 0, 0, 0); __builtin_amdgcn_s_setprio(0); } while (0)
; #define PG8_WAIT_V(n) asm volatile("s_waitcnt vmcnt(" #n ")" ::: "memory")
; #define PG8_WAIT_L(n) asm volatile("s_waitcnt lgkmcnt(" #n ")" ::: "memory")
; #define PG8_BAR __builtin_amdgcn_s_barrier()
; #define PG8_SCHED __builtin_amdgcn_sched_barrier(0)
; template <class Epi>
; DI void gemm_phase(LAS unsigned char* lds, const Gemm g, const Order& S, const Epi& E) {
;     ...
;             PG8_LDA(At, 1, 1); PG8_STAGE(PG8_SB(1, 0), b3, voffB); PG8_STAGE(PG8_SB(1, 1), b3 + hstepB, voffB); PG8_STAGE(PG8_SA(1, 0), a3, voffA);
;             PG8_WAIT_V(8); PG8_WAIT_L(0); PG8_BAR; PG8_MMA(1, 0, At, B0); PG8_MMA(1, 1, At, B1); PG8_BAR; PG8_SCHED;
;         }
	s_add_i32 s22, s85, s36
	v_lshl_add_u64 v[206:207], v[206:207], 0, s[56:57]
	s_mov_b32 m0, s22
	ds_read_b128 v[172:175], v147 offset:49152
	ds_read_b128 v[178:181], v147 offset:50176
	ds_read_b128 v[182:185], v147 offset:51200
	ds_read_b128 v[186:189], v147 offset:52224
	ds_read_b128 v[190:193], v147 offset:53248
	ds_read_b128 v[194:197], v147 offset:54272
	ds_read_b128 v[198:201], v147 offset:55296
	ds_read_b128 v[202:205], v147 offset:56320
	global_load_lds_dwordx4 v[206:207], off
	s_add_i32 m0, s22, 0x2000
	s_add_u32 s22, s26, 0x8080
	v_lshl_add_u64 v[206:207], v[208:209], 0, s[56:57]
	s_addc_u32 s23, s27, 0
	s_add_i32 s26, s86, s36
	global_load_lds_dwordx4 v[206:207], off
	v_lshl_add_u64 v[206:207], s[22:23], 0, v[130:131]
	s_mov_b32 m0, s26
	s_nop 0
	global_load_lds_dwordx4 v[206:207], off
	v_lshl_add_u64 v[206:207], s[22:23], 0, v[128:129]
	s_add_i32 m0, s26, 0x2000
	s_nop 0
	global_load_lds_dwordx4 v[206:207], off
	v_lshl_add_u64 v[206:207], v[210:211], 0, s[56:57]
	s_mov_b32 m0, s76
	s_nop 0
	global_load_lds_dwordx4 v[206:207], off
	v_lshl_add_u64 v[206:207], v[212:213], 0, s[56:57]
	s_mov_b32 m0, s77
	s_nop 0
	global_load_lds_dwordx4 v[206:207], off
	s_waitcnt vmcnt(8)
	s_waitcnt lgkmcnt(0)
	s_barrier
	s_setprio 1
	v_mfma_f32_16x16x32_bf16 v[124:127], v[136:139], v[172:175], v[124:127]
	v_mfma_f32_16x16x32_bf16 v[116:119], v[148:151], v[172:175], v[116:119]
	v_mfma_f32_16x16x32_bf16 v[92:95], v[136:139], v[182:185], v[92:95]
	v_mfma_f32_16x16x32_bf16 v[84:87], v[148:151], v[182:185], v[84:87]
	v_mfma_f32_16x16x32_bf16 v[60:63], v[136:139], v[190:193], v[60:63]
	v_mfma_f32_16x16x32_bf16 v[52:55], v[148:151], v[190:193], v[52:55]
	v_mfma_f32_16x16x32_bf16 v[28:31], v[136:139], v[198:201], v[28:31]
	v_mfma_f32_16x16x32_bf16 v[20:23], v[148:151], v[198:201], v[20:23]
	v_mfma_f32_16x16x32_bf16 v[124:127], v[140:143], v[178:181], v[124:127]
	v_mfma_f32_16x16x32_bf16 v[116:119], v[152:155], v[178:181], v[116:119]
	v_mfma_f32_16x16x32_bf16 v[92:95], v[140:143], v[186:189], v[92:95]
	v_mfma_f32_16x16x32_bf16 v[84:87], v[152:155], v[186:189], v[84:87]
	v_mfma_f32_16x16x32_bf16 v[60:63], v[140:143], v[194:197], v[60:63]
	v_mfma_f32_16x16x32_bf16 v[52:55], v[152:155], v[194:197], v[52:55]
	v_mfma_f32_16x16x32_bf16 v[28:31], v[140:143], v[202:205], v[28:31]
	v_mfma_f32_16x16x32_bf16 v[20:23], v[152:155], v[202:205], v[20:23]
	s_setprio 0
	s_setprio 1
	v_mfma_f32_16x16x32_bf16 v[108:111], v[156:159], v[172:175], v[108:111]
	v_mfma_f32_16x16x32_bf16 v[100:103], v[164:167], v[172:175], v[100:103]
	v_mfma_f32_16x16x32_bf16 v[76:79], v[156:159], v[182:185], v[76:79]
	v_mfma_f32_16x16x32_bf16 v[68:71], v[164:167], v[182:185], v[68:71]
	v_mfma_f32_16x16x32_bf16 v[44:47], v[156:159], v[190:193], v[44:47]
	v_mfma_f32_16x16x32_bf16 v[36:39], v[164:167], v[190:193], v[36:39]
	v_mfma_f32_16x16x32_bf16 v[12:15], v[156:159], v[198:201], v[12:15]
	v_mfma_f32_16x16x32_bf16 v[0:3], v[164:167], v[198:201], v[0:3]
	v_mfma_f32_16x16x32_bf16 v[108:111], v[160:163], v[178:181], v[108:111]
	v_mfma_f32_16x16x32_bf16 v[100:103], v[168:171], v[178:181], v[100:103]
	v_mfma_f32_16x16x32_bf16 v[76:79], v[160:163], v[186:189], v[76:79]
	v_mfma_f32_16x16x32_bf16 v[68:71], v[168:171], v[186:189], v[68:71]
	v_mfma_f32_16x16x32_bf16 v[44:47], v[160:163], v[194:197], v[44:47]
	v_mfma_f32_16x16x32_bf16 v[36:39], v[168:171], v[194:197], v[36:39]
	v_mfma_f32_16x16x32_bf16 v[12:15], v[160:163], v[202:205], v[12:15]
	v_mfma_f32_16x16x32_bf16 v[0:3], v[168:171], v[202:205], v[0:3]
	s_setprio 0
	s_barrier
	s_cmp_ge_i32 s84, s73
	s_mov_b64 s[22:23], s[24:25]
	s_mov_b32 s26, s84
	s_cbranch_scc0 .LBB0_435
	s_mov_b32 s82, 0x3a490fdb
	s_mov_b32 s84, 0x3bb504f3

; #define PG8_STAGE(bufoff, gbase, voff) do { _Pragma("unroll") for (int _i = 0; _i < 2; ++_i) \
;         __builtin_amdgcn_global_load_lds((const unsigned*)((const char*)(gbase) + (voff)[_i]), (LAS unsigned*)(lds + (bufoff) + ldsw + _i * 8192), 16, 0, 0); } while (0)
; #define PG8_LDA(dst, b, h) do { _Pragma("unroll") for (int m = 0; m < 4; ++m) _Pragma("unroll") for (int k = 0; k < 2; ++k) dst[m][k] = *(const LAS bf16x8*)(lds + PG8_SA(b, h) + aoff + m * 2048 + k * 1024); } while (0)
; #define PG8_LDB(dst, b, h) do { _Pragma("unroll") for (int n = 0; n < 2; ++n) _Pragma("unroll") for (int k = 0; k < 2; ++k) dst[n][k] = *(const LAS bf16x8*)(lds + PG8_SB(b, h) + boff + n * 2048 + k * 1024); } while (0)
; #define PG8_MMA(ai, bj, At, Bt) do { __builtin_amdgcn_s_setprio(1); _Pragma("unroll") for (int m = 0; m < 4; ++m) _Pragma("unroll") for (int n = 0; n < 2; ++n) _Pragma("unroll") for (int k = 0; k < 2; ++k) \
;         acc[ai][bj][m][n] = __builtin_amdgcn_mfma_f32_16x16x32_bf16(Bt[n][k], At[m][k], acc[ai][bj][m][n], 0, 0, 0); __builtin_amdgcn_s_setprio(0); } while (0)
; #define PG8_WAIT_V(n) asm volatile("s_waitcnt vmcnt(" #n ")" ::: "memory")
; #define PG8_WAIT_L(n) asm volatile("s_waitcnt lgkmcnt(" #n ")" ::: "memory")
; #define PG8_BAR __builtin_amdgcn_s_barrier()
; #define PG8_SCHED __builtin_amdgcn_sched_barrier(0)
; template <class Epi>
; DI void gemm_phase(LAS unsigned char* lds, const Gemm g, const Order& S, const Epi& E) {
;     ...
;         for (int t = 0; t < nt; t += 2) {
;             const bool last = (t == nt - 2);
;             const char* a1 = cA + (size_t)(t + 1) * kstep;
;             const char* a2 = last ? nA : cA + (size_t)(t + 2) * kstep; const char* b2 = last ? nB : cB + (size_t)(t + 2) * kstep;
;             const char* a3 = a2 + kstep; const char* b3 = b2 + kstep;
;             PG8_LDB(B0, 0, 0); PG8_LDB(B1, 0, 1); PG8_SCHED; PG8_LDA(At, 0, 0); PG8_STAGE(PG8_SA(1, 1), a1 + hstepA, voffA);
;             PG8_WAIT_V(8); PG8_WAIT_L(0); PG8_BAR; PG8_MMA(0, 0, At, B0); PG8_MMA(0, 1, At, B1); PG8_BAR; PG8_SCHED;
;             PG8_LDA(At, 0, 1); PG8_STAGE(PG8_SB(0, 0), b2, voffB); PG8_STAGE(PG8_SB(0, 1), b2 + hstepB, voffB); PG8_STAGE(PG8_SA(0, 0), a2, voffA);
;             PG8_WAIT_V(8); PG8_WAIT_L(0); PG8_BAR; PG8_MMA(1, 0, At, B0); PG8_MMA(1, 1, At, B1); PG8_BAR; PG8_SCHED;
.LBB0_449:
	s_add_i32 s35, s14, 2
	s_add_u32 s15, s12, 0xf9da8080
	s_addc_u32 s16, s13, -1
	s_cmp_lg_u32 s34, s14
	s_cselect_b32 s14, s15, 0
	s_cselect_b32 s36, s16, 0
	s_add_u32 s16, s6, s14
	s_addc_u32 s17, s7, s36
	s_add_i32 s37, 0, 0x10000
	s_add_u32 s14, s10, s14
	s_addc_u32 s15, s11, s36
	s_add_i32 s40, 0, 0x14000
	v_add_u32_e32 v150, s37, v136
	v_add_u32_e32 v166, s40, v136
	ds_read_b128 v[138:141], v150
	ds_read_b128 v[142:145], v150 offset:1024
	ds_read_b128 v[146:149], v150 offset:2048
	ds_read_b128 v[150:153], v150 offset:3072
	ds_read_b128 v[154:157], v166
	ds_read_b128 v[158:161], v166 offset:1024
	ds_read_b128 v[162:165], v166 offset:2048
	ds_read_b128 v[166:169], v166 offset:3072
	v_lshl_add_u64 v[174:175], v[132:133], 0, s[12:13]
	s_add_i32 m0, s25, 0xc000
	ds_read_b128 v[170:173], v137
	ds_read_b128 v[178:181], v137 offset:1024
	ds_read_b128 v[182:185], v137 offset:2048
	ds_read_b128 v[186:189], v137 offset:3072
	ds_read_b128 v[190:193], v137 offset:4096
	ds_read_b128 v[194:197], v137 offset:5120
	ds_read_b128 v[198:201], v137 offset:6144
	ds_read_b128 v[202:205], v137 offset:7168
	global_load_lds_dwordx4 v[174:175], off
	v_lshl_add_u64 v[174:175], v[130:131], 0, s[12:13]
	s_add_i32 m0, s25, 0xe000
	s_nop 0
	global_load_lds_dwordx4 v[174:175], off
	s_waitcnt vmcnt(8)
	s_waitcnt lgkmcnt(0)
	s_barrier
	s_setprio 1
	v_mfma_f32_16x16x32_bf16 v[124:127], v[138:141], v[170:173], v[124:127]
	v_mfma_f32_16x16x32_bf16 v[120:123], v[146:149], v[170:173], v[120:123]
	v_mfma_f32_16x16x32_bf16 v[108:111], v[138:141], v[182:185], v[108:111]
	v_mfma_f32_16x16x32_bf16 v[104:107], v[146:149], v[182:185], v[104:107]
	v_mfma_f32_16x16x32_bf16 v[92:95], v[138:141], v[190:193], v[92:95]
	v_mfma_f32_16x16x32_bf16 v[88:91], v[146:149], v[190:193], v[88:91]
	v_mfma_f32_16x16x32_bf16 v[76:79], v[138:141], v[198:201], v[76:79]
	v_mfma_f32_16x16x32_bf16 v[72:75], v[146:149], v[198:201], v[72:75]
	v_mfma_f32_16x16x32_bf16 v[124:127], v[142:145], v[178:181], v[124:127]
	v_mfma_f32_16x16x32_bf16 v[120:123], v[150:153], v[178:181], v[120:123]
	v_mfma_f32_16x16x32_bf16 v[108:111], v[142:145], v[186:189], v[108:111]
	v_mfma_f32_16x16x32_bf16 v[104:107], v[150:153], v[186:189], v[104:107]
	v_mfma_f32_16x16x32_bf16 v[92:95], v[142:145], v[194:197], v[92:95]
	v_mfma_f32_16x16x32_bf16 v[88:91], v[150:153], v[194:197], v[88:91]
	v_mfma_f32_16x16x32_bf16 v[76:79], v[142:145], v[202:205], v[76:79]
	v_mfma_f32_16x16x32_bf16 v[72:75], v[150:153], v[202:205], v[72:75]
	s_setprio 0
	s_setprio 1
	v_mfma_f32_16x16x32_bf16 v[116:119], v[154:157], v[170:173], v[116:119]
	v_mfma_f32_16x16x32_bf16 v[112:115], v[162:165], v[170:173], v[112:115]
	v_mfma_f32_16x16x32_bf16 v[100:103], v[154:157], v[182:185], v[100:103]
	v_mfma_f32_16x16x32_bf16 v[96:99], v[162:165], v[182:185], v[96:99]
	v_mfma_f32_16x16x32_bf16 v[84:87], v[154:157], v[190:193], v[84:87]
	v_mfma_f32_16x16x32_bf16 v[80:83], v[162:165], v[190:193], v[80:83]
	v_mfma_f32_16x16x32_bf16 v[68:71], v[154:157], v[198:201], v[68:71]
	v_mfma_f32_16x16x32_bf16 v[64:67], v[162:165], v[198:201], v[64:67]
	v_mfma_f32_16x16x32_bf16 v[116:119], v[158:161], v[178:181], v[116:119]
	v_mfma_f32_16x16x32_bf16 v[112:115], v[166:169], v[178:181], v[112:115]
	v_mfma_f32_16x16x32_bf16 v[100:103], v[158:161], v[186:189], v[100:103]
	v_mfma_f32_16x16x32_bf16 v[96:99], v[166:169], v[186:189], v[96:99]
	v_mfma_f32_16x16x32_bf16 v[84:87], v[158:161], v[194:197], v[84:87]
	v_mfma_f32_16x16x32_bf16 v[80:83], v[166:169], v[194:197], v[80:83]
	v_mfma_f32_16x16x32_bf16 v[68:71], v[158:161], v[202:205], v[68:71]
	v_mfma_f32_16x16x32_bf16 v[64:67], v[166:169], v[202:205], v[64:67]
	s_setprio 0
	s_barrier
	s_add_i32 s36, s37, s24
	v_lshl_add_u64 v[174:175], s[14:15], 0, v[176:177]
	s_mov_b32 m0, s36
	ds_read_b128 v[170:173], v137 offset:16384
	ds_read_b128 v[178:181], v137 offset:17408
	ds_read_b128 v[182:185], v137 offset:18432
	ds_read_b128 v[186:189], v137 offset:19456
	ds_read_b128 v[190:193], v137 offset:20480
	ds_read_b128 v[194:197], v137 offset:21504
	ds_read_b128 v[198:201], v137 offset:22528
	ds_read_b128 v[202:205], v137 offset:23552
	global_load_lds_dwordx4 v[174:175], off
	s_add_i32 m0, s36, 0x2000
	s_add_u32 s36, s14, 0x10000
	v_lshl_add_u64 v[206:207], s[14:15], 0, v[128:129]
	s_addc_u32 s37, s15, 0
	s_add_i32 s40, s40, s24
	global_load_lds_dwordx4 v[206:207], off
	v_lshl_add_u64 v[208:209], s[36:37], 0, v[176:177]
	s_mov_b32 m0, s40
	v_lshl_add_u64 v[210:211], s[16:17], 0, v[128:129]
	global_load_lds_dwordx4 v[208:209], off
	v_lshl_add_u64 v[208:209], s[36:37], 0, v[128:129]
	s_add_i32 m0, s40, 0x2000
	s_nop 0
	global_load_lds_dwordx4 v[208:209], off
	v_lshl_add_u64 v[208:209], s[16:17], 0, v[176:177]
	s_mov_b32 m0, s25
	s_nop 0
	global_load_lds_dwordx4 v[208:209], off
	s_mov_b32 m0, s26
	s_nop 0
	global_load_lds_dwordx4 v[210:211], off
	s_waitcnt vmcnt(8)
	s_waitcnt lgkmcnt(0)
	s_barrier
; #define PG8_STAGE(bufoff, gbase, voff) do { _Pragma("unroll") for (int _i = 0; _i < 2; ++_i) \
;         __builtin_amdgcn_global_load_lds((const unsigned*)((const char*)(gbase) + (voff)[_i]), (LAS unsigned*)(lds + (bufoff) + ldsw + _i * 8192), 16, 0, 0); } while (0)
; #define PG8_LDA(dst, b, h) do { _Pragma("unroll") for (int m = 0; m < 4; ++m) _Pragma("unroll") for (int k = 0; k < 2; ++k) dst[m][k] = *(const LAS bf16x8*)(lds + PG8_SA(b, h) + aoff + m * 2048 + k * 1024); } while (0)
; #define PG8_LDB(dst, b, h) do { _Pragma("unroll") for (int n = 0; n < 2; ++n) _Pragma("unroll") for (int k = 0; k < 2; ++k) dst[n][k] = *(const LAS bf16x8*)(lds + PG8_SB(b, h) + boff + n * 2048 + k * 1024); } while (0)
; #define PG8_MMA(ai, bj, At, Bt) do { __builtin_amdgcn_s_setprio(1); _Pragma("unroll") for (int m = 0; m < 4; ++m) _Pragma("unroll") for (int n = 0; n < 2; ++n) _Pragma("unroll") for (int k = 0; k < 2; ++k) \
;         acc[ai][bj][m][n] = __builtin_amdgcn_mfma_f32_16x16x32_bf16(Bt[n][k], At[m][k], acc[ai][bj][m][n], 0, 0, 0); __builtin_amdgcn_s_setprio(0); } while (0)
; #define PG8_WAIT_V(n) asm volatile("s_waitcnt vmcnt(" #n ")" ::: "memory")
; #define PG8_WAIT_L(n) asm volatile("s_waitcnt lgkmcnt(" #n ")" ::: "memory")
; #define PG8_BAR __builtin_amdgcn_s_barrier()
; #define PG8_SCHED __builtin_amdgcn_sched_barrier(0)
; template <class Epi>
; DI void gemm_phase(LAS unsigned char* lds, const Gemm g, const Order& S, const Epi& E) {
;     ...
;             PG8_WAIT_V(8); PG8_WAIT_L(0); PG8_BAR; PG8_MMA(1, 0, At, B0); PG8_MMA(1, 1, At, B1); PG8_BAR; PG8_SCHED;
;             PG8_LDB(B0, 1, 0); PG8_LDB(B1, 1, 1); PG8_SCHED; PG8_LDA(At, 1, 0); PG8_STAGE(PG8_SA(0, 1), a2 + hstepA, voffA);
;             PG8_WAIT_V(8); PG8_WAIT_L(0); PG8_BAR; PG8_MMA(0, 0, At, B0); PG8_MMA(0, 1, At, B1); PG8_BAR; PG8_SCHED;
	s_setprio 1
	v_mfma_f32_16x16x32_bf16 v[60:63], v[138:141], v[170:173], v[60:63]
	v_mfma_f32_16x16x32_bf16 v[56:59], v[146:149], v[170:173], v[56:59]
	v_mfma_f32_16x16x32_bf16 v[44:47], v[138:141], v[182:185], v[44:47]
	v_mfma_f32_16x16x32_bf16 v[40:43], v[146:149], v[182:185], v[40:43]
	v_mfma_f32_16x16x32_bf16 v[28:31], v[138:141], v[190:193], v[28:31]
	v_mfma_f32_16x16x32_bf16 v[24:27], v[146:149], v[190:193], v[24:27]
	v_mfma_f32_16x16x32_bf16 v[12:15], v[138:141], v[198:201], v[12:15]
	v_mfma_f32_16x16x32_bf16 v[8:11], v[146:149], v[198:201], v[8:11]
	v_mfma_f32_16x16x32_bf16 v[60:63], v[142:145], v[178:181], v[60:63]
	v_mfma_f32_16x16x32_bf16 v[56:59], v[150:153], v[178:181], v[56:59]
	v_mfma_f32_16x16x32_bf16 v[44:47], v[142:145], v[186:189], v[44:47]
	v_mfma_f32_16x16x32_bf16 v[40:43], v[150:153], v[186:189], v[40:43]
	v_mfma_f32_16x16x32_bf16 v[28:31], v[142:145], v[194:197], v[28:31]
	v_mfma_f32_16x16x32_bf16 v[24:27], v[150:153], v[194:197], v[24:27]
	v_mfma_f32_16x16x32_bf16 v[12:15], v[142:145], v[202:205], v[12:15]
	v_mfma_f32_16x16x32_bf16 v[8:11], v[150:153], v[202:205], v[8:11]
	s_setprio 0
	s_setprio 1
	v_mfma_f32_16x16x32_bf16 v[52:55], v[154:157], v[170:173], v[52:55]
	v_mfma_f32_16x16x32_bf16 v[48:51], v[162:165], v[170:173], v[48:51]
	v_mfma_f32_16x16x32_bf16 v[36:39], v[154:157], v[182:185], v[36:39]
	v_mfma_f32_16x16x32_bf16 v[32:35], v[162:165], v[182:185], v[32:35]
	v_mfma_f32_16x16x32_bf16 v[20:23], v[154:157], v[190:193], v[20:23]
	v_mfma_f32_16x16x32_bf16 v[16:19], v[162:165], v[190:193], v[16:19]
	v_mfma_f32_16x16x32_bf16 v[4:7], v[154:157], v[198:201], v[4:7]
	v_mfma_f32_16x16x32_bf16 v[0:3], v[162:165], v[198:201], v[0:3]
	v_mfma_f32_16x16x32_bf16 v[52:55], v[158:161], v[178:181], v[52:55]
	v_mfma_f32_16x16x32_bf16 v[48:51], v[166:169], v[178:181], v[48:51]
	v_mfma_f32_16x16x32_bf16 v[36:39], v[158:161], v[186:189], v[36:39]
	v_mfma_f32_16x16x32_bf16 v[32:35], v[166:169], v[186:189], v[32:35]
	v_mfma_f32_16x16x32_bf16 v[20:23], v[158:161], v[194:197], v[20:23]
	v_mfma_f32_16x16x32_bf16 v[16:19], v[166:169], v[194:197], v[16:19]
	v_mfma_f32_16x16x32_bf16 v[4:7], v[158:161], v[202:205], v[4:7]
	v_mfma_f32_16x16x32_bf16 v[0:3], v[166:169], v[202:205], v[0:3]
	s_setprio 0
	s_barrier
	s_add_i32 s36, 0, 0x18000
	s_add_i32 s37, 0, 0x1c000
	v_add_u32_e32 v150, s36, v136
	v_add_u32_e32 v166, s37, v136
	ds_read_b128 v[138:141], v150
	ds_read_b128 v[142:145], v150 offset:1024
	ds_read_b128 v[146:149], v150 offset:2048
	ds_read_b128 v[150:153], v150 offset:3072
	ds_read_b128 v[154:157], v166
	ds_read_b128 v[158:161], v166 offset:1024
	ds_read_b128 v[162:165], v166 offset:2048
	ds_read_b128 v[166:169], v166 offset:3072
	s_add_u32 s16, s16, 0x10000
	s_addc_u32 s17, s17, 0
	s_mov_b32 m0, s27
	v_lshl_add_u64 v[212:213], s[16:17], 0, v[176:177]
	ds_read_b128 v[170:173], v137 offset:32768
	ds_read_b128 v[178:181], v137 offset:33792
	ds_read_b128 v[182:185], v137 offset:34816
	ds_read_b128 v[186:189], v137 offset:35840
	ds_read_b128 v[190:193], v137 offset:36864
	ds_read_b128 v[194:197], v137 offset:37888
	ds_read_b128 v[198:201], v137 offset:38912
	ds_read_b128 v[202:205], v137 offset:39936
	global_load_lds_dwordx4 v[212:213], off
	v_lshl_add_u64 v[212:213], s[16:17], 0, v[128:129]
	s_mov_b32 m0, s28
	s_nop 0
	global_load_lds_dwordx4 v[212:213], off
	s_waitcnt vmcnt(8)
	s_waitcnt lgkmcnt(0)
	s_barrier
	s_setprio 1
	v_mfma_f32_16x16x32_bf16 v[124:127], v[138:141], v[170:173], v[124:127]
	v_mfma_f32_16x16x32_bf16 v[120:123], v[146:149], v[170:173], v[120:123]
	v_mfma_f32_16x16x32_bf16 v[108:111], v[138:141], v[182:185], v[108:111]
	v_mfma_f32_16x16x32_bf16 v[104:107], v[146:149], v[182:185], v[104:107]
	v_mfma_f32_16x16x32_bf16 v[92:95], v[138:141], v[190:193], v[92:95]
	v_mfma_f32_16x16x32_bf16 v[88:91], v[146:149], v[190:193], v[88:91]
	v_mfma_f32_16x16x32_bf16 v[76:79], v[138:141], v[198:201], v[76:79]
	v_mfma_f32_16x16x32_bf16 v[72:75], v[146:149], v[198:201], v[72:75]
	v_mfma_f32_16x16x32_bf16 v[124:127], v[142:145], v[178:181], v[124:127]
	v_mfma_f32_16x16x32_bf16 v[120:123], v[150:153], v[178:181], v[120:123]
	v_mfma_f32_16x16x32_bf16 v[108:111], v[142:145], v[186:189], v[108:111]
	v_mfma_f32_16x16x32_bf16 v[104:107], v[150:153], v[186:189], v[104:107]
	v_mfma_f32_16x16x32_bf16 v[92:95], v[142:145], v[194:197], v[92:95]
	v_mfma_f32_16x16x32_bf16 v[88:91], v[150:153], v[194:197], v[88:91]
	v_mfma_f32_16x16x32_bf16 v[76:79], v[142:145], v[202:205], v[76:79]
	v_mfma_f32_16x16x32_bf16 v[72:75], v[150:153], v[202:205], v[72:75]
	s_setprio 0
	s_setprio 1
	v_mfma_f32_16x16x32_bf16 v[116:119], v[154:157], v[170:173], v[116:119]
	v_mfma_f32_16x16x32_bf16 v[112:115], v[162:165], v[170:173], v[112:115]
	v_mfma_f32_16x16x32_bf16 v[100:103], v[154:157], v[182:185], v[100:103]
	v_mfma_f32_16x16x32_bf16 v[96:99], v[162:165], v[182:185], v[96:99]
	v_mfma_f32_16x16x32_bf16 v[84:87], v[154:157], v[190:193], v[84:87]
	v_mfma_f32_16x16x32_bf16 v[80:83], v[162:165], v[190:193], v[80:83]
	v_mfma_f32_16x16x32_bf16 v[68:71], v[154:157], v[198:201], v[68:71]
	v_mfma_f32_16x16x32_bf16 v[64:67], v[162:165], v[198:201], v[64:67]
	v_mfma_f32_16x16x32_bf16 v[116:119], v[158:161], v[178:181], v[116:119]
	v_mfma_f32_16x16x32_bf16 v[112:115], v[166:169], v[178:181], v[112:115]
	v_mfma_f32_16x16x32_bf16 v[100:103], v[158:161], v[186:189], v[100:103]
	v_mfma_f32_16x16x32_bf16 v[96:99], v[166:169], v[186:189], v[96:99]
	v_mfma_f32_16x16x32_bf16 v[84:87], v[158:161], v[194:197], v[84:87]
	v_mfma_f32_16x16x32_bf16 v[80:83], v[166:169], v[194:197], v[80:83]
	v_mfma_f32_16x16x32_bf16 v[68:71], v[158:161], v[202:205], v[68:71]
	v_mfma_f32_16x16x32_bf16 v[64:67], v[166:169], v[202:205], v[64:67]
	s_setprio 0
	s_barrier
; #define PG8_STAGE(bufoff, gbase, voff) do { _Pragma("unroll") for (int _i = 0; _i < 2; ++_i) \
;         __builtin_amdgcn_global_load_lds((const unsigned*)((const char*)(gbase) + (voff)[_i]), (LAS unsigned*)(lds + (bufoff) + ldsw + _i * 8192), 16, 0, 0); } while (0)
; #define PG8_LDA(dst, b, h) do { _Pragma("unroll") for (int m = 0; m < 4; ++m) _Pragma("unroll") for (int k = 0; k < 2; ++k) dst[m][k] = *(const LAS bf16x8*)(lds + PG8_SA(b, h) + aoff + m * 2048 + k * 1024); } while (0)
; #define PG8_MMA(ai, bj, At, Bt) do { __builtin_amdgcn_s_setprio(1); _Pragma("unroll") for (int m = 0; m < 4; ++m) _Pragma("unroll") for (int n = 0; n < 2; ++n) _Pragma("unroll") for (int k = 0; k < 2; ++k) \
;         acc[ai][bj][m][n] = __builtin_amdgcn_mfma_f32_16x16x32_bf16(Bt[n][k], At[m][k], acc[ai][bj][m][n], 0, 0, 0); __builtin_amdgcn_s_setprio(0); } while (0)
; #define PG8_WAIT_V(n) asm volatile("s_waitcnt vmcnt(" #n ")" ::: "memory")
; #define PG8_WAIT_L(n) asm volatile("s_waitcnt lgkmcnt(" #n ")" ::: "memory")
; #define PG8_BAR __builtin_amdgcn_s_barrier()
; #define PG8_SCHED __builtin_amdgcn_sched_barrier(0)
; template <class Epi>
; DI void gemm_phase(LAS unsigned char* lds, const Gemm g, const Order& S, const Epi& E) {
;     ...
;             PG8_LDA(At, 1, 1); PG8_STAGE(PG8_SB(1, 0), b3, voffB); PG8_STAGE(PG8_SB(1, 1), b3 + hstepB, voffB); PG8_STAGE(PG8_SA(1, 0), a3, voffA);
;             PG8_WAIT_V(8); PG8_WAIT_L(0); PG8_BAR; PG8_MMA(1, 0, At, B0); PG8_MMA(1, 1, At, B1); PG8_BAR; PG8_SCHED;
;         }
	s_add_i32 s16, s36, s24
	v_lshl_add_u64 v[174:175], v[174:175], 0, s[56:57]
	s_mov_b32 m0, s16
	ds_read_b128 v[170:173], v137 offset:49152
	ds_read_b128 v[178:181], v137 offset:50176
	ds_read_b128 v[182:185], v137 offset:51200
	ds_read_b128 v[186:189], v137 offset:52224
	ds_read_b128 v[190:193], v137 offset:53248
	ds_read_b128 v[194:197], v137 offset:54272
	ds_read_b128 v[198:201], v137 offset:55296
	ds_read_b128 v[202:205], v137 offset:56320
	global_load_lds_dwordx4 v[174:175], off
	s_add_i32 m0, s16, 0x2000
	s_add_u32 s14, s14, 0x10080
	v_lshl_add_u64 v[174:175], v[206:207], 0, s[56:57]
	s_addc_u32 s15, s15, 0
	s_add_i32 s16, s37, s24
	global_load_lds_dwordx4 v[174:175], off
	v_lshl_add_u64 v[174:175], s[14:15], 0, v[176:177]
	s_mov_b32 m0, s16
	s_nop 0
	global_load_lds_dwordx4 v[174:175], off
	v_lshl_add_u64 v[174:175], s[14:15], 0, v[128:129]
	s_add_i32 m0, s16, 0x2000
	s_nop 0
	global_load_lds_dwordx4 v[174:175], off
	v_lshl_add_u64 v[174:175], v[208:209], 0, s[56:57]
	s_mov_b32 m0, s29
	s_nop 0
	global_load_lds_dwordx4 v[174:175], off
	v_lshl_add_u64 v[174:175], v[210:211], 0, s[56:57]
	s_mov_b32 m0, s30
	s_nop 0
	global_load_lds_dwordx4 v[174:175], off
	s_waitcnt vmcnt(8)
	s_waitcnt lgkmcnt(0)
	s_barrier
	s_setprio 1
	v_mfma_f32_16x16x32_bf16 v[60:63], v[138:141], v[170:173], v[60:63]
	v_mfma_f32_16x16x32_bf16 v[56:59], v[146:149], v[170:173], v[56:59]
	v_mfma_f32_16x16x32_bf16 v[44:47], v[138:141], v[182:185], v[44:47]
	v_mfma_f32_16x16x32_bf16 v[40:43], v[146:149], v[182:185], v[40:43]
	v_mfma_f32_16x16x32_bf16 v[28:31], v[138:141], v[190:193], v[28:31]
	v_mfma_f32_16x16x32_bf16 v[24:27], v[146:149], v[190:193], v[24:27]
	v_mfma_f32_16x16x32_bf16 v[12:15], v[138:141], v[198:201], v[12:15]
	v_mfma_f32_16x16x32_bf16 v[8:11], v[146:149], v[198:201], v[8:11]
	v_mfma_f32_16x16x32_bf16 v[60:63], v[142:145], v[178:181], v[60:63]
	v_mfma_f32_16x16x32_bf16 v[56:59], v[150:153], v[178:181], v[56:59]
	v_mfma_f32_16x16x32_bf16 v[44:47], v[142:145], v[186:189], v[44:47]
	v_mfma_f32_16x16x32_bf16 v[40:43], v[150:153], v[186:189], v[40:43]
	v_mfma_f32_16x16x32_bf16 v[28:31], v[142:145], v[194:197], v[28:31]
	v_mfma_f32_16x16x32_bf16 v[24:27], v[150:153], v[194:197], v[24:27]
	v_mfma_f32_16x16x32_bf16 v[12:15], v[142:145], v[202:205], v[12:15]
	v_mfma_f32_16x16x32_bf16 v[8:11], v[150:153], v[202:205], v[8:11]
	s_setprio 0
	s_setprio 1
	v_mfma_f32_16x16x32_bf16 v[52:55], v[154:157], v[170:173], v[52:55]
	v_mfma_f32_16x16x32_bf16 v[48:51], v[162:165], v[170:173], v[48:51]
	v_mfma_f32_16x16x32_bf16 v[36:39], v[154:157], v[182:185], v[36:39]
	v_mfma_f32_16x16x32_bf16 v[32:35], v[162:165], v[182:185], v[32:35]
	v_mfma_f32_16x16x32_bf16 v[20:23], v[154:157], v[190:193], v[20:23]
	v_mfma_f32_16x16x32_bf16 v[16:19], v[162:165], v[190:193], v[16:19]
	v_mfma_f32_16x16x32_bf16 v[4:7], v[154:157], v[198:201], v[4:7]
	v_mfma_f32_16x16x32_bf16 v[0:3], v[162:165], v[198:201], v[0:3]
	v_mfma_f32_16x16x32_bf16 v[52:55], v[158:161], v[178:181], v[52:55]
	v_mfma_f32_16x16x32_bf16 v[48:51], v[166:169], v[178:181], v[48:51]
	v_mfma_f32_16x16x32_bf16 v[36:39], v[158:161], v[186:189], v[36:39]
	v_mfma_f32_16x16x32_bf16 v[32:35], v[166:169], v[186:189], v[32:35]
	v_mfma_f32_16x16x32_bf16 v[20:23], v[158:161], v[194:197], v[20:23]
	v_mfma_f32_16x16x32_bf16 v[16:19], v[166:169], v[194:197], v[16:19]
	v_mfma_f32_16x16x32_bf16 v[4:7], v[158:161], v[202:205], v[4:7]
	v_mfma_f32_16x16x32_bf16 v[0:3], v[166:169], v[202:205], v[0:3]
	s_setprio 0
	s_barrier
	s_add_u32 s12, s12, 0x100
	s_addc_u32 s13, s13, 0
	s_cmp_ge_i32 s35, s31
	s_mov_b32 s14, s35
	s_cbranch_scc0 .LBB0_449

; #define PG8_STAGE(bufoff, gbase, voff) do { _Pragma("unroll") for (int _i = 0; _i < 2; ++_i) \
;         __builtin_amdgcn_global_load_lds((const unsigned*)((const char*)(gbase) + (voff)[_i]), (LAS unsigned*)(lds + (bufoff) + ldsw + _i * 8192), 16, 0, 0); } while (0)
; #define PG8_LDA(dst, b, h) do { _Pragma("unroll") for (int m = 0; m < 4; ++m) _Pragma("unroll") for (int k = 0; k < 2; ++k) dst[m][k] = *(const LAS bf16x8*)(lds + PG8_SA(b, h) + aoff + m * 2048 + k * 1024); } while (0)
; #define PG8_LDB(dst, b, h) do { _Pragma("unroll") for (int n = 0; n < 2; ++n) _Pragma("unroll") for (int k = 0; k < 2; ++k) dst[n][k] = *(const LAS bf16x8*)(lds + PG8_SB(b, h) + boff + n * 2048 + k * 1024); } while (0)
; #define PG8_MMA(ai, bj, At, Bt) do { __builtin_amdgcn_s_setprio(1); _Pragma("unroll") for (int m = 0; m < 4; ++m) _Pragma("unroll") for (int n = 0; n < 2; ++n) _Pragma("unroll") for (int k = 0; k < 2; ++k) \
;         acc[ai][bj][m][n] = __builtin_amdgcn_mfma_f32_16x16x32_bf16(Bt[n][k], At[m][k], acc[ai][bj][m][n], 0, 0, 0); __builtin_amdgcn_s_setprio(0); } while (0)
; #define PG8_WAIT_V(n) asm volatile("s_waitcnt vmcnt(" #n ")" ::: "memory")
; #define PG8_WAIT_L(n) asm volatile("s_waitcnt lgkmcnt(" #n ")" ::: "memory")
; #define PG8_BAR __builtin_amdgcn_s_barrier()
; #define PG8_SCHED __builtin_amdgcn_sched_barrier(0)
; template <class Epi>
; DI void gemm_phase(LAS unsigned char* lds, const Gemm g, const Order& S, const Epi& E) {
;     ...
;         for (int t = 0; t < nt; t += 2) {
;             const bool last = (t == nt - 2);
;             const char* a1 = cA + (size_t)(t + 1) * kstep;
;             const char* a2 = last ? nA : cA + (size_t)(t + 2) * kstep; const char* b2 = last ? nB : cB + (size_t)(t + 2) * kstep;
;             const char* a3 = a2 + kstep; const char* b3 = b2 + kstep;
;             PG8_LDB(B0, 0, 0); PG8_LDB(B1, 0, 1); PG8_SCHED; PG8_LDA(At, 0, 0); PG8_STAGE(PG8_SA(1, 1), a1 + hstepA, voffA);
;             PG8_WAIT_V(8); PG8_WAIT_L(0); PG8_BAR; PG8_MMA(0, 0, At, B0); PG8_MMA(0, 1, At, B1); PG8_BAR; PG8_SCHED;
;             PG8_LDA(At, 0, 1); PG8_STAGE(PG8_SB(0, 0), b2, voffB); PG8_STAGE(PG8_SB(0, 1), b2 + hstepB, voffB); PG8_STAGE(PG8_SA(0, 0), a2, voffA);
;             PG8_WAIT_V(8); PG8_WAIT_L(0); PG8_BAR; PG8_MMA(1, 0, At, B0); PG8_MMA(1, 1, At, B1); PG8_BAR; PG8_SCHED;
.LBB0_513:
	s_add_i32 s83, s26, 2
	s_add_u32 s24, s22, 0x100
	s_addc_u32 s25, s23, 0
	s_add_u32 s27, s81, s22
	s_addc_u32 s28, s82, s23
	s_cmp_eq_u32 s78, s26
	s_cselect_b32 s84, 0, s24
	s_cselect_b32 s29, 0, s25
	s_cselect_b32 s26, s80, s27
	s_cselect_b32 s27, s19, s28
	s_add_u32 s28, s4, s84
	s_addc_u32 s29, s5, s29
	s_add_i32 s84, 0, 0x10000
	s_add_i32 s85, 0, 0x14000
	v_add_u32_e32 v92, s84, v78
	v_add_u32_e32 v108, s85, v78
	ds_read_b128 v[80:83], v92
	ds_read_b128 v[84:87], v92 offset:1024
	ds_read_b128 v[88:91], v92 offset:2048
	ds_read_b128 v[92:95], v92 offset:3072
	ds_read_b128 v[96:99], v108
	ds_read_b128 v[100:103], v108 offset:1024
	ds_read_b128 v[104:107], v108 offset:2048
	ds_read_b128 v[108:111], v108 offset:3072
	v_lshl_add_u64 v[144:145], v[74:75], 0, s[22:23]
	s_add_i32 m0, s37, 0xc000
	ds_read_b128 v[112:115], v79
	ds_read_b128 v[116:119], v79 offset:1024
	ds_read_b128 v[120:123], v79 offset:2048
	ds_read_b128 v[124:127], v79 offset:3072
	ds_read_b128 v[128:131], v79 offset:4096
	ds_read_b128 v[132:135], v79 offset:5120
	ds_read_b128 v[136:139], v79 offset:6144
	ds_read_b128 v[140:143], v79 offset:7168
	global_load_lds_dwordx4 v[144:145], off
	v_lshl_add_u64 v[144:145], v[72:73], 0, s[22:23]
	s_add_i32 m0, s37, 0xe000
	s_nop 0
	global_load_lds_dwordx4 v[144:145], off
	s_waitcnt vmcnt(8)
	s_waitcnt lgkmcnt(0)
	s_barrier
	s_setprio 1
	v_mfma_f32_16x16x32_bf16 v[56:59], v[80:83], v[112:115], v[56:59]
	v_mfma_f32_16x16x32_bf16 v[60:63], v[88:91], v[112:115], v[60:63]
	v_mfma_f32_16x16x32_bf16 v[44:47], v[80:83], v[120:123], v[44:47]
	v_mfma_f32_16x16x32_bf16 v[40:43], v[88:91], v[120:123], v[40:43]
	v_mfma_f32_16x16x32_bf16 v[28:31], v[80:83], v[128:131], v[28:31]
	v_mfma_f32_16x16x32_bf16 v[24:27], v[88:91], v[128:131], v[24:27]
	v_mfma_f32_16x16x32_bf16 v[12:15], v[80:83], v[136:139], v[12:15]
	v_mfma_f32_16x16x32_bf16 v[8:11], v[88:91], v[136:139], v[8:11]
	v_mfma_f32_16x16x32_bf16 v[56:59], v[84:87], v[116:119], v[56:59]
	v_mfma_f32_16x16x32_bf16 v[60:63], v[92:95], v[116:119], v[60:63]
	v_mfma_f32_16x16x32_bf16 v[44:47], v[84:87], v[124:127], v[44:47]
	v_mfma_f32_16x16x32_bf16 v[40:43], v[92:95], v[124:127], v[40:43]
	v_mfma_f32_16x16x32_bf16 v[28:31], v[84:87], v[132:135], v[28:31]
	v_mfma_f32_16x16x32_bf16 v[24:27], v[92:95], v[132:135], v[24:27]
	v_mfma_f32_16x16x32_bf16 v[12:15], v[84:87], v[140:143], v[12:15]
	v_mfma_f32_16x16x32_bf16 v[8:11], v[92:95], v[140:143], v[8:11]
	s_setprio 0
	s_setprio 1
	v_mfma_f32_16x16x32_bf16 v[52:55], v[96:99], v[112:115], v[52:55]
	v_mfma_f32_16x16x32_bf16 v[48:51], v[104:107], v[112:115], v[48:51]
	v_mfma_f32_16x16x32_bf16 v[36:39], v[96:99], v[120:123], v[36:39]
	v_mfma_f32_16x16x32_bf16 v[32:35], v[104:107], v[120:123], v[32:35]
	v_mfma_f32_16x16x32_bf16 v[20:23], v[96:99], v[128:131], v[20:23]
	v_mfma_f32_16x16x32_bf16 v[16:19], v[104:107], v[128:131], v[16:19]
	v_mfma_f32_16x16x32_bf16 v[4:7], v[96:99], v[136:139], v[4:7]
	v_mfma_f32_16x16x32_bf16 v[0:3], v[104:107], v[136:139], v[0:3]
	v_mfma_f32_16x16x32_bf16 v[52:55], v[100:103], v[116:119], v[52:55]
	v_mfma_f32_16x16x32_bf16 v[48:51], v[108:111], v[116:119], v[48:51]
	v_mfma_f32_16x16x32_bf16 v[36:39], v[100:103], v[124:127], v[36:39]
	v_mfma_f32_16x16x32_bf16 v[32:35], v[108:111], v[124:127], v[32:35]
	v_mfma_f32_16x16x32_bf16 v[20:23], v[100:103], v[132:135], v[20:23]
	v_mfma_f32_16x16x32_bf16 v[16:19], v[108:111], v[132:135], v[16:19]
	v_mfma_f32_16x16x32_bf16 v[4:7], v[100:103], v[140:143], v[4:7]
	v_mfma_f32_16x16x32_bf16 v[0:3], v[108:111], v[140:143], v[0:3]
	s_setprio 0
	s_barrier
	s_add_i32 s22, s84, s36
	v_lshl_add_u64 v[144:145], s[26:27], 0, v[68:69]
	s_mov_b32 m0, s22
	v_lshl_add_u64 v[146:147], s[26:27], 0, v[64:65]
	global_load_lds_dwordx4 v[144:145], off
	s_add_i32 m0, s22, 0x2000
	s_add_u32 s22, s26, 0x8000
	s_addc_u32 s23, s27, 0
	s_add_i32 s84, s85, s36
	global_load_lds_dwordx4 v[146:147], off
	v_lshl_add_u64 v[80:81], s[22:23], 0, v[68:69]
	s_mov_b32 m0, s84
	v_lshl_add_u64 v[148:149], s[28:29], 0, v[70:71]
	global_load_lds_dwordx4 v[80:81], off
	v_lshl_add_u64 v[80:81], s[22:23], 0, v[64:65]
	s_add_i32 m0, s84, 0x2000
	v_lshl_add_u64 v[150:151], s[28:29], 0, v[66:67]
	global_load_lds_dwordx4 v[80:81], off
	s_mov_b32 m0, s37
	s_nop 0
	global_load_lds_dwordx4 v[148:149], off
	s_mov_b32 m0, s40
	s_nop 0
	global_load_lds_dwordx4 v[150:151], off
	s_waitcnt vmcnt(8)
	s_waitcnt lgkmcnt(0)
	s_barrier
; #define PG8_STAGE(bufoff, gbase, voff) do { _Pragma("unroll") for (int _i = 0; _i < 2; ++_i) \
;         __builtin_amdgcn_global_load_lds((const unsigned*)((const char*)(gbase) + (voff)[_i]), (LAS unsigned*)(lds + (bufoff) + ldsw + _i * 8192), 16, 0, 0); } while (0)
; #define PG8_LDA(dst, b, h) do { _Pragma("unroll") for (int m = 0; m < 4; ++m) _Pragma("unroll") for (int k = 0; k < 2; ++k) dst[m][k] = *(const LAS bf16x8*)(lds + PG8_SA(b, h) + aoff + m * 2048 + k * 1024); } while (0)
; #define PG8_LDB(dst, b, h) do { _Pragma("unroll") for (int n = 0; n < 2; ++n) _Pragma("unroll") for (int k = 0; k < 2; ++k) dst[n][k] = *(const LAS bf16x8*)(lds + PG8_SB(b, h) + boff + n * 2048 + k * 1024); } while (0)
; #define PG8_MMA(ai, bj, At, Bt) do { __builtin_amdgcn_s_setprio(1); _Pragma("unroll") for (int m = 0; m < 4; ++m) _Pragma("unroll") for (int n = 0; n < 2; ++n) _Pragma("unroll") for (int k = 0; k < 2; ++k) \
;         acc[ai][bj][m][n] = __builtin_amdgcn_mfma_f32_16x16x32_bf16(Bt[n][k], At[m][k], acc[ai][bj][m][n], 0, 0, 0); __builtin_amdgcn_s_setprio(0); } while (0)
; #define PG8_WAIT_V(n) asm volatile("s_waitcnt vmcnt(" #n ")" ::: "memory")
; #define PG8_WAIT_L(n) asm volatile("s_waitcnt lgkmcnt(" #n ")" ::: "memory")
; #define PG8_BAR __builtin_amdgcn_s_barrier()
; #define PG8_SCHED __builtin_amdgcn_sched_barrier(0)
; template <class Epi>
; DI void gemm_phase(LAS unsigned char* lds, const Gemm g, const Order& S, const Epi& E) {
;     ...
;             PG8_WAIT_V(8); PG8_WAIT_L(0); PG8_BAR; PG8_MMA(1, 0, At, B0); PG8_MMA(1, 1, At, B1); PG8_BAR; PG8_SCHED;
;             PG8_LDB(B0, 1, 0); PG8_LDB(B1, 1, 1); PG8_SCHED; PG8_LDA(At, 1, 0); PG8_STAGE(PG8_SA(0, 1), a2 + hstepA, voffA);
;             PG8_WAIT_V(8); PG8_WAIT_L(0); PG8_BAR; PG8_MMA(0, 0, At, B0); PG8_MMA(0, 1, At, B1); PG8_BAR; PG8_SCHED;
;             PG8_LDA(At, 1, 1); PG8_STAGE(PG8_SB(1, 0), b3, voffB); PG8_STAGE(PG8_SB(1, 1), b3 + hstepB, voffB); PG8_STAGE(PG8_SA(1, 0), a3, voffA);
;             PG8_WAIT_V(8); PG8_WAIT_L(0); PG8_BAR; PG8_MMA(1, 0, At, B0); PG8_MMA(1, 1, At, B1); PG8_BAR; PG8_SCHED;
;         }
	s_setprio 1
	s_setprio 0
	s_setprio 1
	s_setprio 0
	s_barrier
	s_add_i32 s84, 0, 0x18000
	s_add_i32 s85, 0, 0x1c000
	v_add_u32_e32 v92, s84, v78
	v_add_u32_e32 v108, s85, v78
	ds_read_b128 v[80:83], v92
	ds_read_b128 v[84:87], v92 offset:1024
	ds_read_b128 v[88:91], v92 offset:2048
	ds_read_b128 v[92:95], v92 offset:3072
	ds_read_b128 v[96:99], v108
	ds_read_b128 v[100:103], v108 offset:1024
	ds_read_b128 v[104:107], v108 offset:2048
	ds_read_b128 v[108:111], v108 offset:3072
	s_add_u32 s22, s28, 0x8000
	s_addc_u32 s23, s29, 0
	s_mov_b32 m0, s65
	v_lshl_add_u64 v[152:153], s[22:23], 0, v[70:71]
	ds_read_b128 v[112:115], v79 offset:32768
	ds_read_b128 v[116:119], v79 offset:33792
	ds_read_b128 v[120:123], v79 offset:34816
	ds_read_b128 v[124:127], v79 offset:35840
	ds_read_b128 v[128:131], v79 offset:36864
	ds_read_b128 v[132:135], v79 offset:37888
	ds_read_b128 v[136:139], v79 offset:38912
	ds_read_b128 v[140:143], v79 offset:39936
	global_load_lds_dwordx4 v[152:153], off
	v_lshl_add_u64 v[152:153], s[22:23], 0, v[66:67]
	s_mov_b32 m0, s72
	s_nop 0
	global_load_lds_dwordx4 v[152:153], off
	s_waitcnt vmcnt(8)
	s_waitcnt lgkmcnt(0)
	s_barrier
	s_setprio 1
	v_mfma_f32_16x16x32_bf16 v[56:59], v[80:83], v[112:115], v[56:59]
	v_mfma_f32_16x16x32_bf16 v[60:63], v[88:91], v[112:115], v[60:63]
	v_mfma_f32_16x16x32_bf16 v[44:47], v[80:83], v[120:123], v[44:47]
	v_mfma_f32_16x16x32_bf16 v[40:43], v[88:91], v[120:123], v[40:43]
	v_mfma_f32_16x16x32_bf16 v[28:31], v[80:83], v[128:131], v[28:31]
	v_mfma_f32_16x16x32_bf16 v[24:27], v[88:91], v[128:131], v[24:27]
	v_mfma_f32_16x16x32_bf16 v[12:15], v[80:83], v[136:139], v[12:15]
	v_mfma_f32_16x16x32_bf16 v[8:11], v[88:91], v[136:139], v[8:11]
	v_mfma_f32_16x16x32_bf16 v[56:59], v[84:87], v[116:119], v[56:59]
	v_mfma_f32_16x16x32_bf16 v[60:63], v[92:95], v[116:119], v[60:63]
	v_mfma_f32_16x16x32_bf16 v[44:47], v[84:87], v[124:127], v[44:47]
	v_mfma_f32_16x16x32_bf16 v[40:43], v[92:95], v[124:127], v[40:43]
	v_mfma_f32_16x16x32_bf16 v[28:31], v[84:87], v[132:135], v[28:31]
	v_mfma_f32_16x16x32_bf16 v[24:27], v[92:95], v[132:135], v[24:27]
	v_mfma_f32_16x16x32_bf16 v[12:15], v[84:87], v[140:143], v[12:15]
	v_mfma_f32_16x16x32_bf16 v[8:11], v[92:95], v[140:143], v[8:11]
	s_setprio 0
	s_setprio 1
	v_mfma_f32_16x16x32_bf16 v[52:55], v[96:99], v[112:115], v[52:55]
	v_mfma_f32_16x16x32_bf16 v[48:51], v[104:107], v[112:115], v[48:51]
	v_mfma_f32_16x16x32_bf16 v[36:39], v[96:99], v[120:123], v[36:39]
	v_mfma_f32_16x16x32_bf16 v[32:35], v[104:107], v[120:123], v[32:35]
	v_mfma_f32_16x16x32_bf16 v[20:23], v[96:99], v[128:131], v[20:23]
	v_mfma_f32_16x16x32_bf16 v[16:19], v[104:107], v[128:131], v[16:19]
	v_mfma_f32_16x16x32_bf16 v[4:7], v[96:99], v[136:139], v[4:7]
	v_mfma_f32_16x16x32_bf16 v[0:3], v[104:107], v[136:139], v[0:3]
	v_mfma_f32_16x16x32_bf16 v[52:55], v[100:103], v[116:119], v[52:55]
	v_mfma_f32_16x16x32_bf16 v[48:51], v[108:111], v[116:119], v[48:51]
	v_mfma_f32_16x16x32_bf16 v[36:39], v[100:103], v[124:127], v[36:39]
	v_mfma_f32_16x16x32_bf16 v[32:35], v[108:111], v[124:127], v[32:35]
	v_mfma_f32_16x16x32_bf16 v[20:23], v[100:103], v[132:135], v[20:23]
	v_mfma_f32_16x16x32_bf16 v[16:19], v[108:111], v[132:135], v[16:19]
	v_mfma_f32_16x16x32_bf16 v[4:7], v[100:103], v[140:143], v[4:7]
	v_mfma_f32_16x16x32_bf16 v[0:3], v[108:111], v[140:143], v[0:3]
	s_setprio 0
	s_barrier
	s_add_i32 s22, s84, s36
	v_lshl_add_u64 v[80:81], v[144:145], 0, s[56:57]
	s_mov_b32 m0, s22
	s_nop 0
	global_load_lds_dwordx4 v[80:81], off
	s_add_i32 m0, s22, 0x2000
	s_add_u32 s22, s26, 0x8080
	v_lshl_add_u64 v[80:81], v[146:147], 0, s[56:57]
	s_addc_u32 s23, s27, 0
	s_add_i32 s26, s85, s36
	global_load_lds_dwordx4 v[80:81], off
	v_lshl_add_u64 v[80:81], s[22:23], 0, v[68:69]
	s_mov_b32 m0, s26
	s_nop 0
	global_load_lds_dwordx4 v[80:81], off
	v_lshl_add_u64 v[80:81], s[22:23], 0, v[64:65]
	s_add_i32 m0, s26, 0x2000
	s_nop 0
	global_load_lds_dwordx4 v[80:81], off
	v_lshl_add_u64 v[80:81], v[148:149], 0, s[56:57]
	s_mov_b32 m0, s75
	s_nop 0
	global_load_lds_dwordx4 v[80:81], off
	v_lshl_add_u64 v[80:81], v[150:151], 0, s[56:57]
	s_mov_b32 m0, s76
	s_nop 0
	global_load_lds_dwordx4 v[80:81], off
	s_waitcnt vmcnt(8)
	s_waitcnt lgkmcnt(0)
	s_barrier
	s_setprio 1
	s_setprio 0
	s_setprio 1
	s_setprio 0
	s_barrier
	s_cmp_ge_i32 s83, s73
	s_mov_b64 s[22:23], s[24:25]
	s_mov_b32 s26, s83
	s_cbranch_scc0 .LBB0_513
	s_mov_b32 s82, 0x3a490fdb
	s_mov_b32 s84, 0x3bb504f3

; #define PG8_STAGE(bufoff, gbase, voff) do { _Pragma("unroll") for (int _i = 0; _i < 2; ++_i) \
;         __builtin_amdgcn_global_load_lds((const unsigned*)((const char*)(gbase) + (voff)[_i]), (LAS unsigned*)(lds + (bufoff) + ldsw + _i * 8192), 16, 0, 0); } while (0)
; #define PG8_LDA(dst, b, h) do { _Pragma("unroll") for (int m = 0; m < 4; ++m) _Pragma("unroll") for (int k = 0; k < 2; ++k) dst[m][k] = *(const LAS bf16x8*)(lds + PG8_SA(b, h) + aoff + m * 2048 + k * 1024); } while (0)
; #define PG8_LDB(dst, b, h) do { _Pragma("unroll") for (int n = 0; n < 2; ++n) _Pragma("unroll") for (int k = 0; k < 2; ++k) dst[n][k] = *(const LAS bf16x8*)(lds + PG8_SB(b, h) + boff + n * 2048 + k * 1024); } while (0)
; #define PG8_MMA(ai, bj, At, Bt) do { __builtin_amdgcn_s_setprio(1); _Pragma("unroll") for (int m = 0; m < 4; ++m) _Pragma("unroll") for (int n = 0; n < 2; ++n) _Pragma("unroll") for (int k = 0; k < 2; ++k) \
;         acc[ai][bj][m][n] = __builtin_amdgcn_mfma_f32_16x16x32_bf16(Bt[n][k], At[m][k], acc[ai][bj][m][n], 0, 0, 0); __builtin_amdgcn_s_setprio(0); } while (0)
; #define PG8_WAIT_V(n) asm volatile("s_waitcnt vmcnt(" #n ")" ::: "memory")
; #define PG8_WAIT_L(n) asm volatile("s_waitcnt lgkmcnt(" #n ")" ::: "memory")
; #define PG8_BAR __builtin_amdgcn_s_barrier()
; #define PG8_SCHED __builtin_amdgcn_sched_barrier(0)
; template <class Epi>
; DI void gemm_phase(LAS unsigned char* lds, const Gemm g, const Order& S, const Epi& E) {
;     ...
;         for (int t = 0; t < nt; t += 2) {
;             const bool last = (t == nt - 2);
;             const char* a1 = cA + (size_t)(t + 1) * kstep;
;             const char* a2 = last ? nA : cA + (size_t)(t + 2) * kstep; const char* b2 = last ? nB : cB + (size_t)(t + 2) * kstep;
;             const char* a3 = a2 + kstep; const char* b3 = b2 + kstep;
;             PG8_LDB(B0, 0, 0); PG8_LDB(B1, 0, 1); PG8_SCHED; PG8_LDA(At, 0, 0); PG8_STAGE(PG8_SA(1, 1), a1 + hstepA, voffA);
;             PG8_WAIT_V(8); PG8_WAIT_L(0); PG8_BAR; PG8_MMA(0, 0, At, B0); PG8_MMA(0, 1, At, B1); PG8_BAR; PG8_SCHED;
;             PG8_LDA(At, 0, 1); PG8_STAGE(PG8_SB(0, 0), b2, voffB); PG8_STAGE(PG8_SB(0, 1), b2 + hstepB, voffB); PG8_STAGE(PG8_SA(0, 0), a2, voffA);
;             PG8_WAIT_V(8); PG8_WAIT_L(0); PG8_BAR; PG8_MMA(1, 0, At, B0); PG8_MMA(1, 1, At, B1); PG8_BAR; PG8_SCHED;
.LBB0_670:
	s_add_i32 s89, s26, 2
	s_add_u32 s27, s24, 0xfffc0080
	s_addc_u32 s28, s25, -1
	s_add_i32 s90, 0, 0x10000
	s_cmp_eq_u32 s85, s26
	s_cselect_b32 s29, s21, s28
	s_cselect_b32 s28, s20, s27
	s_cselect_b32 s27, s23, s19
	s_cselect_b32 s26, s22, s17
	s_add_i32 s92, 0, 0x14000
	v_add_u32_e32 v154, s90, v140
	v_add_u32_e32 v170, s92, v140
	ds_read_b128 v[142:145], v154
	ds_read_b128 v[146:149], v154 offset:1024
	ds_read_b128 v[150:153], v154 offset:2048
	ds_read_b128 v[154:157], v154 offset:3072
	ds_read_b128 v[158:161], v170
	ds_read_b128 v[162:165], v170 offset:1024
	ds_read_b128 v[166:169], v170 offset:2048
	ds_read_b128 v[170:173], v170 offset:3072
	v_lshl_add_u64 v[174:175], s[24:25], 0, v[136:137]
	s_add_i32 m0, s76, 0xc000
	ds_read_b128 v[178:181], v141
	ds_read_b128 v[182:185], v141 offset:1024
	ds_read_b128 v[186:189], v141 offset:2048
	ds_read_b128 v[190:193], v141 offset:3072
	ds_read_b128 v[194:197], v141 offset:4096
	ds_read_b128 v[198:201], v141 offset:5120
	ds_read_b128 v[202:205], v141 offset:6144
	ds_read_b128 v[206:209], v141 offset:7168
	global_load_lds_dwordx4 v[174:175], off
	v_lshl_add_u64 v[174:175], s[24:25], 0, v[134:135]
	s_add_i32 m0, s76, 0xe000
	s_nop 0
	global_load_lds_dwordx4 v[174:175], off
	s_waitcnt vmcnt(8)
	s_waitcnt lgkmcnt(0)
	s_barrier
	s_setprio 1
	v_mfma_f32_16x16x32_bf16 v[120:123], v[142:145], v[178:181], v[120:123]
	v_mfma_f32_16x16x32_bf16 v[124:127], v[150:153], v[178:181], v[124:127]
	v_mfma_f32_16x16x32_bf16 v[108:111], v[142:145], v[186:189], v[108:111]
	v_mfma_f32_16x16x32_bf16 v[104:107], v[150:153], v[186:189], v[104:107]
	v_mfma_f32_16x16x32_bf16 v[92:95], v[142:145], v[194:197], v[92:95]
	v_mfma_f32_16x16x32_bf16 v[88:91], v[150:153], v[194:197], v[88:91]
	v_mfma_f32_16x16x32_bf16 v[76:79], v[142:145], v[202:205], v[76:79]
	v_mfma_f32_16x16x32_bf16 v[72:75], v[150:153], v[202:205], v[72:75]
	v_mfma_f32_16x16x32_bf16 v[120:123], v[146:149], v[182:185], v[120:123]
	v_mfma_f32_16x16x32_bf16 v[124:127], v[154:157], v[182:185], v[124:127]
	v_mfma_f32_16x16x32_bf16 v[108:111], v[146:149], v[190:193], v[108:111]
	v_mfma_f32_16x16x32_bf16 v[104:107], v[154:157], v[190:193], v[104:107]
	v_mfma_f32_16x16x32_bf16 v[92:95], v[146:149], v[198:201], v[92:95]
	v_mfma_f32_16x16x32_bf16 v[88:91], v[154:157], v[198:201], v[88:91]
	v_mfma_f32_16x16x32_bf16 v[76:79], v[146:149], v[206:209], v[76:79]
	v_mfma_f32_16x16x32_bf16 v[72:75], v[154:157], v[206:209], v[72:75]
	s_setprio 0
	s_setprio 1
	v_mfma_f32_16x16x32_bf16 v[116:119], v[158:161], v[178:181], v[116:119]
	v_mfma_f32_16x16x32_bf16 v[112:115], v[166:169], v[178:181], v[112:115]
	v_mfma_f32_16x16x32_bf16 v[100:103], v[158:161], v[186:189], v[100:103]
	v_mfma_f32_16x16x32_bf16 v[96:99], v[166:169], v[186:189], v[96:99]
	v_mfma_f32_16x16x32_bf16 v[84:87], v[158:161], v[194:197], v[84:87]
	v_mfma_f32_16x16x32_bf16 v[80:83], v[166:169], v[194:197], v[80:83]
	v_mfma_f32_16x16x32_bf16 v[68:71], v[158:161], v[202:205], v[68:71]
	v_mfma_f32_16x16x32_bf16 v[64:67], v[166:169], v[202:205], v[64:67]
	v_mfma_f32_16x16x32_bf16 v[116:119], v[162:165], v[182:185], v[116:119]
	v_mfma_f32_16x16x32_bf16 v[112:115], v[170:173], v[182:185], v[112:115]
	v_mfma_f32_16x16x32_bf16 v[100:103], v[162:165], v[190:193], v[100:103]
	v_mfma_f32_16x16x32_bf16 v[96:99], v[170:173], v[190:193], v[96:99]
	v_mfma_f32_16x16x32_bf16 v[84:87], v[162:165], v[198:201], v[84:87]
	v_mfma_f32_16x16x32_bf16 v[80:83], v[170:173], v[198:201], v[80:83]
	v_mfma_f32_16x16x32_bf16 v[68:71], v[162:165], v[206:209], v[68:71]
	v_mfma_f32_16x16x32_bf16 v[64:67], v[170:173], v[206:209], v[64:67]
	s_setprio 0
	s_barrier
	s_add_i32 s90, s90, s65
	v_lshl_add_u64 v[174:175], s[26:27], 0, v[176:177]
	s_mov_b32 m0, s90
	ds_read_b128 v[178:181], v141 offset:16384
	ds_read_b128 v[182:185], v141 offset:17408
	ds_read_b128 v[186:189], v141 offset:18432
	ds_read_b128 v[190:193], v141 offset:19456
	ds_read_b128 v[194:197], v141 offset:20480
	ds_read_b128 v[198:201], v141 offset:21504
	ds_read_b128 v[202:205], v141 offset:22528
	ds_read_b128 v[206:209], v141 offset:23552
	global_load_lds_dwordx4 v[174:175], off
	s_add_i32 m0, s90, 0x2000
	s_add_u32 s90, s26, 0x40000
	v_lshl_add_u64 v[210:211], s[26:27], 0, v[132:133]
	s_addc_u32 s91, s27, 0
	s_add_i32 s92, s92, s65
	global_load_lds_dwordx4 v[210:211], off
	v_lshl_add_u64 v[212:213], s[90:91], 0, v[176:177]
	s_mov_b32 m0, s92
	v_lshl_add_u64 v[214:215], s[28:29], 0, v[130:131]
	global_load_lds_dwordx4 v[212:213], off
	v_lshl_add_u64 v[212:213], s[90:91], 0, v[132:133]
	s_add_i32 m0, s92, 0x2000
	s_nop 0
	global_load_lds_dwordx4 v[212:213], off
	v_lshl_add_u64 v[212:213], s[28:29], 0, v[128:129]
	s_mov_b32 m0, s76
	s_nop 0
	global_load_lds_dwordx4 v[212:213], off
	s_mov_b32 m0, s77
	s_nop 0
	global_load_lds_dwordx4 v[214:215], off
	s_waitcnt vmcnt(8)
	s_waitcnt lgkmcnt(0)
	s_barrier
; #define PG8_STAGE(bufoff, gbase, voff) do { _Pragma("unroll") for (int _i = 0; _i < 2; ++_i) \
;         __builtin_amdgcn_global_load_lds((const unsigned*)((const char*)(gbase) + (voff)[_i]), (LAS unsigned*)(lds + (bufoff) + ldsw + _i * 8192), 16, 0, 0); } while (0)
; #define PG8_LDA(dst, b, h) do { _Pragma("unroll") for (int m = 0; m < 4; ++m) _Pragma("unroll") for (int k = 0; k < 2; ++k) dst[m][k] = *(const LAS bf16x8*)(lds + PG8_SA(b, h) + aoff + m * 2048 + k * 1024); } while (0)
; #define PG8_LDB(dst, b, h) do { _Pragma("unroll") for (int n = 0; n < 2; ++n) _Pragma("unroll") for (int k = 0; k < 2; ++k) dst[n][k] = *(const LAS bf16x8*)(lds + PG8_SB(b, h) + boff + n * 2048 + k * 1024); } while (0)
; #define PG8_MMA(ai, bj, At, Bt) do { __builtin_amdgcn_s_setprio(1); _Pragma("unroll") for (int m = 0; m < 4; ++m) _Pragma("unroll") for (int n = 0; n < 2; ++n) _Pragma("unroll") for (int k = 0; k < 2; ++k) \
;         acc[ai][bj][m][n] = __builtin_amdgcn_mfma_f32_16x16x32_bf16(Bt[n][k], At[m][k], acc[ai][bj][m][n], 0, 0, 0); __builtin_amdgcn_s_setprio(0); } while (0)
; #define PG8_WAIT_V(n) asm volatile("s_waitcnt vmcnt(" #n ")" ::: "memory")
; #define PG8_WAIT_L(n) asm volatile("s_waitcnt lgkmcnt(" #n ")" ::: "memory")
; #define PG8_BAR __builtin_amdgcn_s_barrier()
; #define PG8_SCHED __builtin_amdgcn_sched_barrier(0)
; template <class Epi>
; DI void gemm_phase(LAS unsigned char* lds, const Gemm g, const Order& S, const Epi& E) {
;     ...
;             PG8_WAIT_V(8); PG8_WAIT_L(0); PG8_BAR; PG8_MMA(1, 0, At, B0); PG8_MMA(1, 1, At, B1); PG8_BAR; PG8_SCHED;
;             PG8_LDB(B0, 1, 0); PG8_LDB(B1, 1, 1); PG8_SCHED; PG8_LDA(At, 1, 0); PG8_STAGE(PG8_SA(0, 1), a2 + hstepA, voffA);
;             PG8_WAIT_V(8); PG8_WAIT_L(0); PG8_BAR; PG8_MMA(0, 0, At, B0); PG8_MMA(0, 1, At, B1); PG8_BAR; PG8_SCHED;
	s_setprio 1
	v_mfma_f32_16x16x32_bf16 v[60:63], v[142:145], v[178:181], v[60:63]
	v_mfma_f32_16x16x32_bf16 v[56:59], v[150:153], v[178:181], v[56:59]
	v_mfma_f32_16x16x32_bf16 v[44:47], v[142:145], v[186:189], v[44:47]
	v_mfma_f32_16x16x32_bf16 v[40:43], v[150:153], v[186:189], v[40:43]
	v_mfma_f32_16x16x32_bf16 v[28:31], v[142:145], v[194:197], v[28:31]
	v_mfma_f32_16x16x32_bf16 v[24:27], v[150:153], v[194:197], v[24:27]
	v_mfma_f32_16x16x32_bf16 v[12:15], v[142:145], v[202:205], v[12:15]
	v_mfma_f32_16x16x32_bf16 v[8:11], v[150:153], v[202:205], v[8:11]
	v_mfma_f32_16x16x32_bf16 v[60:63], v[146:149], v[182:185], v[60:63]
	v_mfma_f32_16x16x32_bf16 v[56:59], v[154:157], v[182:185], v[56:59]
	v_mfma_f32_16x16x32_bf16 v[44:47], v[146:149], v[190:193], v[44:47]
	v_mfma_f32_16x16x32_bf16 v[40:43], v[154:157], v[190:193], v[40:43]
	v_mfma_f32_16x16x32_bf16 v[28:31], v[146:149], v[198:201], v[28:31]
	v_mfma_f32_16x16x32_bf16 v[24:27], v[154:157], v[198:201], v[24:27]
	v_mfma_f32_16x16x32_bf16 v[12:15], v[146:149], v[206:209], v[12:15]
	v_mfma_f32_16x16x32_bf16 v[8:11], v[154:157], v[206:209], v[8:11]
	s_setprio 0
	s_setprio 1
	v_mfma_f32_16x16x32_bf16 v[52:55], v[158:161], v[178:181], v[52:55]
	v_mfma_f32_16x16x32_bf16 v[48:51], v[166:169], v[178:181], v[48:51]
	v_mfma_f32_16x16x32_bf16 v[36:39], v[158:161], v[186:189], v[36:39]
	v_mfma_f32_16x16x32_bf16 v[32:35], v[166:169], v[186:189], v[32:35]
	v_mfma_f32_16x16x32_bf16 v[20:23], v[158:161], v[194:197], v[20:23]
	v_mfma_f32_16x16x32_bf16 v[16:19], v[166:169], v[194:197], v[16:19]
	v_mfma_f32_16x16x32_bf16 v[4:7], v[158:161], v[202:205], v[4:7]
	v_mfma_f32_16x16x32_bf16 v[0:3], v[166:169], v[202:205], v[0:3]
	v_mfma_f32_16x16x32_bf16 v[52:55], v[162:165], v[182:185], v[52:55]
	v_mfma_f32_16x16x32_bf16 v[48:51], v[170:173], v[182:185], v[48:51]
	v_mfma_f32_16x16x32_bf16 v[36:39], v[162:165], v[190:193], v[36:39]
	v_mfma_f32_16x16x32_bf16 v[32:35], v[170:173], v[190:193], v[32:35]
	v_mfma_f32_16x16x32_bf16 v[20:23], v[162:165], v[198:201], v[20:23]
	v_mfma_f32_16x16x32_bf16 v[16:19], v[170:173], v[198:201], v[16:19]
	v_mfma_f32_16x16x32_bf16 v[4:7], v[162:165], v[206:209], v[4:7]
	v_mfma_f32_16x16x32_bf16 v[0:3], v[170:173], v[206:209], v[0:3]
	s_setprio 0
	s_barrier
	s_add_i32 s90, 0, 0x18000
	s_add_i32 s91, 0, 0x1c000
	v_add_u32_e32 v154, s90, v140
	v_add_u32_e32 v170, s91, v140
	ds_read_b128 v[142:145], v154
	ds_read_b128 v[146:149], v154 offset:1024
	ds_read_b128 v[150:153], v154 offset:2048
	ds_read_b128 v[154:157], v154 offset:3072
	ds_read_b128 v[158:161], v170
	ds_read_b128 v[162:165], v170 offset:1024
	ds_read_b128 v[166:169], v170 offset:2048
	ds_read_b128 v[170:173], v170 offset:3072
	s_add_u32 s28, s28, 0x40000
	s_addc_u32 s29, s29, 0
	s_mov_b32 m0, s78
	v_lshl_add_u64 v[216:217], s[28:29], 0, v[128:129]
	ds_read_b128 v[178:181], v141 offset:32768
	ds_read_b128 v[182:185], v141 offset:33792
	ds_read_b128 v[186:189], v141 offset:34816
	ds_read_b128 v[190:193], v141 offset:35840
	ds_read_b128 v[194:197], v141 offset:36864
	ds_read_b128 v[198:201], v141 offset:37888
	ds_read_b128 v[202:205], v141 offset:38912
	ds_read_b128 v[206:209], v141 offset:39936
	global_load_lds_dwordx4 v[216:217], off
	v_lshl_add_u64 v[216:217], s[28:29], 0, v[130:131]
	s_mov_b32 m0, s79
	s_nop 0
	global_load_lds_dwordx4 v[216:217], off
	s_waitcnt vmcnt(8)
	s_waitcnt lgkmcnt(0)
	s_barrier
	s_setprio 1
	v_mfma_f32_16x16x32_bf16 v[120:123], v[142:145], v[178:181], v[120:123]
	v_mfma_f32_16x16x32_bf16 v[124:127], v[150:153], v[178:181], v[124:127]
	v_mfma_f32_16x16x32_bf16 v[108:111], v[142:145], v[186:189], v[108:111]
	v_mfma_f32_16x16x32_bf16 v[104:107], v[150:153], v[186:189], v[104:107]
	v_mfma_f32_16x16x32_bf16 v[92:95], v[142:145], v[194:197], v[92:95]
	v_mfma_f32_16x16x32_bf16 v[88:91], v[150:153], v[194:197], v[88:91]
	v_mfma_f32_16x16x32_bf16 v[76:79], v[142:145], v[202:205], v[76:79]
	v_mfma_f32_16x16x32_bf16 v[72:75], v[150:153], v[202:205], v[72:75]
	v_mfma_f32_16x16x32_bf16 v[120:123], v[146:149], v[182:185], v[120:123]
	v_mfma_f32_16x16x32_bf16 v[124:127], v[154:157], v[182:185], v[124:127]
	v_mfma_f32_16x16x32_bf16 v[108:111], v[146:149], v[190:193], v[108:111]
	v_mfma_f32_16x16x32_bf16 v[104:107], v[154:157], v[190:193], v[104:107]
	v_mfma_f32_16x16x32_bf16 v[92:95], v[146:149], v[198:201], v[92:95]
	v_mfma_f32_16x16x32_bf16 v[88:91], v[154:157], v[198:201], v[88:91]
	v_mfma_f32_16x16x32_bf16 v[76:79], v[146:149], v[206:209], v[76:79]
	v_mfma_f32_16x16x32_bf16 v[72:75], v[154:157], v[206:209], v[72:75]
	s_setprio 0
	s_setprio 1
	v_mfma_f32_16x16x32_bf16 v[116:119], v[158:161], v[178:181], v[116:119]
	v_mfma_f32_16x16x32_bf16 v[112:115], v[166:169], v[178:181], v[112:115]
	v_mfma_f32_16x16x32_bf16 v[100:103], v[158:161], v[186:189], v[100:103]
	v_mfma_f32_16x16x32_bf16 v[96:99], v[166:169], v[186:189], v[96:99]
	v_mfma_f32_16x16x32_bf16 v[84:87], v[158:161], v[194:197], v[84:87]
	v_mfma_f32_16x16x32_bf16 v[80:83], v[166:169], v[194:197], v[80:83]
	v_mfma_f32_16x16x32_bf16 v[68:71], v[158:161], v[202:205], v[68:71]
	v_mfma_f32_16x16x32_bf16 v[64:67], v[166:169], v[202:205], v[64:67]
	v_mfma_f32_16x16x32_bf16 v[116:119], v[162:165], v[182:185], v[116:119]
	v_mfma_f32_16x16x32_bf16 v[112:115], v[170:173], v[182:185], v[112:115]
	v_mfma_f32_16x16x32_bf16 v[100:103], v[162:165], v[190:193], v[100:103]
	v_mfma_f32_16x16x32_bf16 v[96:99], v[170:173], v[190:193], v[96:99]
	v_mfma_f32_16x16x32_bf16 v[84:87], v[162:165], v[198:201], v[84:87]
	v_mfma_f32_16x16x32_bf16 v[80:83], v[170:173], v[198:201], v[80:83]
	v_mfma_f32_16x16x32_bf16 v[68:71], v[162:165], v[206:209], v[68:71]
	v_mfma_f32_16x16x32_bf16 v[64:67], v[170:173], v[206:209], v[64:67]
	s_setprio 0
	s_barrier
; #define PG8_STAGE(bufoff, gbase, voff) do { _Pragma("unroll") for (int _i = 0; _i < 2; ++_i) \
;         __builtin_amdgcn_global_load_lds((const unsigned*)((const char*)(gbase) + (voff)[_i]), (LAS unsigned*)(lds + (bufoff) + ldsw + _i * 8192), 16, 0, 0); } while (0)
; #define PG8_LDA(dst, b, h) do { _Pragma("unroll") for (int m = 0; m < 4; ++m) _Pragma("unroll") for (int k = 0; k < 2; ++k) dst[m][k] = *(const LAS bf16x8*)(lds + PG8_SA(b, h) + aoff + m * 2048 + k * 1024); } while (0)
; #define PG8_MMA(ai, bj, At, Bt) do { __builtin_amdgcn_s_setprio(1); _Pragma("unroll") for (int m = 0; m < 4; ++m) _Pragma("unroll") for (int n = 0; n < 2; ++n) _Pragma("unroll") for (int k = 0; k < 2; ++k) \
;         acc[ai][bj][m][n] = __builtin_amdgcn_mfma_f32_16x16x32_bf16(Bt[n][k], At[m][k], acc[ai][bj][m][n], 0, 0, 0); __builtin_amdgcn_s_setprio(0); } while (0)
; #define PG8_WAIT_V(n) asm volatile("s_waitcnt vmcnt(" #n ")" ::: "memory")
; #define PG8_WAIT_L(n) asm volatile("s_waitcnt lgkmcnt(" #n ")" ::: "memory")
; #define PG8_BAR __builtin_amdgcn_s_barrier()
; #define PG8_SCHED __builtin_amdgcn_sched_barrier(0)
; template <class Epi>
; DI void gemm_phase(LAS unsigned char* lds, const Gemm g, const Order& S, const Epi& E) {
;     ...
;             PG8_LDA(At, 1, 1); PG8_STAGE(PG8_SB(1, 0), b3, voffB); PG8_STAGE(PG8_SB(1, 1), b3 + hstepB, voffB); PG8_STAGE(PG8_SA(1, 0), a3, voffA);
;             PG8_WAIT_V(8); PG8_WAIT_L(0); PG8_BAR; PG8_MMA(1, 0, At, B0); PG8_MMA(1, 1, At, B1); PG8_BAR; PG8_SCHED;
;         }
	s_add_i32 s28, s90, s65
	v_lshl_add_u64 v[174:175], v[174:175], 0, s[56:57]
	s_mov_b32 m0, s28
	ds_read_b128 v[178:181], v141 offset:49152
	ds_read_b128 v[182:185], v141 offset:50176
	ds_read_b128 v[186:189], v141 offset:51200
	ds_read_b128 v[190:193], v141 offset:52224
	ds_read_b128 v[194:197], v141 offset:53248
	ds_read_b128 v[198:201], v141 offset:54272
	ds_read_b128 v[202:205], v141 offset:55296
	ds_read_b128 v[206:209], v141 offset:56320
	global_load_lds_dwordx4 v[174:175], off
	s_add_i32 m0, s28, 0x2000
	s_add_u32 s26, s26, 0x40080
	v_lshl_add_u64 v[174:175], v[210:211], 0, s[56:57]
	s_addc_u32 s27, s27, 0
	s_add_i32 s28, s91, s65
	global_load_lds_dwordx4 v[174:175], off
	v_lshl_add_u64 v[174:175], s[26:27], 0, v[176:177]
	s_mov_b32 m0, s28
	s_nop 0
	global_load_lds_dwordx4 v[174:175], off
	v_lshl_add_u64 v[174:175], s[26:27], 0, v[132:133]
	s_add_i32 m0, s28, 0x2000
	s_nop 0
	global_load_lds_dwordx4 v[174:175], off
	v_lshl_add_u64 v[174:175], v[212:213], 0, s[56:57]
	s_mov_b32 m0, s83
	s_nop 0
	global_load_lds_dwordx4 v[174:175], off
	v_lshl_add_u64 v[174:175], v[214:215], 0, s[56:57]
	s_mov_b32 m0, s84
	s_nop 0
	global_load_lds_dwordx4 v[174:175], off
	s_waitcnt vmcnt(8)
	s_waitcnt lgkmcnt(0)
	s_barrier
	s_setprio 1
	v_mfma_f32_16x16x32_bf16 v[60:63], v[142:145], v[178:181], v[60:63]
	v_mfma_f32_16x16x32_bf16 v[56:59], v[150:153], v[178:181], v[56:59]
	v_mfma_f32_16x16x32_bf16 v[44:47], v[142:145], v[186:189], v[44:47]
	v_mfma_f32_16x16x32_bf16 v[40:43], v[150:153], v[186:189], v[40:43]
	v_mfma_f32_16x16x32_bf16 v[28:31], v[142:145], v[194:197], v[28:31]
	v_mfma_f32_16x16x32_bf16 v[24:27], v[150:153], v[194:197], v[24:27]
	v_mfma_f32_16x16x32_bf16 v[12:15], v[142:145], v[202:205], v[12:15]
	v_mfma_f32_16x16x32_bf16 v[8:11], v[150:153], v[202:205], v[8:11]
	v_mfma_f32_16x16x32_bf16 v[60:63], v[146:149], v[182:185], v[60:63]
	v_mfma_f32_16x16x32_bf16 v[56:59], v[154:157], v[182:185], v[56:59]
	v_mfma_f32_16x16x32_bf16 v[44:47], v[146:149], v[190:193], v[44:47]
	v_mfma_f32_16x16x32_bf16 v[40:43], v[154:157], v[190:193], v[40:43]
	v_mfma_f32_16x16x32_bf16 v[28:31], v[146:149], v[198:201], v[28:31]
	v_mfma_f32_16x16x32_bf16 v[24:27], v[154:157], v[198:201], v[24:27]
	v_mfma_f32_16x16x32_bf16 v[12:15], v[146:149], v[206:209], v[12:15]
	v_mfma_f32_16x16x32_bf16 v[8:11], v[154:157], v[206:209], v[8:11]
	s_setprio 0
	s_setprio 1
	v_mfma_f32_16x16x32_bf16 v[52:55], v[158:161], v[178:181], v[52:55]
	v_mfma_f32_16x16x32_bf16 v[48:51], v[166:169], v[178:181], v[48:51]
	v_mfma_f32_16x16x32_bf16 v[36:39], v[158:161], v[186:189], v[36:39]
	v_mfma_f32_16x16x32_bf16 v[32:35], v[166:169], v[186:189], v[32:35]
	v_mfma_f32_16x16x32_bf16 v[20:23], v[158:161], v[194:197], v[20:23]
	v_mfma_f32_16x16x32_bf16 v[16:19], v[166:169], v[194:197], v[16:19]
	v_mfma_f32_16x16x32_bf16 v[4:7], v[158:161], v[202:205], v[4:7]
	v_mfma_f32_16x16x32_bf16 v[0:3], v[166:169], v[202:205], v[0:3]
	v_mfma_f32_16x16x32_bf16 v[52:55], v[162:165], v[182:185], v[52:55]
	v_mfma_f32_16x16x32_bf16 v[48:51], v[170:173], v[182:185], v[48:51]
	v_mfma_f32_16x16x32_bf16 v[36:39], v[162:165], v[190:193], v[36:39]
	v_mfma_f32_16x16x32_bf16 v[32:35], v[170:173], v[190:193], v[32:35]
	v_mfma_f32_16x16x32_bf16 v[20:23], v[162:165], v[198:201], v[20:23]
	v_mfma_f32_16x16x32_bf16 v[16:19], v[170:173], v[198:201], v[16:19]
	v_mfma_f32_16x16x32_bf16 v[4:7], v[162:165], v[206:209], v[4:7]
	v_mfma_f32_16x16x32_bf16 v[0:3], v[170:173], v[206:209], v[0:3]
	s_setprio 0
	s_barrier
	s_add_u32 s17, s17, 0x100
	s_addc_u32 s19, s19, 0
	s_add_u32 s24, s24, 0x100
	s_addc_u32 s25, s25, 0
	s_cmp_ge_i32 s89, s80
	s_mov_b32 s26, s89
	s_cbranch_scc0 .LBB0_670

; #define PG8_STAGE(bufoff, gbase, voff) do { _Pragma("unroll") for (int _i = 0; _i < 2; ++_i) \
;         __builtin_amdgcn_global_load_lds((const unsigned*)((const char*)(gbase) + (voff)[_i]), (LAS unsigned*)(lds + (bufoff) + ldsw + _i * 8192), 16, 0, 0); } while (0)
; #define PG8_LDA(dst, b, h) do { _Pragma("unroll") for (int m = 0; m < 4; ++m) _Pragma("unroll") for (int k = 0; k < 2; ++k) dst[m][k] = *(const LAS bf16x8*)(lds + PG8_SA(b, h) + aoff + m * 2048 + k * 1024); } while (0)
; #define PG8_LDB(dst, b, h) do { _Pragma("unroll") for (int n = 0; n < 2; ++n) _Pragma("unroll") for (int k = 0; k < 2; ++k) dst[n][k] = *(const LAS bf16x8*)(lds + PG8_SB(b, h) + boff + n * 2048 + k * 1024); } while (0)
; #define PG8_MMA(ai, bj, At, Bt) do { __builtin_amdgcn_s_setprio(1); _Pragma("unroll") for (int m = 0; m < 4; ++m) _Pragma("unroll") for (int n = 0; n < 2; ++n) _Pragma("unroll") for (int k = 0; k < 2; ++k) \
;         acc[ai][bj][m][n] = __builtin_amdgcn_mfma_f32_16x16x32_bf16(Bt[n][k], At[m][k], acc[ai][bj][m][n], 0, 0, 0); __builtin_amdgcn_s_setprio(0); } while (0)
; #define PG8_WAIT_V(n) asm volatile("s_waitcnt vmcnt(" #n ")" ::: "memory")
; #define PG8_WAIT_L(n) asm volatile("s_waitcnt lgkmcnt(" #n ")" ::: "memory")
; #define PG8_BAR __builtin_amdgcn_s_barrier()
; #define PG8_SCHED __builtin_amdgcn_sched_barrier(0)
; template <class Epi>
; DI void gemm_phase(LAS unsigned char* lds, const Gemm g, const Order& S, const Epi& E) {
;     ...
;         for (int t = 0; t < nt; t += 2) {
;             const bool last = (t == nt - 2);
;             const char* a1 = cA + (size_t)(t + 1) * kstep;
;             const char* a2 = last ? nA : cA + (size_t)(t + 2) * kstep; const char* b2 = last ? nB : cB + (size_t)(t + 2) * kstep;
;             const char* a3 = a2 + kstep; const char* b3 = b2 + kstep;
;             PG8_LDB(B0, 0, 0); PG8_LDB(B1, 0, 1); PG8_SCHED; PG8_LDA(At, 0, 0); PG8_STAGE(PG8_SA(1, 1), a1 + hstepA, voffA);
;             PG8_WAIT_V(8); PG8_WAIT_L(0); PG8_BAR; PG8_MMA(0, 0, At, B0); PG8_MMA(0, 1, At, B1); PG8_BAR; PG8_SCHED;
;             PG8_LDA(At, 0, 1); PG8_STAGE(PG8_SB(0, 0), b2, voffB); PG8_STAGE(PG8_SB(0, 1), b2 + hstepB, voffB); PG8_STAGE(PG8_SA(0, 0), a2, voffA);
;             PG8_WAIT_V(8); PG8_WAIT_L(0); PG8_BAR; PG8_MMA(1, 0, At, B0); PG8_MMA(1, 1, At, B1); PG8_BAR; PG8_SCHED;
.LBB0_743:
	s_add_i32 s88, s28, 2
	s_add_u32 s29, s26, 0xfff80080
	s_addc_u32 s30, s27, -1
	s_add_i32 s89, 0, 0x10000
	s_cmp_eq_u32 s84, s28
	s_cselect_b32 s31, s23, s30
	s_cselect_b32 s30, s22, s29
	s_cselect_b32 s29, s25, s21
	s_cselect_b32 s28, s24, s19
	s_add_i32 s92, 0, 0x14000
	s_waitcnt vmcnt(0) lgkmcnt(0)
	v_add_u32_e32 v140, s89, v206
	v_add_u32_e32 v156, s92, v206
	ds_read_b128 v[128:131], v140
	ds_read_b128 v[132:135], v140 offset:1024
	ds_read_b128 v[136:139], v140 offset:2048
	ds_read_b128 v[140:143], v140 offset:3072
	ds_read_b128 v[144:147], v156
	ds_read_b128 v[148:151], v156 offset:1024
	ds_read_b128 v[152:155], v156 offset:2048
	ds_read_b128 v[156:159], v156 offset:3072
	v_lshl_add_u64 v[174:175], s[26:27], 0, v[172:173]
	s_add_i32 m0, s74, 0xc000
	ds_read_b128 v[160:163], v207
	ds_read_b128 v[178:181], v207 offset:1024
	ds_read_b128 v[182:185], v207 offset:2048
	ds_read_b128 v[186:189], v207 offset:3072
	ds_read_b128 v[190:193], v207 offset:4096
	ds_read_b128 v[194:197], v207 offset:5120
	ds_read_b128 v[198:201], v207 offset:6144
	ds_read_b128 v[208:211], v207 offset:7168
	global_load_lds_dwordx4 v[174:175], off
	v_lshl_add_u64 v[174:175], s[26:27], 0, v[170:171]
	s_add_i32 m0, s74, 0xe000
	s_nop 0
	global_load_lds_dwordx4 v[174:175], off
	s_waitcnt vmcnt(8)
	s_waitcnt lgkmcnt(0)
	s_barrier
	s_setprio 1
	v_mfma_f32_16x16x32_bf16 v[120:123], v[128:131], v[160:163], v[120:123]
	v_mfma_f32_16x16x32_bf16 v[124:127], v[136:139], v[160:163], v[124:127]
	v_mfma_f32_16x16x32_bf16 v[108:111], v[128:131], v[182:185], v[108:111]
	v_mfma_f32_16x16x32_bf16 v[104:107], v[136:139], v[182:185], v[104:107]
	v_mfma_f32_16x16x32_bf16 v[92:95], v[128:131], v[190:193], v[92:95]
	v_mfma_f32_16x16x32_bf16 v[88:91], v[136:139], v[190:193], v[88:91]
	v_mfma_f32_16x16x32_bf16 v[76:79], v[128:131], v[198:201], v[76:79]
	v_mfma_f32_16x16x32_bf16 v[72:75], v[136:139], v[198:201], v[72:75]
	v_mfma_f32_16x16x32_bf16 v[120:123], v[132:135], v[178:181], v[120:123]
	v_mfma_f32_16x16x32_bf16 v[124:127], v[140:143], v[178:181], v[124:127]
	v_mfma_f32_16x16x32_bf16 v[108:111], v[132:135], v[186:189], v[108:111]
	v_mfma_f32_16x16x32_bf16 v[104:107], v[140:143], v[186:189], v[104:107]
	v_mfma_f32_16x16x32_bf16 v[92:95], v[132:135], v[194:197], v[92:95]
	v_mfma_f32_16x16x32_bf16 v[88:91], v[140:143], v[194:197], v[88:91]
	v_mfma_f32_16x16x32_bf16 v[76:79], v[132:135], v[208:211], v[76:79]
	v_mfma_f32_16x16x32_bf16 v[72:75], v[140:143], v[208:211], v[72:75]
	s_setprio 0
	s_setprio 1
	v_mfma_f32_16x16x32_bf16 v[116:119], v[144:147], v[160:163], v[116:119]
	v_mfma_f32_16x16x32_bf16 v[112:115], v[152:155], v[160:163], v[112:115]
	v_mfma_f32_16x16x32_bf16 v[100:103], v[144:147], v[182:185], v[100:103]
	v_mfma_f32_16x16x32_bf16 v[96:99], v[152:155], v[182:185], v[96:99]
	v_mfma_f32_16x16x32_bf16 v[84:87], v[144:147], v[190:193], v[84:87]
	v_mfma_f32_16x16x32_bf16 v[80:83], v[152:155], v[190:193], v[80:83]
	v_mfma_f32_16x16x32_bf16 v[68:71], v[144:147], v[198:201], v[68:71]
	v_mfma_f32_16x16x32_bf16 v[64:67], v[152:155], v[198:201], v[64:67]
	v_mfma_f32_16x16x32_bf16 v[116:119], v[148:151], v[178:181], v[116:119]
	v_mfma_f32_16x16x32_bf16 v[112:115], v[156:159], v[178:181], v[112:115]
	v_mfma_f32_16x16x32_bf16 v[100:103], v[148:151], v[186:189], v[100:103]
	v_mfma_f32_16x16x32_bf16 v[96:99], v[156:159], v[186:189], v[96:99]
	v_mfma_f32_16x16x32_bf16 v[84:87], v[148:151], v[194:197], v[84:87]
	v_mfma_f32_16x16x32_bf16 v[80:83], v[156:159], v[194:197], v[80:83]
	v_mfma_f32_16x16x32_bf16 v[68:71], v[148:151], v[208:211], v[68:71]
	v_mfma_f32_16x16x32_bf16 v[64:67], v[156:159], v[208:211], v[64:67]
	s_setprio 0
	s_barrier
	s_add_i32 s89, s89, s37
	v_lshl_add_u64 v[174:175], s[28:29], 0, v[176:177]
	s_mov_b32 m0, s89
	ds_read_b128 v[160:163], v207 offset:16384
	ds_read_b128 v[178:181], v207 offset:17408
	ds_read_b128 v[182:185], v207 offset:18432
	ds_read_b128 v[186:189], v207 offset:19456
	ds_read_b128 v[190:193], v207 offset:20480
	ds_read_b128 v[194:197], v207 offset:21504
	ds_read_b128 v[198:201], v207 offset:22528
	ds_read_b128 v[208:211], v207 offset:23552
	global_load_lds_dwordx4 v[174:175], off
	s_add_i32 m0, s89, 0x2000
	s_add_u32 s90, s28, 0x80000
	v_lshl_add_u64 v[202:203], s[28:29], 0, v[164:165]
	s_addc_u32 s91, s29, 0
	s_add_i32 s89, s92, s37
	global_load_lds_dwordx4 v[202:203], off
	v_lshl_add_u64 v[212:213], s[90:91], 0, v[176:177]
	s_mov_b32 m0, s89
	v_lshl_add_u64 v[214:215], s[30:31], 0, v[166:167]
	global_load_lds_dwordx4 v[212:213], off
	v_lshl_add_u64 v[212:213], s[90:91], 0, v[164:165]
	s_add_i32 m0, s89, 0x2000
	s_nop 0
	global_load_lds_dwordx4 v[212:213], off
	v_lshl_add_u64 v[212:213], s[30:31], 0, v[168:169]
	s_mov_b32 m0, s74
	s_nop 0
	global_load_lds_dwordx4 v[212:213], off
	s_mov_b32 m0, s75
	s_nop 0
	global_load_lds_dwordx4 v[214:215], off
	s_waitcnt vmcnt(8)
	s_waitcnt lgkmcnt(0)
	s_barrier
; #define PG8_STAGE(bufoff, gbase, voff) do { _Pragma("unroll") for (int _i = 0; _i < 2; ++_i) \
;         __builtin_amdgcn_global_load_lds((const unsigned*)((const char*)(gbase) + (voff)[_i]), (LAS unsigned*)(lds + (bufoff) + ldsw + _i * 8192), 16, 0, 0); } while (0)
; #define PG8_LDA(dst, b, h) do { _Pragma("unroll") for (int m = 0; m < 4; ++m) _Pragma("unroll") for (int k = 0; k < 2; ++k) dst[m][k] = *(const LAS bf16x8*)(lds + PG8_SA(b, h) + aoff + m * 2048 + k * 1024); } while (0)
; #define PG8_LDB(dst, b, h) do { _Pragma("unroll") for (int n = 0; n < 2; ++n) _Pragma("unroll") for (int k = 0; k < 2; ++k) dst[n][k] = *(const LAS bf16x8*)(lds + PG8_SB(b, h) + boff + n * 2048 + k * 1024); } while (0)
; #define PG8_MMA(ai, bj, At, Bt) do { __builtin_amdgcn_s_setprio(1); _Pragma("unroll") for (int m = 0; m < 4; ++m) _Pragma("unroll") for (int n = 0; n < 2; ++n) _Pragma("unroll") for (int k = 0; k < 2; ++k) \
;         acc[ai][bj][m][n] = __builtin_amdgcn_mfma_f32_16x16x32_bf16(Bt[n][k], At[m][k], acc[ai][bj][m][n], 0, 0, 0); __builtin_amdgcn_s_setprio(0); } while (0)
; #define PG8_WAIT_V(n) asm volatile("s_waitcnt vmcnt(" #n ")" ::: "memory")
; #define PG8_WAIT_L(n) asm volatile("s_waitcnt lgkmcnt(" #n ")" ::: "memory")
; #define PG8_BAR __builtin_amdgcn_s_barrier()
; #define PG8_SCHED __builtin_amdgcn_sched_barrier(0)
; template <class Epi>
; DI void gemm_phase(LAS unsigned char* lds, const Gemm g, const Order& S, const Epi& E) {
;     ...
;             PG8_WAIT_V(8); PG8_WAIT_L(0); PG8_BAR; PG8_MMA(1, 0, At, B0); PG8_MMA(1, 1, At, B1); PG8_BAR; PG8_SCHED;
;             PG8_LDB(B0, 1, 0); PG8_LDB(B1, 1, 1); PG8_SCHED; PG8_LDA(At, 1, 0); PG8_STAGE(PG8_SA(0, 1), a2 + hstepA, voffA);
;             PG8_WAIT_V(8); PG8_WAIT_L(0); PG8_BAR; PG8_MMA(0, 0, At, B0); PG8_MMA(0, 1, At, B1); PG8_BAR; PG8_SCHED;
	s_setprio 1
	v_mfma_f32_16x16x32_bf16 v[60:63], v[128:131], v[160:163], v[60:63]
	v_mfma_f32_16x16x32_bf16 v[56:59], v[136:139], v[160:163], v[56:59]
	v_mfma_f32_16x16x32_bf16 v[44:47], v[128:131], v[182:185], v[44:47]
	v_mfma_f32_16x16x32_bf16 v[40:43], v[136:139], v[182:185], v[40:43]
	v_mfma_f32_16x16x32_bf16 v[28:31], v[128:131], v[190:193], v[28:31]
	v_mfma_f32_16x16x32_bf16 v[24:27], v[136:139], v[190:193], v[24:27]
	v_mfma_f32_16x16x32_bf16 v[12:15], v[128:131], v[198:201], v[12:15]
	v_mfma_f32_16x16x32_bf16 v[8:11], v[136:139], v[198:201], v[8:11]
	v_mfma_f32_16x16x32_bf16 v[60:63], v[132:135], v[178:181], v[60:63]
	v_mfma_f32_16x16x32_bf16 v[56:59], v[140:143], v[178:181], v[56:59]
	v_mfma_f32_16x16x32_bf16 v[44:47], v[132:135], v[186:189], v[44:47]
	v_mfma_f32_16x16x32_bf16 v[40:43], v[140:143], v[186:189], v[40:43]
	v_mfma_f32_16x16x32_bf16 v[28:31], v[132:135], v[194:197], v[28:31]
	v_mfma_f32_16x16x32_bf16 v[24:27], v[140:143], v[194:197], v[24:27]
	v_mfma_f32_16x16x32_bf16 v[12:15], v[132:135], v[208:211], v[12:15]
	v_mfma_f32_16x16x32_bf16 v[8:11], v[140:143], v[208:211], v[8:11]
	s_setprio 0
	s_setprio 1
	v_mfma_f32_16x16x32_bf16 v[52:55], v[144:147], v[160:163], v[52:55]
	v_mfma_f32_16x16x32_bf16 v[48:51], v[152:155], v[160:163], v[48:51]
	v_mfma_f32_16x16x32_bf16 v[36:39], v[144:147], v[182:185], v[36:39]
	v_mfma_f32_16x16x32_bf16 v[32:35], v[152:155], v[182:185], v[32:35]
	v_mfma_f32_16x16x32_bf16 v[20:23], v[144:147], v[190:193], v[20:23]
	v_mfma_f32_16x16x32_bf16 v[16:19], v[152:155], v[190:193], v[16:19]
	v_mfma_f32_16x16x32_bf16 v[4:7], v[144:147], v[198:201], v[4:7]
	v_mfma_f32_16x16x32_bf16 v[0:3], v[152:155], v[198:201], v[0:3]
	v_mfma_f32_16x16x32_bf16 v[52:55], v[148:151], v[178:181], v[52:55]
	v_mfma_f32_16x16x32_bf16 v[48:51], v[156:159], v[178:181], v[48:51]
	v_mfma_f32_16x16x32_bf16 v[36:39], v[148:151], v[186:189], v[36:39]
	v_mfma_f32_16x16x32_bf16 v[32:35], v[156:159], v[186:189], v[32:35]
	v_mfma_f32_16x16x32_bf16 v[20:23], v[148:151], v[194:197], v[20:23]
	v_mfma_f32_16x16x32_bf16 v[16:19], v[156:159], v[194:197], v[16:19]
	v_mfma_f32_16x16x32_bf16 v[4:7], v[148:151], v[208:211], v[4:7]
	v_mfma_f32_16x16x32_bf16 v[0:3], v[156:159], v[208:211], v[0:3]
	s_setprio 0
	s_barrier
	s_add_i32 s89, 0, 0x18000
	s_add_i32 s90, 0, 0x1c000
	v_add_u32_e32 v140, s89, v206
	v_add_u32_e32 v156, s90, v206
	ds_read_b128 v[128:131], v140
	ds_read_b128 v[132:135], v140 offset:1024
	ds_read_b128 v[136:139], v140 offset:2048
	ds_read_b128 v[140:143], v140 offset:3072
	ds_read_b128 v[144:147], v156
	ds_read_b128 v[148:151], v156 offset:1024
	ds_read_b128 v[152:155], v156 offset:2048
	ds_read_b128 v[156:159], v156 offset:3072
	s_add_u32 s30, s30, 0x80000
	s_addc_u32 s31, s31, 0
	s_mov_b32 m0, s76
	v_lshl_add_u64 v[216:217], s[30:31], 0, v[168:169]
	ds_read_b128 v[160:163], v207 offset:32768
	ds_read_b128 v[178:181], v207 offset:33792
	ds_read_b128 v[182:185], v207 offset:34816
	ds_read_b128 v[186:189], v207 offset:35840
	ds_read_b128 v[190:193], v207 offset:36864
	ds_read_b128 v[194:197], v207 offset:37888
	ds_read_b128 v[198:201], v207 offset:38912
	ds_read_b128 v[208:211], v207 offset:39936
	global_load_lds_dwordx4 v[216:217], off
	v_lshl_add_u64 v[216:217], s[30:31], 0, v[166:167]
	s_mov_b32 m0, s77
	s_nop 0
	global_load_lds_dwordx4 v[216:217], off
	s_waitcnt vmcnt(8)
	s_waitcnt lgkmcnt(0)
	s_barrier
	s_setprio 1
	v_mfma_f32_16x16x32_bf16 v[120:123], v[128:131], v[160:163], v[120:123]
	v_mfma_f32_16x16x32_bf16 v[124:127], v[136:139], v[160:163], v[124:127]
	v_mfma_f32_16x16x32_bf16 v[108:111], v[128:131], v[182:185], v[108:111]
	v_mfma_f32_16x16x32_bf16 v[104:107], v[136:139], v[182:185], v[104:107]
	v_mfma_f32_16x16x32_bf16 v[92:95], v[128:131], v[190:193], v[92:95]
	v_mfma_f32_16x16x32_bf16 v[88:91], v[136:139], v[190:193], v[88:91]
	v_mfma_f32_16x16x32_bf16 v[76:79], v[128:131], v[198:201], v[76:79]
	v_mfma_f32_16x16x32_bf16 v[72:75], v[136:139], v[198:201], v[72:75]
	v_mfma_f32_16x16x32_bf16 v[120:123], v[132:135], v[178:181], v[120:123]
	v_mfma_f32_16x16x32_bf16 v[124:127], v[140:143], v[178:181], v[124:127]
	v_mfma_f32_16x16x32_bf16 v[108:111], v[132:135], v[186:189], v[108:111]
	v_mfma_f32_16x16x32_bf16 v[104:107], v[140:143], v[186:189], v[104:107]
	v_mfma_f32_16x16x32_bf16 v[92:95], v[132:135], v[194:197], v[92:95]
	v_mfma_f32_16x16x32_bf16 v[88:91], v[140:143], v[194:197], v[88:91]
	v_mfma_f32_16x16x32_bf16 v[76:79], v[132:135], v[208:211], v[76:79]
	v_mfma_f32_16x16x32_bf16 v[72:75], v[140:143], v[208:211], v[72:75]
	s_setprio 0
	s_setprio 1
	v_mfma_f32_16x16x32_bf16 v[116:119], v[144:147], v[160:163], v[116:119]
	v_mfma_f32_16x16x32_bf16 v[112:115], v[152:155], v[160:163], v[112:115]
	v_mfma_f32_16x16x32_bf16 v[100:103], v[144:147], v[182:185], v[100:103]
	v_mfma_f32_16x16x32_bf16 v[96:99], v[152:155], v[182:185], v[96:99]
	v_mfma_f32_16x16x32_bf16 v[84:87], v[144:147], v[190:193], v[84:87]
	v_mfma_f32_16x16x32_bf16 v[80:83], v[152:155], v[190:193], v[80:83]
	v_mfma_f32_16x16x32_bf16 v[68:71], v[144:147], v[198:201], v[68:71]
	v_mfma_f32_16x16x32_bf16 v[64:67], v[152:155], v[198:201], v[64:67]
	v_mfma_f32_16x16x32_bf16 v[116:119], v[148:151], v[178:181], v[116:119]
	v_mfma_f32_16x16x32_bf16 v[112:115], v[156:159], v[178:181], v[112:115]
	v_mfma_f32_16x16x32_bf16 v[100:103], v[148:151], v[186:189], v[100:103]
	v_mfma_f32_16x16x32_bf16 v[96:99], v[156:159], v[186:189], v[96:99]
	v_mfma_f32_16x16x32_bf16 v[84:87], v[148:151], v[194:197], v[84:87]
	v_mfma_f32_16x16x32_bf16 v[80:83], v[156:159], v[194:197], v[80:83]
	v_mfma_f32_16x16x32_bf16 v[68:71], v[148:151], v[208:211], v[68:71]
	v_mfma_f32_16x16x32_bf16 v[64:67], v[156:159], v[208:211], v[64:67]
	s_setprio 0
	s_barrier
; #define PG8_STAGE(bufoff, gbase, voff) do { _Pragma("unroll") for (int _i = 0; _i < 2; ++_i) \
;         __builtin_amdgcn_global_load_lds((const unsigned*)((const char*)(gbase) + (voff)[_i]), (LAS unsigned*)(lds + (bufoff) + ldsw + _i * 8192), 16, 0, 0); } while (0)
; #define PG8_LDA(dst, b, h) do { _Pragma("unroll") for (int m = 0; m < 4; ++m) _Pragma("unroll") for (int k = 0; k < 2; ++k) dst[m][k] = *(const LAS bf16x8*)(lds + PG8_SA(b, h) + aoff + m * 2048 + k * 1024); } while (0)
; #define PG8_MMA(ai, bj, At, Bt) do { __builtin_amdgcn_s_setprio(1); _Pragma("unroll") for (int m = 0; m < 4; ++m) _Pragma("unroll") for (int n = 0; n < 2; ++n) _Pragma("unroll") for (int k = 0; k < 2; ++k) \
;         acc[ai][bj][m][n] = __builtin_amdgcn_mfma_f32_16x16x32_bf16(Bt[n][k], At[m][k], acc[ai][bj][m][n], 0, 0, 0); __builtin_amdgcn_s_setprio(0); } while (0)
; #define PG8_WAIT_V(n) asm volatile("s_waitcnt vmcnt(" #n ")" ::: "memory")
; #define PG8_WAIT_L(n) asm volatile("s_waitcnt lgkmcnt(" #n ")" ::: "memory")
; #define PG8_BAR __builtin_amdgcn_s_barrier()
; #define PG8_SCHED __builtin_amdgcn_sched_barrier(0)
; template <class Epi>
; DI void gemm_phase(LAS unsigned char* lds, const Gemm g, const Order& S, const Epi& E) {
;     ...
;             PG8_LDA(At, 1, 1); PG8_STAGE(PG8_SB(1, 0), b3, voffB); PG8_STAGE(PG8_SB(1, 1), b3 + hstepB, voffB); PG8_STAGE(PG8_SA(1, 0), a3, voffA);
;             PG8_WAIT_V(8); PG8_WAIT_L(0); PG8_BAR; PG8_MMA(1, 0, At, B0); PG8_MMA(1, 1, At, B1); PG8_BAR; PG8_SCHED;
;         }
	s_add_i32 s30, s89, s37
	v_lshl_add_u64 v[174:175], v[174:175], 0, s[56:57]
	s_mov_b32 m0, s30
	ds_read_b128 v[160:163], v207 offset:49152
	ds_read_b128 v[178:181], v207 offset:50176
	ds_read_b128 v[182:185], v207 offset:51200
	ds_read_b128 v[186:189], v207 offset:52224
	ds_read_b128 v[190:193], v207 offset:53248
	ds_read_b128 v[194:197], v207 offset:54272
	ds_read_b128 v[198:201], v207 offset:55296
	ds_read_b128 v[208:211], v207 offset:56320
	global_load_lds_dwordx4 v[174:175], off
	s_add_i32 m0, s30, 0x2000
	s_add_u32 s28, s28, 0x80080
	v_lshl_add_u64 v[174:175], v[202:203], 0, s[56:57]
	s_addc_u32 s29, s29, 0
	s_add_i32 s30, s90, s37
	global_load_lds_dwordx4 v[174:175], off
	v_lshl_add_u64 v[174:175], s[28:29], 0, v[176:177]
	s_mov_b32 m0, s30
	s_nop 0
	global_load_lds_dwordx4 v[174:175], off
	v_lshl_add_u64 v[174:175], s[28:29], 0, v[164:165]
	s_add_i32 m0, s30, 0x2000
	s_nop 0
	global_load_lds_dwordx4 v[174:175], off
	v_lshl_add_u64 v[174:175], v[212:213], 0, s[56:57]
	s_mov_b32 m0, s82
	s_nop 0
	global_load_lds_dwordx4 v[174:175], off
	v_lshl_add_u64 v[174:175], v[214:215], 0, s[56:57]
	s_mov_b32 m0, s83
	s_nop 0
	global_load_lds_dwordx4 v[174:175], off
	s_waitcnt vmcnt(8)
	s_waitcnt lgkmcnt(0)
	s_barrier
	s_setprio 1
	v_mfma_f32_16x16x32_bf16 v[60:63], v[128:131], v[160:163], v[60:63]
	v_mfma_f32_16x16x32_bf16 v[56:59], v[136:139], v[160:163], v[56:59]
	v_mfma_f32_16x16x32_bf16 v[44:47], v[128:131], v[182:185], v[44:47]
	v_mfma_f32_16x16x32_bf16 v[40:43], v[136:139], v[182:185], v[40:43]
	v_mfma_f32_16x16x32_bf16 v[28:31], v[128:131], v[190:193], v[28:31]
	v_mfma_f32_16x16x32_bf16 v[24:27], v[136:139], v[190:193], v[24:27]
	v_mfma_f32_16x16x32_bf16 v[12:15], v[128:131], v[198:201], v[12:15]
	v_mfma_f32_16x16x32_bf16 v[8:11], v[136:139], v[198:201], v[8:11]
	v_mfma_f32_16x16x32_bf16 v[60:63], v[132:135], v[178:181], v[60:63]
	v_mfma_f32_16x16x32_bf16 v[56:59], v[140:143], v[178:181], v[56:59]
	v_mfma_f32_16x16x32_bf16 v[44:47], v[132:135], v[186:189], v[44:47]
	v_mfma_f32_16x16x32_bf16 v[40:43], v[140:143], v[186:189], v[40:43]
	v_mfma_f32_16x16x32_bf16 v[28:31], v[132:135], v[194:197], v[28:31]
	v_mfma_f32_16x16x32_bf16 v[24:27], v[140:143], v[194:197], v[24:27]
	v_mfma_f32_16x16x32_bf16 v[12:15], v[132:135], v[208:211], v[12:15]
	v_mfma_f32_16x16x32_bf16 v[8:11], v[140:143], v[208:211], v[8:11]
	s_setprio 0
	s_setprio 1
	v_mfma_f32_16x16x32_bf16 v[52:55], v[144:147], v[160:163], v[52:55]
	v_mfma_f32_16x16x32_bf16 v[48:51], v[152:155], v[160:163], v[48:51]
	v_mfma_f32_16x16x32_bf16 v[36:39], v[144:147], v[182:185], v[36:39]
	v_mfma_f32_16x16x32_bf16 v[32:35], v[152:155], v[182:185], v[32:35]
	v_mfma_f32_16x16x32_bf16 v[20:23], v[144:147], v[190:193], v[20:23]
	v_mfma_f32_16x16x32_bf16 v[16:19], v[152:155], v[190:193], v[16:19]
	v_mfma_f32_16x16x32_bf16 v[4:7], v[144:147], v[198:201], v[4:7]
	v_mfma_f32_16x16x32_bf16 v[0:3], v[152:155], v[198:201], v[0:3]
	v_mfma_f32_16x16x32_bf16 v[52:55], v[148:151], v[178:181], v[52:55]
	v_mfma_f32_16x16x32_bf16 v[48:51], v[156:159], v[178:181], v[48:51]
	v_mfma_f32_16x16x32_bf16 v[36:39], v[148:151], v[186:189], v[36:39]
	v_mfma_f32_16x16x32_bf16 v[32:35], v[156:159], v[186:189], v[32:35]
	v_mfma_f32_16x16x32_bf16 v[20:23], v[148:151], v[194:197], v[20:23]
	v_mfma_f32_16x16x32_bf16 v[16:19], v[156:159], v[194:197], v[16:19]
	v_mfma_f32_16x16x32_bf16 v[4:7], v[148:151], v[208:211], v[4:7]
	v_mfma_f32_16x16x32_bf16 v[0:3], v[156:159], v[208:211], v[0:3]
	s_setprio 0
	s_barrier
	s_add_u32 s19, s19, 0x100
	s_addc_u32 s21, s21, 0
	s_add_u32 s26, s26, 0x100
	s_addc_u32 s27, s27, 0
	s_cmp_ge_i32 s88, s79
	s_mov_b32 s28, s88
	s_cbranch_scc0 .LBB0_743

; #define PG8_STAGE(bufoff, gbase, voff) do { _Pragma("unroll") for (int _i = 0; _i < 2; ++_i) \
;         __builtin_amdgcn_global_load_lds((const unsigned*)((const char*)(gbase) + (voff)[_i]), (LAS unsigned*)(lds + (bufoff) + ldsw + _i * 8192), 16, 0, 0); } while (0)
; #define PG8_LDA(dst, b, h) do { _Pragma("unroll") for (int m = 0; m < 4; ++m) _Pragma("unroll") for (int k = 0; k < 2; ++k) dst[m][k] = *(const LAS bf16x8*)(lds + PG8_SA(b, h) + aoff + m * 2048 + k * 1024); } while (0)
; #define PG8_LDB(dst, b, h) do { _Pragma("unroll") for (int n = 0; n < 2; ++n) _Pragma("unroll") for (int k = 0; k < 2; ++k) dst[n][k] = *(const LAS bf16x8*)(lds + PG8_SB(b, h) + boff + n * 2048 + k * 1024); } while (0)
; #define PG8_MMA(ai, bj, At, Bt) do { __builtin_amdgcn_s_setprio(1); _Pragma("unroll") for (int m = 0; m < 4; ++m) _Pragma("unroll") for (int n = 0; n < 2; ++n) _Pragma("unroll") for (int k = 0; k < 2; ++k) \
;         acc[ai][bj][m][n] = __builtin_amdgcn_mfma_f32_16x16x32_bf16(Bt[n][k], At[m][k], acc[ai][bj][m][n], 0, 0, 0); __builtin_amdgcn_s_setprio(0); } while (0)
; #define PG8_WAIT_V(n) asm volatile("s_waitcnt vmcnt(" #n ")" ::: "memory")
; #define PG8_WAIT_L(n) asm volatile("s_waitcnt lgkmcnt(" #n ")" ::: "memory")
; #define PG8_BAR __builtin_amdgcn_s_barrier()
; #define PG8_SCHED __builtin_amdgcn_sched_barrier(0)
; template <class Epi>
; DI void gemm_phase(LAS unsigned char* lds, const Gemm g, const Order& S, const Epi& E) {
;     ...
;         for (int t = 0; t < nt; t += 2) {
;             const bool last = (t == nt - 2);
;             const char* a1 = cA + (size_t)(t + 1) * kstep;
;             const char* a2 = last ? nA : cA + (size_t)(t + 2) * kstep; const char* b2 = last ? nB : cB + (size_t)(t + 2) * kstep;
;             const char* a3 = a2 + kstep; const char* b3 = b2 + kstep;
;             PG8_LDB(B0, 0, 0); PG8_LDB(B1, 0, 1); PG8_SCHED; PG8_LDA(At, 0, 0); PG8_STAGE(PG8_SA(1, 1), a1 + hstepA, voffA);
;             PG8_WAIT_V(8); PG8_WAIT_L(0); PG8_BAR; PG8_MMA(0, 0, At, B0); PG8_MMA(0, 1, At, B1); PG8_BAR; PG8_SCHED;
;             PG8_LDA(At, 0, 1); PG8_STAGE(PG8_SB(0, 0), b2, voffB); PG8_STAGE(PG8_SB(0, 1), b2 + hstepB, voffB); PG8_STAGE(PG8_SA(0, 0), a2, voffA);
;             PG8_WAIT_V(8); PG8_WAIT_L(0); PG8_BAR; PG8_MMA(1, 0, At, B0); PG8_MMA(1, 1, At, B1); PG8_BAR; PG8_SCHED;
.LBB0_773:
	s_add_i32 s87, s19, 2
	s_add_u32 s26, s24, 0xfff80080
	s_addc_u32 s27, s25, -1
	s_add_i32 s88, 0, 0x10000
	s_cmp_eq_u32 s82, s19
	s_cselect_b32 s29, s21, s27
	s_cselect_b32 s28, s20, s26
	s_cselect_b32 s27, s23, s17
	s_cselect_b32 s26, s22, s15
	s_add_i32 s19, 0, 0x14000
	v_add_u32_e32 v154, s88, v140
	v_add_u32_e32 v170, s19, v140
	ds_read_b128 v[142:145], v154
	ds_read_b128 v[146:149], v154 offset:1024
	ds_read_b128 v[150:153], v154 offset:2048
	ds_read_b128 v[154:157], v154 offset:3072
	ds_read_b128 v[158:161], v170
	ds_read_b128 v[162:165], v170 offset:1024
	ds_read_b128 v[166:169], v170 offset:2048
	ds_read_b128 v[170:173], v170 offset:3072
	v_lshl_add_u64 v[174:175], s[24:25], 0, v[136:137]
	s_add_i32 m0, s65, 0xc000
	ds_read_b128 v[178:181], v141
	ds_read_b128 v[182:185], v141 offset:1024
	ds_read_b128 v[186:189], v141 offset:2048
	ds_read_b128 v[190:193], v141 offset:3072
	ds_read_b128 v[194:197], v141 offset:4096
	ds_read_b128 v[198:201], v141 offset:5120
	ds_read_b128 v[202:205], v141 offset:6144
	ds_read_b128 v[206:209], v141 offset:7168
	global_load_lds_dwordx4 v[174:175], off
	v_lshl_add_u64 v[174:175], s[24:25], 0, v[134:135]
	s_add_i32 m0, s65, 0xe000
	s_nop 0
	global_load_lds_dwordx4 v[174:175], off
	s_waitcnt vmcnt(8)
	s_waitcnt lgkmcnt(0)
	s_barrier
	s_setprio 1
	v_mfma_f32_16x16x32_bf16 v[124:127], v[142:145], v[178:181], v[124:127]
	v_mfma_f32_16x16x32_bf16 v[120:123], v[150:153], v[178:181], v[120:123]
	v_mfma_f32_16x16x32_bf16 v[108:111], v[142:145], v[186:189], v[108:111]
	v_mfma_f32_16x16x32_bf16 v[104:107], v[150:153], v[186:189], v[104:107]
	v_mfma_f32_16x16x32_bf16 v[92:95], v[142:145], v[194:197], v[92:95]
	v_mfma_f32_16x16x32_bf16 v[88:91], v[150:153], v[194:197], v[88:91]
	v_mfma_f32_16x16x32_bf16 v[76:79], v[142:145], v[202:205], v[76:79]
	v_mfma_f32_16x16x32_bf16 v[72:75], v[150:153], v[202:205], v[72:75]
	v_mfma_f32_16x16x32_bf16 v[124:127], v[146:149], v[182:185], v[124:127]
	v_mfma_f32_16x16x32_bf16 v[120:123], v[154:157], v[182:185], v[120:123]
	v_mfma_f32_16x16x32_bf16 v[108:111], v[146:149], v[190:193], v[108:111]
	v_mfma_f32_16x16x32_bf16 v[104:107], v[154:157], v[190:193], v[104:107]
	v_mfma_f32_16x16x32_bf16 v[92:95], v[146:149], v[198:201], v[92:95]
	v_mfma_f32_16x16x32_bf16 v[88:91], v[154:157], v[198:201], v[88:91]
	v_mfma_f32_16x16x32_bf16 v[76:79], v[146:149], v[206:209], v[76:79]
	v_mfma_f32_16x16x32_bf16 v[72:75], v[154:157], v[206:209], v[72:75]
	s_setprio 0
	s_setprio 1
	v_mfma_f32_16x16x32_bf16 v[116:119], v[158:161], v[178:181], v[116:119]
	v_mfma_f32_16x16x32_bf16 v[112:115], v[166:169], v[178:181], v[112:115]
	v_mfma_f32_16x16x32_bf16 v[100:103], v[158:161], v[186:189], v[100:103]
	v_mfma_f32_16x16x32_bf16 v[96:99], v[166:169], v[186:189], v[96:99]
	v_mfma_f32_16x16x32_bf16 v[84:87], v[158:161], v[194:197], v[84:87]
	v_mfma_f32_16x16x32_bf16 v[80:83], v[166:169], v[194:197], v[80:83]
	v_mfma_f32_16x16x32_bf16 v[68:71], v[158:161], v[202:205], v[68:71]
	v_mfma_f32_16x16x32_bf16 v[64:67], v[166:169], v[202:205], v[64:67]
	v_mfma_f32_16x16x32_bf16 v[116:119], v[162:165], v[182:185], v[116:119]
	v_mfma_f32_16x16x32_bf16 v[112:115], v[170:173], v[182:185], v[112:115]
	v_mfma_f32_16x16x32_bf16 v[100:103], v[162:165], v[190:193], v[100:103]
	v_mfma_f32_16x16x32_bf16 v[96:99], v[170:173], v[190:193], v[96:99]
	v_mfma_f32_16x16x32_bf16 v[84:87], v[162:165], v[198:201], v[84:87]
	v_mfma_f32_16x16x32_bf16 v[80:83], v[170:173], v[198:201], v[80:83]
	v_mfma_f32_16x16x32_bf16 v[68:71], v[162:165], v[206:209], v[68:71]
	v_mfma_f32_16x16x32_bf16 v[64:67], v[170:173], v[206:209], v[64:67]
	s_setprio 0
	s_barrier
	s_add_i32 s88, s88, s63
	v_lshl_add_u64 v[174:175], s[26:27], 0, v[176:177]
	s_mov_b32 m0, s88
	ds_read_b128 v[178:181], v141 offset:16384
	ds_read_b128 v[182:185], v141 offset:17408
	ds_read_b128 v[186:189], v141 offset:18432
	ds_read_b128 v[190:193], v141 offset:19456
	ds_read_b128 v[194:197], v141 offset:20480
	ds_read_b128 v[198:201], v141 offset:21504
	ds_read_b128 v[202:205], v141 offset:22528
	ds_read_b128 v[206:209], v141 offset:23552
	global_load_lds_dwordx4 v[174:175], off
	s_add_i32 m0, s88, 0x2000
	s_add_u32 s88, s26, 0x80000
	v_lshl_add_u64 v[210:211], s[26:27], 0, v[128:129]
	s_addc_u32 s89, s27, 0
	s_add_i32 s19, s19, s63
	global_load_lds_dwordx4 v[210:211], off
	v_lshl_add_u64 v[212:213], s[88:89], 0, v[176:177]
	s_mov_b32 m0, s19
	v_lshl_add_u64 v[214:215], s[28:29], 0, v[130:131]
	global_load_lds_dwordx4 v[212:213], off
	v_lshl_add_u64 v[212:213], s[88:89], 0, v[128:129]
	s_add_i32 m0, s19, 0x2000
	s_nop 0
	global_load_lds_dwordx4 v[212:213], off
	v_lshl_add_u64 v[212:213], s[28:29], 0, v[132:133]
	s_mov_b32 m0, s65
	s_nop 0
	global_load_lds_dwordx4 v[212:213], off
	s_mov_b32 m0, s72
	s_nop 0
	global_load_lds_dwordx4 v[214:215], off
	s_waitcnt vmcnt(8)
	s_waitcnt lgkmcnt(0)
	s_barrier
; #define PG8_STAGE(bufoff, gbase, voff) do { _Pragma("unroll") for (int _i = 0; _i < 2; ++_i) \
;         __builtin_amdgcn_global_load_lds((const unsigned*)((const char*)(gbase) + (voff)[_i]), (LAS unsigned*)(lds + (bufoff) + ldsw + _i * 8192), 16, 0, 0); } while (0)
; #define PG8_LDA(dst, b, h) do { _Pragma("unroll") for (int m = 0; m < 4; ++m) _Pragma("unroll") for (int k = 0; k < 2; ++k) dst[m][k] = *(const LAS bf16x8*)(lds + PG8_SA(b, h) + aoff + m * 2048 + k * 1024); } while (0)
; #define PG8_LDB(dst, b, h) do { _Pragma("unroll") for (int n = 0; n < 2; ++n) _Pragma("unroll") for (int k = 0; k < 2; ++k) dst[n][k] = *(const LAS bf16x8*)(lds + PG8_SB(b, h) + boff + n * 2048 + k * 1024); } while (0)
; #define PG8_MMA(ai, bj, At, Bt) do { __builtin_amdgcn_s_setprio(1); _Pragma("unroll") for (int m = 0; m < 4; ++m) _Pragma("unroll") for (int n = 0; n < 2; ++n) _Pragma("unroll") for (int k = 0; k < 2; ++k) \
;         acc[ai][bj][m][n] = __builtin_amdgcn_mfma_f32_16x16x32_bf16(Bt[n][k], At[m][k], acc[ai][bj][m][n], 0, 0, 0); __builtin_amdgcn_s_setprio(0); } while (0)
; #define PG8_WAIT_V(n) asm volatile("s_waitcnt vmcnt(" #n ")" ::: "memory")
; #define PG8_WAIT_L(n) asm volatile("s_waitcnt lgkmcnt(" #n ")" ::: "memory")
; #define PG8_BAR __builtin_amdgcn_s_barrier()
; #define PG8_SCHED __builtin_amdgcn_sched_barrier(0)
; template <class Epi>
; DI void gemm_phase(LAS unsigned char* lds, const Gemm g, const Order& S, const Epi& E) {
;     ...
;             PG8_WAIT_V(8); PG8_WAIT_L(0); PG8_BAR; PG8_MMA(1, 0, At, B0); PG8_MMA(1, 1, At, B1); PG8_BAR; PG8_SCHED;
;             PG8_LDB(B0, 1, 0); PG8_LDB(B1, 1, 1); PG8_SCHED; PG8_LDA(At, 1, 0); PG8_STAGE(PG8_SA(0, 1), a2 + hstepA, voffA);
;             PG8_WAIT_V(8); PG8_WAIT_L(0); PG8_BAR; PG8_MMA(0, 0, At, B0); PG8_MMA(0, 1, At, B1); PG8_BAR; PG8_SCHED;
	s_setprio 1
	v_mfma_f32_16x16x32_bf16 v[60:63], v[142:145], v[178:181], v[60:63]
	v_mfma_f32_16x16x32_bf16 v[56:59], v[150:153], v[178:181], v[56:59]
	v_mfma_f32_16x16x32_bf16 v[44:47], v[142:145], v[186:189], v[44:47]
	v_mfma_f32_16x16x32_bf16 v[40:43], v[150:153], v[186:189], v[40:43]
	v_mfma_f32_16x16x32_bf16 v[28:31], v[142:145], v[194:197], v[28:31]
	v_mfma_f32_16x16x32_bf16 v[24:27], v[150:153], v[194:197], v[24:27]
	v_mfma_f32_16x16x32_bf16 v[12:15], v[142:145], v[202:205], v[12:15]
	v_mfma_f32_16x16x32_bf16 v[8:11], v[150:153], v[202:205], v[8:11]
	v_mfma_f32_16x16x32_bf16 v[60:63], v[146:149], v[182:185], v[60:63]
	v_mfma_f32_16x16x32_bf16 v[56:59], v[154:157], v[182:185], v[56:59]
	v_mfma_f32_16x16x32_bf16 v[44:47], v[146:149], v[190:193], v[44:47]
	v_mfma_f32_16x16x32_bf16 v[40:43], v[154:157], v[190:193], v[40:43]
	v_mfma_f32_16x16x32_bf16 v[28:31], v[146:149], v[198:201], v[28:31]
	v_mfma_f32_16x16x32_bf16 v[24:27], v[154:157], v[198:201], v[24:27]
	v_mfma_f32_16x16x32_bf16 v[12:15], v[146:149], v[206:209], v[12:15]
	v_mfma_f32_16x16x32_bf16 v[8:11], v[154:157], v[206:209], v[8:11]
	s_setprio 0
	s_setprio 1
	v_mfma_f32_16x16x32_bf16 v[52:55], v[158:161], v[178:181], v[52:55]
	v_mfma_f32_16x16x32_bf16 v[48:51], v[166:169], v[178:181], v[48:51]
	v_mfma_f32_16x16x32_bf16 v[36:39], v[158:161], v[186:189], v[36:39]
	v_mfma_f32_16x16x32_bf16 v[32:35], v[166:169], v[186:189], v[32:35]
	v_mfma_f32_16x16x32_bf16 v[20:23], v[158:161], v[194:197], v[20:23]
	v_mfma_f32_16x16x32_bf16 v[16:19], v[166:169], v[194:197], v[16:19]
	v_mfma_f32_16x16x32_bf16 v[4:7], v[158:161], v[202:205], v[4:7]
	v_mfma_f32_16x16x32_bf16 v[0:3], v[166:169], v[202:205], v[0:3]
	v_mfma_f32_16x16x32_bf16 v[52:55], v[162:165], v[182:185], v[52:55]
	v_mfma_f32_16x16x32_bf16 v[48:51], v[170:173], v[182:185], v[48:51]
	v_mfma_f32_16x16x32_bf16 v[36:39], v[162:165], v[190:193], v[36:39]
	v_mfma_f32_16x16x32_bf16 v[32:35], v[170:173], v[190:193], v[32:35]
	v_mfma_f32_16x16x32_bf16 v[20:23], v[162:165], v[198:201], v[20:23]
	v_mfma_f32_16x16x32_bf16 v[16:19], v[170:173], v[198:201], v[16:19]
	v_mfma_f32_16x16x32_bf16 v[4:7], v[162:165], v[206:209], v[4:7]
	v_mfma_f32_16x16x32_bf16 v[0:3], v[170:173], v[206:209], v[0:3]
	s_setprio 0
	s_barrier
	s_add_i32 s19, 0, 0x18000
	s_add_i32 s88, 0, 0x1c000
	v_add_u32_e32 v154, s19, v140
	v_add_u32_e32 v170, s88, v140
	ds_read_b128 v[142:145], v154
	ds_read_b128 v[146:149], v154 offset:1024
	ds_read_b128 v[150:153], v154 offset:2048
	ds_read_b128 v[154:157], v154 offset:3072
	ds_read_b128 v[158:161], v170
	ds_read_b128 v[162:165], v170 offset:1024
	ds_read_b128 v[166:169], v170 offset:2048
	ds_read_b128 v[170:173], v170 offset:3072
	s_add_u32 s28, s28, 0x80000
	s_addc_u32 s29, s29, 0
	s_mov_b32 m0, s73
	v_lshl_add_u64 v[216:217], s[28:29], 0, v[132:133]
	ds_read_b128 v[178:181], v141 offset:32768
	ds_read_b128 v[182:185], v141 offset:33792
	ds_read_b128 v[186:189], v141 offset:34816
	ds_read_b128 v[190:193], v141 offset:35840
	ds_read_b128 v[194:197], v141 offset:36864
	ds_read_b128 v[198:201], v141 offset:37888
	ds_read_b128 v[202:205], v141 offset:38912
	ds_read_b128 v[206:209], v141 offset:39936
	global_load_lds_dwordx4 v[216:217], off
	v_lshl_add_u64 v[216:217], s[28:29], 0, v[130:131]
	s_mov_b32 m0, s74
	s_nop 0
	global_load_lds_dwordx4 v[216:217], off
	s_waitcnt vmcnt(8)
	s_waitcnt lgkmcnt(0)
	s_barrier
	s_setprio 1
	v_mfma_f32_16x16x32_bf16 v[124:127], v[142:145], v[178:181], v[124:127]
	v_mfma_f32_16x16x32_bf16 v[120:123], v[150:153], v[178:181], v[120:123]
	v_mfma_f32_16x16x32_bf16 v[108:111], v[142:145], v[186:189], v[108:111]
	v_mfma_f32_16x16x32_bf16 v[104:107], v[150:153], v[186:189], v[104:107]
	v_mfma_f32_16x16x32_bf16 v[92:95], v[142:145], v[194:197], v[92:95]
	v_mfma_f32_16x16x32_bf16 v[88:91], v[150:153], v[194:197], v[88:91]
	v_mfma_f32_16x16x32_bf16 v[76:79], v[142:145], v[202:205], v[76:79]
	v_mfma_f32_16x16x32_bf16 v[72:75], v[150:153], v[202:205], v[72:75]
	v_mfma_f32_16x16x32_bf16 v[124:127], v[146:149], v[182:185], v[124:127]
	v_mfma_f32_16x16x32_bf16 v[120:123], v[154:157], v[182:185], v[120:123]
	v_mfma_f32_16x16x32_bf16 v[108:111], v[146:149], v[190:193], v[108:111]
	v_mfma_f32_16x16x32_bf16 v[104:107], v[154:157], v[190:193], v[104:107]
	v_mfma_f32_16x16x32_bf16 v[92:95], v[146:149], v[198:201], v[92:95]
	v_mfma_f32_16x16x32_bf16 v[88:91], v[154:157], v[198:201], v[88:91]
	v_mfma_f32_16x16x32_bf16 v[76:79], v[146:149], v[206:209], v[76:79]
	v_mfma_f32_16x16x32_bf16 v[72:75], v[154:157], v[206:209], v[72:75]
	s_setprio 0
	s_setprio 1
	v_mfma_f32_16x16x32_bf16 v[116:119], v[158:161], v[178:181], v[116:119]
	v_mfma_f32_16x16x32_bf16 v[112:115], v[166:169], v[178:181], v[112:115]
	v_mfma_f32_16x16x32_bf16 v[100:103], v[158:161], v[186:189], v[100:103]
	v_mfma_f32_16x16x32_bf16 v[96:99], v[166:169], v[186:189], v[96:99]
	v_mfma_f32_16x16x32_bf16 v[84:87], v[158:161], v[194:197], v[84:87]
	v_mfma_f32_16x16x32_bf16 v[80:83], v[166:169], v[194:197], v[80:83]
	v_mfma_f32_16x16x32_bf16 v[68:71], v[158:161], v[202:205], v[68:71]
	v_mfma_f32_16x16x32_bf16 v[64:67], v[166:169], v[202:205], v[64:67]
	v_mfma_f32_16x16x32_bf16 v[116:119], v[162:165], v[182:185], v[116:119]
	v_mfma_f32_16x16x32_bf16 v[112:115], v[170:173], v[182:185], v[112:115]
	v_mfma_f32_16x16x32_bf16 v[100:103], v[162:165], v[190:193], v[100:103]
	v_mfma_f32_16x16x32_bf16 v[96:99], v[170:173], v[190:193], v[96:99]
	v_mfma_f32_16x16x32_bf16 v[84:87], v[162:165], v[198:201], v[84:87]
	v_mfma_f32_16x16x32_bf16 v[80:83], v[170:173], v[198:201], v[80:83]
	v_mfma_f32_16x16x32_bf16 v[68:71], v[162:165], v[206:209], v[68:71]
	v_mfma_f32_16x16x32_bf16 v[64:67], v[170:173], v[206:209], v[64:67]
	s_setprio 0
	s_barrier
; #define PG8_STAGE(bufoff, gbase, voff) do { _Pragma("unroll") for (int _i = 0; _i < 2; ++_i) \
;         __builtin_amdgcn_global_load_lds((const unsigned*)((const char*)(gbase) + (voff)[_i]), (LAS unsigned*)(lds + (bufoff) + ldsw + _i * 8192), 16, 0, 0); } while (0)
; #define PG8_LDA(dst, b, h) do { _Pragma("unroll") for (int m = 0; m < 4; ++m) _Pragma("unroll") for (int k = 0; k < 2; ++k) dst[m][k] = *(const LAS bf16x8*)(lds + PG8_SA(b, h) + aoff + m * 2048 + k * 1024); } while (0)
; #define PG8_MMA(ai, bj, At, Bt) do { __builtin_amdgcn_s_setprio(1); _Pragma("unroll") for (int m = 0; m < 4; ++m) _Pragma("unroll") for (int n = 0; n < 2; ++n) _Pragma("unroll") for (int k = 0; k < 2; ++k) \
;         acc[ai][bj][m][n] = __builtin_amdgcn_mfma_f32_16x16x32_bf16(Bt[n][k], At[m][k], acc[ai][bj][m][n], 0, 0, 0); __builtin_amdgcn_s_setprio(0); } while (0)
; #define PG8_WAIT_V(n) asm volatile("s_waitcnt vmcnt(" #n ")" ::: "memory")
; #define PG8_WAIT_L(n) asm volatile("s_waitcnt lgkmcnt(" #n ")" ::: "memory")
; #define PG8_BAR __builtin_amdgcn_s_barrier()
; #define PG8_SCHED __builtin_amdgcn_sched_barrier(0)
; template <class Epi>
; DI void gemm_phase(LAS unsigned char* lds, const Gemm g, const Order& S, const Epi& E) {
;     ...
;             PG8_LDA(At, 1, 1); PG8_STAGE(PG8_SB(1, 0), b3, voffB); PG8_STAGE(PG8_SB(1, 1), b3 + hstepB, voffB); PG8_STAGE(PG8_SA(1, 0), a3, voffA);
;             PG8_WAIT_V(8); PG8_WAIT_L(0); PG8_BAR; PG8_MMA(1, 0, At, B0); PG8_MMA(1, 1, At, B1); PG8_BAR; PG8_SCHED;
;         }
	s_add_i32 s19, s19, s63
	v_lshl_add_u64 v[174:175], v[174:175], 0, s[56:57]
	s_mov_b32 m0, s19
	ds_read_b128 v[178:181], v141 offset:49152
	ds_read_b128 v[182:185], v141 offset:50176
	ds_read_b128 v[186:189], v141 offset:51200
	ds_read_b128 v[190:193], v141 offset:52224
	ds_read_b128 v[194:197], v141 offset:53248
	ds_read_b128 v[198:201], v141 offset:54272
	ds_read_b128 v[202:205], v141 offset:55296
	ds_read_b128 v[206:209], v141 offset:56320
	global_load_lds_dwordx4 v[174:175], off
	s_add_i32 m0, s19, 0x2000
	s_add_u32 s26, s26, 0x80080
	v_lshl_add_u64 v[174:175], v[210:211], 0, s[56:57]
	s_addc_u32 s27, s27, 0
	s_add_i32 s19, s88, s63
	global_load_lds_dwordx4 v[174:175], off
	v_lshl_add_u64 v[174:175], s[26:27], 0, v[176:177]
	s_mov_b32 m0, s19
	s_nop 0
	global_load_lds_dwordx4 v[174:175], off
	v_lshl_add_u64 v[174:175], s[26:27], 0, v[128:129]
	s_add_i32 m0, s19, 0x2000
	s_nop 0
	global_load_lds_dwordx4 v[174:175], off
	v_lshl_add_u64 v[174:175], v[212:213], 0, s[56:57]
	s_mov_b32 m0, s80
	s_nop 0
	global_load_lds_dwordx4 v[174:175], off
	v_lshl_add_u64 v[174:175], v[214:215], 0, s[56:57]
	s_mov_b32 m0, s81
	s_nop 0
	global_load_lds_dwordx4 v[174:175], off
	s_waitcnt vmcnt(8)
	s_waitcnt lgkmcnt(0)
	s_barrier
	s_setprio 1
	v_mfma_f32_16x16x32_bf16 v[60:63], v[142:145], v[178:181], v[60:63]
	v_mfma_f32_16x16x32_bf16 v[56:59], v[150:153], v[178:181], v[56:59]
	v_mfma_f32_16x16x32_bf16 v[44:47], v[142:145], v[186:189], v[44:47]
	v_mfma_f32_16x16x32_bf16 v[40:43], v[150:153], v[186:189], v[40:43]
	v_mfma_f32_16x16x32_bf16 v[28:31], v[142:145], v[194:197], v[28:31]
	v_mfma_f32_16x16x32_bf16 v[24:27], v[150:153], v[194:197], v[24:27]
	v_mfma_f32_16x16x32_bf16 v[12:15], v[142:145], v[202:205], v[12:15]
	v_mfma_f32_16x16x32_bf16 v[8:11], v[150:153], v[202:205], v[8:11]
	v_mfma_f32_16x16x32_bf16 v[60:63], v[146:149], v[182:185], v[60:63]
	v_mfma_f32_16x16x32_bf16 v[56:59], v[154:157], v[182:185], v[56:59]
	v_mfma_f32_16x16x32_bf16 v[44:47], v[146:149], v[190:193], v[44:47]
	v_mfma_f32_16x16x32_bf16 v[40:43], v[154:157], v[190:193], v[40:43]
	v_mfma_f32_16x16x32_bf16 v[28:31], v[146:149], v[198:201], v[28:31]
	v_mfma_f32_16x16x32_bf16 v[24:27], v[154:157], v[198:201], v[24:27]
	v_mfma_f32_16x16x32_bf16 v[12:15], v[146:149], v[206:209], v[12:15]
	v_mfma_f32_16x16x32_bf16 v[8:11], v[154:157], v[206:209], v[8:11]
	s_setprio 0
	s_setprio 1
	v_mfma_f32_16x16x32_bf16 v[52:55], v[158:161], v[178:181], v[52:55]
	v_mfma_f32_16x16x32_bf16 v[48:51], v[166:169], v[178:181], v[48:51]
	v_mfma_f32_16x16x32_bf16 v[36:39], v[158:161], v[186:189], v[36:39]
	v_mfma_f32_16x16x32_bf16 v[32:35], v[166:169], v[186:189], v[32:35]
	v_mfma_f32_16x16x32_bf16 v[20:23], v[158:161], v[194:197], v[20:23]
	v_mfma_f32_16x16x32_bf16 v[16:19], v[166:169], v[194:197], v[16:19]
	v_mfma_f32_16x16x32_bf16 v[4:7], v[158:161], v[202:205], v[4:7]
	v_mfma_f32_16x16x32_bf16 v[0:3], v[166:169], v[202:205], v[0:3]
	v_mfma_f32_16x16x32_bf16 v[52:55], v[162:165], v[182:185], v[52:55]
	v_mfma_f32_16x16x32_bf16 v[48:51], v[170:173], v[182:185], v[48:51]
	v_mfma_f32_16x16x32_bf16 v[36:39], v[162:165], v[190:193], v[36:39]
	v_mfma_f32_16x16x32_bf16 v[32:35], v[170:173], v[190:193], v[32:35]
	v_mfma_f32_16x16x32_bf16 v[20:23], v[162:165], v[198:201], v[20:23]
	v_mfma_f32_16x16x32_bf16 v[16:19], v[170:173], v[198:201], v[16:19]
	v_mfma_f32_16x16x32_bf16 v[4:7], v[162:165], v[206:209], v[4:7]
	v_mfma_f32_16x16x32_bf16 v[0:3], v[170:173], v[206:209], v[0:3]
	s_setprio 0
	s_barrier
	s_add_u32 s15, s15, 0x100
	s_addc_u32 s17, s17, 0
	s_add_u32 s24, s24, 0x100
	s_addc_u32 s25, s25, 0
	s_cmp_ge_i32 s87, s77
	s_mov_b32 s19, s87
	s_cbranch_scc0 .LBB0_773

; #define PG8_STAGE(bufoff, gbase, voff) do { _Pragma("unroll") for (int _i = 0; _i < 2; ++_i) \
;         __builtin_amdgcn_global_load_lds((const unsigned*)((const char*)(gbase) + (voff)[_i]), (LAS unsigned*)(lds + (bufoff) + ldsw + _i * 8192), 16, 0, 0); } while (0)
; #define PG8_LDA(dst, b, h) do { _Pragma("unroll") for (int m = 0; m < 4; ++m) _Pragma("unroll") for (int k = 0; k < 2; ++k) dst[m][k] = *(const LAS bf16x8*)(lds + PG8_SA(b, h) + aoff + m * 2048 + k * 1024); } while (0)
; #define PG8_LDB(dst, b, h) do { _Pragma("unroll") for (int n = 0; n < 2; ++n) _Pragma("unroll") for (int k = 0; k < 2; ++k) dst[n][k] = *(const LAS bf16x8*)(lds + PG8_SB(b, h) + boff + n * 2048 + k * 1024); } while (0)
; #define PG8_MMA(ai, bj, At, Bt) do { __builtin_amdgcn_s_setprio(1); _Pragma("unroll") for (int m = 0; m < 4; ++m) _Pragma("unroll") for (int n = 0; n < 2; ++n) _Pragma("unroll") for (int k = 0; k < 2; ++k) \
;         acc[ai][bj][m][n] = __builtin_amdgcn_mfma_f32_16x16x32_bf16(Bt[n][k], At[m][k], acc[ai][bj][m][n], 0, 0, 0); __builtin_amdgcn_s_setprio(0); } while (0)
; #define PG8_WAIT_V(n) asm volatile("s_waitcnt vmcnt(" #n ")" ::: "memory")
; #define PG8_WAIT_L(n) asm volatile("s_waitcnt lgkmcnt(" #n ")" ::: "memory")
; #define PG8_BAR __builtin_amdgcn_s_barrier()
; #define PG8_SCHED __builtin_amdgcn_sched_barrier(0)
; template <class Epi>
; DI void gemm_phase(LAS unsigned char* lds, const Gemm g, const Order& S, const Epi& E) {
;     ...
;         for (int t = 0; t < nt; t += 2) {
;             const bool last = (t == nt - 2);
;             const char* a1 = cA + (size_t)(t + 1) * kstep;
;             const char* a2 = last ? nA : cA + (size_t)(t + 2) * kstep; const char* b2 = last ? nB : cB + (size_t)(t + 2) * kstep;
;             const char* a3 = a2 + kstep; const char* b3 = b2 + kstep;
;             PG8_LDB(B0, 0, 0); PG8_LDB(B1, 0, 1); PG8_SCHED; PG8_LDA(At, 0, 0); PG8_STAGE(PG8_SA(1, 1), a1 + hstepA, voffA);
;             PG8_WAIT_V(8); PG8_WAIT_L(0); PG8_BAR; PG8_MMA(0, 0, At, B0); PG8_MMA(0, 1, At, B1); PG8_BAR; PG8_SCHED;
;             PG8_LDA(At, 0, 1); PG8_STAGE(PG8_SB(0, 0), b2, voffB); PG8_STAGE(PG8_SB(0, 1), b2 + hstepB, voffB); PG8_STAGE(PG8_SA(0, 0), a2, voffA);
;             PG8_WAIT_V(8); PG8_WAIT_L(0); PG8_BAR; PG8_MMA(1, 0, At, B0); PG8_MMA(1, 1, At, B1); PG8_BAR; PG8_SCHED;
.LBB0_923:
	s_add_i32 s92, s26, 2
	s_add_u32 s27, s24, 0xfff80080
	s_addc_u32 s28, s25, -1
	s_add_i32 s93, 0, 0x10000
	s_cmp_eq_u32 s84, s26
	s_cselect_b32 s29, s17, s28
	s_cselect_b32 s28, s19, s27
	v_add_u32_e32 v138, s93, v142
	s_cselect_b32 s27, s88, s91
	s_cselect_b32 s26, s89, s90
	s_add_i32 s96, 0, 0x14000
	ds_read_b128 v[144:147], v138
	ds_read_b128 v[148:151], v138 offset:1024
	ds_read_b128 v[152:155], v138 offset:2048
	ds_read_b128 v[156:159], v138 offset:3072
	v_add_u32_e32 v138, s96, v142
	ds_read_b128 v[160:163], v138
	ds_read_b128 v[164:167], v138 offset:1024
	ds_read_b128 v[168:171], v138 offset:2048
	ds_read_b128 v[172:175], v138 offset:3072
	v_lshl_add_u64 v[138:139], s[24:25], 0, v[136:137]
	s_add_i32 m0, s75, 0xc000
	ds_read_b128 v[178:181], v143
	ds_read_b128 v[182:185], v143 offset:1024
	ds_read_b128 v[186:189], v143 offset:2048
	ds_read_b128 v[190:193], v143 offset:3072
	ds_read_b128 v[194:197], v143 offset:4096
	ds_read_b128 v[198:201], v143 offset:5120
	ds_read_b128 v[202:205], v143 offset:6144
	ds_read_b128 v[206:209], v143 offset:7168
	global_load_lds_dwordx4 v[138:139], off
	v_lshl_add_u64 v[138:139], s[24:25], 0, v[134:135]
	s_add_i32 m0, s75, 0xe000
	s_nop 0
	global_load_lds_dwordx4 v[138:139], off
	s_waitcnt vmcnt(8)
	s_waitcnt lgkmcnt(0)
	s_barrier
	s_setprio 1
	v_mfma_f32_16x16x32_bf16 v[120:123], v[144:147], v[178:181], v[120:123]
	v_mfma_f32_16x16x32_bf16 v[124:127], v[152:155], v[178:181], v[124:127]
	v_mfma_f32_16x16x32_bf16 v[108:111], v[144:147], v[186:189], v[108:111]
	v_mfma_f32_16x16x32_bf16 v[104:107], v[152:155], v[186:189], v[104:107]
	v_mfma_f32_16x16x32_bf16 v[92:95], v[144:147], v[194:197], v[92:95]
	v_mfma_f32_16x16x32_bf16 v[88:91], v[152:155], v[194:197], v[88:91]
	v_mfma_f32_16x16x32_bf16 v[76:79], v[144:147], v[202:205], v[76:79]
	v_mfma_f32_16x16x32_bf16 v[72:75], v[152:155], v[202:205], v[72:75]
	v_mfma_f32_16x16x32_bf16 v[120:123], v[148:151], v[182:185], v[120:123]
	v_mfma_f32_16x16x32_bf16 v[124:127], v[156:159], v[182:185], v[124:127]
	v_mfma_f32_16x16x32_bf16 v[108:111], v[148:151], v[190:193], v[108:111]
	v_mfma_f32_16x16x32_bf16 v[104:107], v[156:159], v[190:193], v[104:107]
	v_mfma_f32_16x16x32_bf16 v[92:95], v[148:151], v[198:201], v[92:95]
	v_mfma_f32_16x16x32_bf16 v[88:91], v[156:159], v[198:201], v[88:91]
	v_mfma_f32_16x16x32_bf16 v[76:79], v[148:151], v[206:209], v[76:79]
	v_mfma_f32_16x16x32_bf16 v[72:75], v[156:159], v[206:209], v[72:75]
	s_setprio 0
	s_setprio 1
	v_mfma_f32_16x16x32_bf16 v[116:119], v[160:163], v[178:181], v[116:119]
	v_mfma_f32_16x16x32_bf16 v[112:115], v[168:171], v[178:181], v[112:115]
	v_mfma_f32_16x16x32_bf16 v[100:103], v[160:163], v[186:189], v[100:103]
	v_mfma_f32_16x16x32_bf16 v[96:99], v[168:171], v[186:189], v[96:99]
	v_mfma_f32_16x16x32_bf16 v[84:87], v[160:163], v[194:197], v[84:87]
	v_mfma_f32_16x16x32_bf16 v[80:83], v[168:171], v[194:197], v[80:83]
	v_mfma_f32_16x16x32_bf16 v[68:71], v[160:163], v[202:205], v[68:71]
	v_mfma_f32_16x16x32_bf16 v[64:67], v[168:171], v[202:205], v[64:67]
	v_mfma_f32_16x16x32_bf16 v[116:119], v[164:167], v[182:185], v[116:119]
	v_mfma_f32_16x16x32_bf16 v[112:115], v[172:175], v[182:185], v[112:115]
	v_mfma_f32_16x16x32_bf16 v[100:103], v[164:167], v[190:193], v[100:103]
	v_mfma_f32_16x16x32_bf16 v[96:99], v[172:175], v[190:193], v[96:99]
	v_mfma_f32_16x16x32_bf16 v[84:87], v[164:167], v[198:201], v[84:87]
	v_mfma_f32_16x16x32_bf16 v[80:83], v[172:175], v[198:201], v[80:83]
	v_mfma_f32_16x16x32_bf16 v[68:71], v[164:167], v[206:209], v[68:71]
	v_mfma_f32_16x16x32_bf16 v[64:67], v[172:175], v[206:209], v[64:67]
	s_setprio 0
	s_barrier
	s_add_i32 s93, s93, s37
	v_lshl_add_u64 v[138:139], s[26:27], 0, v[176:177]
	s_mov_b32 m0, s93
	ds_read_b128 v[178:181], v143 offset:16384
	ds_read_b128 v[182:185], v143 offset:17408
	ds_read_b128 v[186:189], v143 offset:18432
	ds_read_b128 v[190:193], v143 offset:19456
	ds_read_b128 v[194:197], v143 offset:20480
	ds_read_b128 v[198:201], v143 offset:21504
	ds_read_b128 v[202:205], v143 offset:22528
	ds_read_b128 v[206:209], v143 offset:23552
	global_load_lds_dwordx4 v[138:139], off
	s_add_i32 m0, s93, 0x2000
	s_add_u32 s94, s26, 0x80000
	v_lshl_add_u64 v[210:211], s[26:27], 0, v[128:129]
	s_addc_u32 s95, s27, 0
	s_add_i32 s93, s96, s37
	global_load_lds_dwordx4 v[210:211], off
	v_lshl_add_u64 v[212:213], s[94:95], 0, v[176:177]
	s_mov_b32 m0, s93
	v_lshl_add_u64 v[214:215], s[28:29], 0, v[130:131]
	global_load_lds_dwordx4 v[212:213], off
	v_lshl_add_u64 v[212:213], s[94:95], 0, v[128:129]
	s_add_i32 m0, s93, 0x2000
	s_nop 0
	global_load_lds_dwordx4 v[212:213], off
	v_lshl_add_u64 v[212:213], s[28:29], 0, v[132:133]
	s_mov_b32 m0, s75
	s_nop 0
	global_load_lds_dwordx4 v[212:213], off
	s_mov_b32 m0, s76
	s_nop 0
	global_load_lds_dwordx4 v[214:215], off
	s_waitcnt vmcnt(8)
	s_waitcnt lgkmcnt(0)
	s_barrier
; #define PG8_STAGE(bufoff, gbase, voff) do { _Pragma("unroll") for (int _i = 0; _i < 2; ++_i) \
;         __builtin_amdgcn_global_load_lds((const unsigned*)((const char*)(gbase) + (voff)[_i]), (LAS unsigned*)(lds + (bufoff) + ldsw + _i * 8192), 16, 0, 0); } while (0)
; #define PG8_LDA(dst, b, h) do { _Pragma("unroll") for (int m = 0; m < 4; ++m) _Pragma("unroll") for (int k = 0; k < 2; ++k) dst[m][k] = *(const LAS bf16x8*)(lds + PG8_SA(b, h) + aoff + m * 2048 + k * 1024); } while (0)
; #define PG8_LDB(dst, b, h) do { _Pragma("unroll") for (int n = 0; n < 2; ++n) _Pragma("unroll") for (int k = 0; k < 2; ++k) dst[n][k] = *(const LAS bf16x8*)(lds + PG8_SB(b, h) + boff + n * 2048 + k * 1024); } while (0)
; #define PG8_MMA(ai, bj, At, Bt) do { __builtin_amdgcn_s_setprio(1); _Pragma("unroll") for (int m = 0; m < 4; ++m) _Pragma("unroll") for (int n = 0; n < 2; ++n) _Pragma("unroll") for (int k = 0; k < 2; ++k) \
;         acc[ai][bj][m][n] = __builtin_amdgcn_mfma_f32_16x16x32_bf16(Bt[n][k], At[m][k], acc[ai][bj][m][n], 0, 0, 0); __builtin_amdgcn_s_setprio(0); } while (0)
; #define PG8_WAIT_V(n) asm volatile("s_waitcnt vmcnt(" #n ")" ::: "memory")
; #define PG8_WAIT_L(n) asm volatile("s_waitcnt lgkmcnt(" #n ")" ::: "memory")
; #define PG8_BAR __builtin_amdgcn_s_barrier()
; #define PG8_SCHED __builtin_amdgcn_sched_barrier(0)
; template <class Epi>
; DI void gemm_phase(LAS unsigned char* lds, const Gemm g, const Order& S, const Epi& E) {
;     ...
;             PG8_WAIT_V(8); PG8_WAIT_L(0); PG8_BAR; PG8_MMA(1, 0, At, B0); PG8_MMA(1, 1, At, B1); PG8_BAR; PG8_SCHED;
;             PG8_LDB(B0, 1, 0); PG8_LDB(B1, 1, 1); PG8_SCHED; PG8_LDA(At, 1, 0); PG8_STAGE(PG8_SA(0, 1), a2 + hstepA, voffA);
;             PG8_WAIT_V(8); PG8_WAIT_L(0); PG8_BAR; PG8_MMA(0, 0, At, B0); PG8_MMA(0, 1, At, B1); PG8_BAR; PG8_SCHED;
	s_setprio 1
	v_mfma_f32_16x16x32_bf16 v[60:63], v[144:147], v[178:181], v[60:63]
	v_mfma_f32_16x16x32_bf16 v[56:59], v[152:155], v[178:181], v[56:59]
	v_mfma_f32_16x16x32_bf16 v[44:47], v[144:147], v[186:189], v[44:47]
	v_mfma_f32_16x16x32_bf16 v[40:43], v[152:155], v[186:189], v[40:43]
	v_mfma_f32_16x16x32_bf16 v[28:31], v[144:147], v[194:197], v[28:31]
	v_mfma_f32_16x16x32_bf16 v[24:27], v[152:155], v[194:197], v[24:27]
	v_mfma_f32_16x16x32_bf16 v[12:15], v[144:147], v[202:205], v[12:15]
	v_mfma_f32_16x16x32_bf16 v[8:11], v[152:155], v[202:205], v[8:11]
	v_mfma_f32_16x16x32_bf16 v[60:63], v[148:151], v[182:185], v[60:63]
	v_mfma_f32_16x16x32_bf16 v[56:59], v[156:159], v[182:185], v[56:59]
	v_mfma_f32_16x16x32_bf16 v[44:47], v[148:151], v[190:193], v[44:47]
	v_mfma_f32_16x16x32_bf16 v[40:43], v[156:159], v[190:193], v[40:43]
	v_mfma_f32_16x16x32_bf16 v[28:31], v[148:151], v[198:201], v[28:31]
	v_mfma_f32_16x16x32_bf16 v[24:27], v[156:159], v[198:201], v[24:27]
	v_mfma_f32_16x16x32_bf16 v[12:15], v[148:151], v[206:209], v[12:15]
	v_mfma_f32_16x16x32_bf16 v[8:11], v[156:159], v[206:209], v[8:11]
	s_setprio 0
	s_setprio 1
	v_mfma_f32_16x16x32_bf16 v[52:55], v[160:163], v[178:181], v[52:55]
	v_mfma_f32_16x16x32_bf16 v[48:51], v[168:171], v[178:181], v[48:51]
	v_mfma_f32_16x16x32_bf16 v[36:39], v[160:163], v[186:189], v[36:39]
	v_mfma_f32_16x16x32_bf16 v[32:35], v[168:171], v[186:189], v[32:35]
	v_mfma_f32_16x16x32_bf16 v[20:23], v[160:163], v[194:197], v[20:23]
	v_mfma_f32_16x16x32_bf16 v[16:19], v[168:171], v[194:197], v[16:19]
	v_mfma_f32_16x16x32_bf16 v[4:7], v[160:163], v[202:205], v[4:7]
	v_mfma_f32_16x16x32_bf16 v[0:3], v[168:171], v[202:205], v[0:3]
	v_mfma_f32_16x16x32_bf16 v[52:55], v[164:167], v[182:185], v[52:55]
	v_mfma_f32_16x16x32_bf16 v[48:51], v[172:175], v[182:185], v[48:51]
	v_mfma_f32_16x16x32_bf16 v[36:39], v[164:167], v[190:193], v[36:39]
	v_mfma_f32_16x16x32_bf16 v[32:35], v[172:175], v[190:193], v[32:35]
	v_mfma_f32_16x16x32_bf16 v[20:23], v[164:167], v[198:201], v[20:23]
	v_mfma_f32_16x16x32_bf16 v[16:19], v[172:175], v[198:201], v[16:19]
	v_mfma_f32_16x16x32_bf16 v[4:7], v[164:167], v[206:209], v[4:7]
	v_mfma_f32_16x16x32_bf16 v[0:3], v[172:175], v[206:209], v[0:3]
	s_setprio 0
	s_barrier
	s_add_i32 s93, 0, 0x18000
	s_add_i32 s94, 0, 0x1c000
	v_add_u32_e32 v156, s93, v142
	v_add_u32_e32 v172, s94, v142
	ds_read_b128 v[144:147], v156
	ds_read_b128 v[148:151], v156 offset:1024
	ds_read_b128 v[152:155], v156 offset:2048
	ds_read_b128 v[156:159], v156 offset:3072
	ds_read_b128 v[160:163], v172
	ds_read_b128 v[164:167], v172 offset:1024
	ds_read_b128 v[168:171], v172 offset:2048
	ds_read_b128 v[172:175], v172 offset:3072
	s_add_u32 s28, s28, 0x80000
	s_addc_u32 s29, s29, 0
	s_mov_b32 m0, s77
	v_lshl_add_u64 v[216:217], s[28:29], 0, v[132:133]
	ds_read_b128 v[178:181], v143 offset:32768
	ds_read_b128 v[182:185], v143 offset:33792
	ds_read_b128 v[186:189], v143 offset:34816
	ds_read_b128 v[190:193], v143 offset:35840
	ds_read_b128 v[194:197], v143 offset:36864
	ds_read_b128 v[198:201], v143 offset:37888
	ds_read_b128 v[202:205], v143 offset:38912
	ds_read_b128 v[206:209], v143 offset:39936
	global_load_lds_dwordx4 v[216:217], off
	v_lshl_add_u64 v[216:217], s[28:29], 0, v[130:131]
	s_mov_b32 m0, s78
	s_nop 0
	global_load_lds_dwordx4 v[216:217], off
	s_waitcnt vmcnt(8)
	s_waitcnt lgkmcnt(0)
	s_barrier
	s_setprio 1
	v_mfma_f32_16x16x32_bf16 v[120:123], v[144:147], v[178:181], v[120:123]
	v_mfma_f32_16x16x32_bf16 v[124:127], v[152:155], v[178:181], v[124:127]
	v_mfma_f32_16x16x32_bf16 v[108:111], v[144:147], v[186:189], v[108:111]
	v_mfma_f32_16x16x32_bf16 v[104:107], v[152:155], v[186:189], v[104:107]
	v_mfma_f32_16x16x32_bf16 v[92:95], v[144:147], v[194:197], v[92:95]
	v_mfma_f32_16x16x32_bf16 v[88:91], v[152:155], v[194:197], v[88:91]
	v_mfma_f32_16x16x32_bf16 v[76:79], v[144:147], v[202:205], v[76:79]
	v_mfma_f32_16x16x32_bf16 v[72:75], v[152:155], v[202:205], v[72:75]
	v_mfma_f32_16x16x32_bf16 v[120:123], v[148:151], v[182:185], v[120:123]
	v_mfma_f32_16x16x32_bf16 v[124:127], v[156:159], v[182:185], v[124:127]
	v_mfma_f32_16x16x32_bf16 v[108:111], v[148:151], v[190:193], v[108:111]
	v_mfma_f32_16x16x32_bf16 v[104:107], v[156:159], v[190:193], v[104:107]
	v_mfma_f32_16x16x32_bf16 v[92:95], v[148:151], v[198:201], v[92:95]
	v_mfma_f32_16x16x32_bf16 v[88:91], v[156:159], v[198:201], v[88:91]
	v_mfma_f32_16x16x32_bf16 v[76:79], v[148:151], v[206:209], v[76:79]
	v_mfma_f32_16x16x32_bf16 v[72:75], v[156:159], v[206:209], v[72:75]
	s_setprio 0
	s_setprio 1
	v_mfma_f32_16x16x32_bf16 v[116:119], v[160:163], v[178:181], v[116:119]
	v_mfma_f32_16x16x32_bf16 v[112:115], v[168:171], v[178:181], v[112:115]
	v_mfma_f32_16x16x32_bf16 v[100:103], v[160:163], v[186:189], v[100:103]
	v_mfma_f32_16x16x32_bf16 v[96:99], v[168:171], v[186:189], v[96:99]
	v_mfma_f32_16x16x32_bf16 v[84:87], v[160:163], v[194:197], v[84:87]
	v_mfma_f32_16x16x32_bf16 v[80:83], v[168:171], v[194:197], v[80:83]
	v_mfma_f32_16x16x32_bf16 v[68:71], v[160:163], v[202:205], v[68:71]
	v_mfma_f32_16x16x32_bf16 v[64:67], v[168:171], v[202:205], v[64:67]
	v_mfma_f32_16x16x32_bf16 v[116:119], v[164:167], v[182:185], v[116:119]
	v_mfma_f32_16x16x32_bf16 v[112:115], v[172:175], v[182:185], v[112:115]
	v_mfma_f32_16x16x32_bf16 v[100:103], v[164:167], v[190:193], v[100:103]
	v_mfma_f32_16x16x32_bf16 v[96:99], v[172:175], v[190:193], v[96:99]
	v_mfma_f32_16x16x32_bf16 v[84:87], v[164:167], v[198:201], v[84:87]
	v_mfma_f32_16x16x32_bf16 v[80:83], v[172:175], v[198:201], v[80:83]
	v_mfma_f32_16x16x32_bf16 v[68:71], v[164:167], v[206:209], v[68:71]
	v_mfma_f32_16x16x32_bf16 v[64:67], v[172:175], v[206:209], v[64:67]
	s_setprio 0
	s_barrier
; #define PG8_STAGE(bufoff, gbase, voff) do { _Pragma("unroll") for (int _i = 0; _i < 2; ++_i) \
;         __builtin_amdgcn_global_load_lds((const unsigned*)((const char*)(gbase) + (voff)[_i]), (LAS unsigned*)(lds + (bufoff) + ldsw + _i * 8192), 16, 0, 0); } while (0)
; #define PG8_LDA(dst, b, h) do { _Pragma("unroll") for (int m = 0; m < 4; ++m) _Pragma("unroll") for (int k = 0; k < 2; ++k) dst[m][k] = *(const LAS bf16x8*)(lds + PG8_SA(b, h) + aoff + m * 2048 + k * 1024); } while (0)
; #define PG8_MMA(ai, bj, At, Bt) do { __builtin_amdgcn_s_setprio(1); _Pragma("unroll") for (int m = 0; m < 4; ++m) _Pragma("unroll") for (int n = 0; n < 2; ++n) _Pragma("unroll") for (int k = 0; k < 2; ++k) \
;         acc[ai][bj][m][n] = __builtin_amdgcn_mfma_f32_16x16x32_bf16(Bt[n][k], At[m][k], acc[ai][bj][m][n], 0, 0, 0); __builtin_amdgcn_s_setprio(0); } while (0)
; #define PG8_WAIT_V(n) asm volatile("s_waitcnt vmcnt(" #n ")" ::: "memory")
; #define PG8_WAIT_L(n) asm volatile("s_waitcnt lgkmcnt(" #n ")" ::: "memory")
; #define PG8_BAR __builtin_amdgcn_s_barrier()
; #define PG8_SCHED __builtin_amdgcn_sched_barrier(0)
; template <class Epi>
; DI void gemm_phase(LAS unsigned char* lds, const Gemm g, const Order& S, const Epi& E) {
;     ...
;             PG8_LDA(At, 1, 1); PG8_STAGE(PG8_SB(1, 0), b3, voffB); PG8_STAGE(PG8_SB(1, 1), b3 + hstepB, voffB); PG8_STAGE(PG8_SA(1, 0), a3, voffA);
;             PG8_WAIT_V(8); PG8_WAIT_L(0); PG8_BAR; PG8_MMA(1, 0, At, B0); PG8_MMA(1, 1, At, B1); PG8_BAR; PG8_SCHED;
;         }
	s_add_i32 s28, s93, s37
	v_lshl_add_u64 v[138:139], v[138:139], 0, s[56:57]
	s_mov_b32 m0, s28
	ds_read_b128 v[178:181], v143 offset:49152
	ds_read_b128 v[182:185], v143 offset:50176
	ds_read_b128 v[186:189], v143 offset:51200
	ds_read_b128 v[190:193], v143 offset:52224
	ds_read_b128 v[194:197], v143 offset:53248
	ds_read_b128 v[198:201], v143 offset:54272
	ds_read_b128 v[202:205], v143 offset:55296
	ds_read_b128 v[206:209], v143 offset:56320
	global_load_lds_dwordx4 v[138:139], off
	s_add_i32 m0, s28, 0x2000
	s_add_u32 s26, s26, 0x80080
	v_lshl_add_u64 v[138:139], v[210:211], 0, s[56:57]
	s_addc_u32 s27, s27, 0
	s_add_i32 s28, s94, s37
	global_load_lds_dwordx4 v[138:139], off
	v_lshl_add_u64 v[138:139], s[26:27], 0, v[176:177]
	s_mov_b32 m0, s28
	s_nop 0
	global_load_lds_dwordx4 v[138:139], off
	v_lshl_add_u64 v[138:139], s[26:27], 0, v[128:129]
	s_add_i32 m0, s28, 0x2000
	s_nop 0
	global_load_lds_dwordx4 v[138:139], off
	v_lshl_add_u64 v[138:139], v[212:213], 0, s[56:57]
	s_mov_b32 m0, s82
	s_nop 0
	global_load_lds_dwordx4 v[138:139], off
	v_lshl_add_u64 v[138:139], v[214:215], 0, s[56:57]
	s_mov_b32 m0, s83
	s_nop 0
	global_load_lds_dwordx4 v[138:139], off
	s_waitcnt vmcnt(8)
	s_waitcnt lgkmcnt(0)
	s_barrier
	s_setprio 1
	v_mfma_f32_16x16x32_bf16 v[60:63], v[144:147], v[178:181], v[60:63]
	v_mfma_f32_16x16x32_bf16 v[56:59], v[152:155], v[178:181], v[56:59]
	v_mfma_f32_16x16x32_bf16 v[44:47], v[144:147], v[186:189], v[44:47]
	v_mfma_f32_16x16x32_bf16 v[40:43], v[152:155], v[186:189], v[40:43]
	v_mfma_f32_16x16x32_bf16 v[28:31], v[144:147], v[194:197], v[28:31]
	v_mfma_f32_16x16x32_bf16 v[24:27], v[152:155], v[194:197], v[24:27]
	v_mfma_f32_16x16x32_bf16 v[12:15], v[144:147], v[202:205], v[12:15]
	v_mfma_f32_16x16x32_bf16 v[8:11], v[152:155], v[202:205], v[8:11]
	v_mfma_f32_16x16x32_bf16 v[60:63], v[148:151], v[182:185], v[60:63]
	v_mfma_f32_16x16x32_bf16 v[56:59], v[156:159], v[182:185], v[56:59]
	v_mfma_f32_16x16x32_bf16 v[44:47], v[148:151], v[190:193], v[44:47]
	v_mfma_f32_16x16x32_bf16 v[40:43], v[156:159], v[190:193], v[40:43]
	v_mfma_f32_16x16x32_bf16 v[28:31], v[148:151], v[198:201], v[28:31]
	v_mfma_f32_16x16x32_bf16 v[24:27], v[156:159], v[198:201], v[24:27]
	v_mfma_f32_16x16x32_bf16 v[12:15], v[148:151], v[206:209], v[12:15]
	v_mfma_f32_16x16x32_bf16 v[8:11], v[156:159], v[206:209], v[8:11]
	s_setprio 0
	s_setprio 1
	v_mfma_f32_16x16x32_bf16 v[52:55], v[160:163], v[178:181], v[52:55]
	v_mfma_f32_16x16x32_bf16 v[48:51], v[168:171], v[178:181], v[48:51]
	v_mfma_f32_16x16x32_bf16 v[36:39], v[160:163], v[186:189], v[36:39]
	v_mfma_f32_16x16x32_bf16 v[32:35], v[168:171], v[186:189], v[32:35]
	v_mfma_f32_16x16x32_bf16 v[20:23], v[160:163], v[194:197], v[20:23]
	v_mfma_f32_16x16x32_bf16 v[16:19], v[168:171], v[194:197], v[16:19]
	v_mfma_f32_16x16x32_bf16 v[4:7], v[160:163], v[202:205], v[4:7]
	v_mfma_f32_16x16x32_bf16 v[0:3], v[168:171], v[202:205], v[0:3]
	v_mfma_f32_16x16x32_bf16 v[52:55], v[164:167], v[182:185], v[52:55]
	v_mfma_f32_16x16x32_bf16 v[48:51], v[172:175], v[182:185], v[48:51]
	v_mfma_f32_16x16x32_bf16 v[36:39], v[164:167], v[190:193], v[36:39]
	v_mfma_f32_16x16x32_bf16 v[32:35], v[172:175], v[190:193], v[32:35]
	v_mfma_f32_16x16x32_bf16 v[20:23], v[164:167], v[198:201], v[20:23]
	v_mfma_f32_16x16x32_bf16 v[16:19], v[172:175], v[198:201], v[16:19]
	v_mfma_f32_16x16x32_bf16 v[4:7], v[164:167], v[206:209], v[4:7]
	v_mfma_f32_16x16x32_bf16 v[0:3], v[172:175], v[206:209], v[0:3]
	s_setprio 0
	s_barrier
	s_add_u32 s90, s90, 0x100
	s_addc_u32 s91, s91, 0
	s_add_u32 s24, s24, 0x100
	s_addc_u32 s25, s25, 0
	s_cmp_ge_i32 s92, s79
	s_mov_b32 s26, s92
	s_cbranch_scc0 .LBB0_923

; #define PG8_STAGE(bufoff, gbase, voff) do { _Pragma("unroll") for (int _i = 0; _i < 2; ++_i) \
;         __builtin_amdgcn_global_load_lds((const unsigned*)((const char*)(gbase) + (voff)[_i]), (LAS unsigned*)(lds + (bufoff) + ldsw + _i * 8192), 16, 0, 0); } while (0)
; #define PG8_LDA(dst, b, h) do { _Pragma("unroll") for (int m = 0; m < 4; ++m) _Pragma("unroll") for (int k = 0; k < 2; ++k) dst[m][k] = *(const LAS bf16x8*)(lds + PG8_SA(b, h) + aoff + m * 2048 + k * 1024); } while (0)
; #define PG8_LDB(dst, b, h) do { _Pragma("unroll") for (int n = 0; n < 2; ++n) _Pragma("unroll") for (int k = 0; k < 2; ++k) dst[n][k] = *(const LAS bf16x8*)(lds + PG8_SB(b, h) + boff + n * 2048 + k * 1024); } while (0)
; #define PG8_MMA(ai, bj, At, Bt) do { __builtin_amdgcn_s_setprio(1); _Pragma("unroll") for (int m = 0; m < 4; ++m) _Pragma("unroll") for (int n = 0; n < 2; ++n) _Pragma("unroll") for (int k = 0; k < 2; ++k) \
;         acc[ai][bj][m][n] = __builtin_amdgcn_mfma_f32_16x16x32_bf16(Bt[n][k], At[m][k], acc[ai][bj][m][n], 0, 0, 0); __builtin_amdgcn_s_setprio(0); } while (0)
; #define PG8_WAIT_V(n) asm volatile("s_waitcnt vmcnt(" #n ")" ::: "memory")
; #define PG8_WAIT_L(n) asm volatile("s_waitcnt lgkmcnt(" #n ")" ::: "memory")
; #define PG8_BAR __builtin_amdgcn_s_barrier()
; #define PG8_SCHED __builtin_amdgcn_sched_barrier(0)
; template <class Epi>
; DI void gemm_phase(LAS unsigned char* lds, const Gemm g, const Order& S, const Epi& E) {
;     ...
;         for (int t = 0; t < nt; t += 2) {
;             const bool last = (t == nt - 2);
;             const char* a1 = cA + (size_t)(t + 1) * kstep;
;             const char* a2 = last ? nA : cA + (size_t)(t + 2) * kstep; const char* b2 = last ? nB : cB + (size_t)(t + 2) * kstep;
;             const char* a3 = a2 + kstep; const char* b3 = b2 + kstep;
;             PG8_LDB(B0, 0, 0); PG8_LDB(B1, 0, 1); PG8_SCHED; PG8_LDA(At, 0, 0); PG8_STAGE(PG8_SA(1, 1), a1 + hstepA, voffA);
;             PG8_WAIT_V(8); PG8_WAIT_L(0); PG8_BAR; PG8_MMA(0, 0, At, B0); PG8_MMA(0, 1, At, B1); PG8_BAR; PG8_SCHED;
;             PG8_LDA(At, 0, 1); PG8_STAGE(PG8_SB(0, 0), b2, voffB); PG8_STAGE(PG8_SB(0, 1), b2 + hstepB, voffB); PG8_STAGE(PG8_SA(0, 0), a2, voffA);
;             PG8_WAIT_V(8); PG8_WAIT_L(0); PG8_BAR; PG8_MMA(1, 0, At, B0); PG8_MMA(1, 1, At, B1); PG8_BAR; PG8_SCHED;
.LBB0_1003:
	s_add_i32 s86, s27, 2
	s_add_u32 s34, s30, 0xffe00080
	s_addc_u32 s35, s31, -1
	s_add_i32 s87, 0, 0x10000
	s_cmp_eq_u32 s84, s27
	s_cselect_b32 s37, s23, s35
	s_cselect_b32 s36, s22, s34
	s_cselect_b32 s35, s25, s21
	s_cselect_b32 s34, s24, s19
	s_add_i32 s27, 0, 0x14000
	v_add_u32_e32 v120, s87, v204
	v_add_u32_e32 v156, s27, v204
	ds_read_b128 v[96:99], v120
	ds_read_b128 v[104:107], v120 offset:1024
	ds_read_b128 v[112:115], v120 offset:2048
	ds_read_b128 v[120:123], v120 offset:3072
	ds_read_b128 v[144:147], v156
	ds_read_b128 v[148:151], v156 offset:1024
	ds_read_b128 v[152:155], v156 offset:2048
	ds_read_b128 v[156:159], v156 offset:3072
	v_lshl_add_u64 v[200:201], s[30:31], 0, v[186:187]
	s_add_i32 m0, s29, 0xc000
	ds_read_b128 v[160:163], v205
	ds_read_b128 v[164:167], v205 offset:1024
	ds_read_b128 v[168:171], v205 offset:2048
	ds_read_b128 v[172:175], v205 offset:3072
	ds_read_b128 v[188:191], v205 offset:4096
	ds_read_b128 v[192:195], v205 offset:5120
	ds_read_b128 v[196:199], v205 offset:6144
	ds_read_b128 v[206:209], v205 offset:7168
	global_load_lds_dwordx4 v[200:201], off
	v_lshl_add_u64 v[200:201], s[30:31], 0, v[184:185]
	s_add_i32 m0, s29, 0xe000
	s_nop 0
	global_load_lds_dwordx4 v[200:201], off
	s_waitcnt vmcnt(8)
	s_waitcnt lgkmcnt(0)
	s_barrier
	s_setprio 1
	v_mfma_f32_16x16x32_bf16 v[136:139], v[96:99], v[160:163], v[136:139]
	v_mfma_f32_16x16x32_bf16 v[140:143], v[112:115], v[160:163], v[140:143]
	v_mfma_f32_16x16x32_bf16 v[124:127], v[96:99], v[168:171], v[124:127]
	v_mfma_f32_16x16x32_bf16 v[116:119], v[112:115], v[168:171], v[116:119]
	v_mfma_f32_16x16x32_bf16 v[92:95], v[96:99], v[188:191], v[92:95]
	v_mfma_f32_16x16x32_bf16 v[88:91], v[112:115], v[188:191], v[88:91]
	v_mfma_f32_16x16x32_bf16 v[76:79], v[96:99], v[196:199], v[76:79]
	v_mfma_f32_16x16x32_bf16 v[72:75], v[112:115], v[196:199], v[72:75]
	v_mfma_f32_16x16x32_bf16 v[136:139], v[104:107], v[164:167], v[136:139]
	v_mfma_f32_16x16x32_bf16 v[140:143], v[120:123], v[164:167], v[140:143]
	v_mfma_f32_16x16x32_bf16 v[124:127], v[104:107], v[172:175], v[124:127]
	v_mfma_f32_16x16x32_bf16 v[116:119], v[120:123], v[172:175], v[116:119]
	v_mfma_f32_16x16x32_bf16 v[92:95], v[104:107], v[192:195], v[92:95]
	v_mfma_f32_16x16x32_bf16 v[88:91], v[120:123], v[192:195], v[88:91]
	v_mfma_f32_16x16x32_bf16 v[76:79], v[104:107], v[206:209], v[76:79]
	v_mfma_f32_16x16x32_bf16 v[72:75], v[120:123], v[206:209], v[72:75]
	s_setprio 0
	s_setprio 1
	v_mfma_f32_16x16x32_bf16 v[132:135], v[144:147], v[160:163], v[132:135]
	v_mfma_f32_16x16x32_bf16 v[128:131], v[152:155], v[160:163], v[128:131]
	v_mfma_f32_16x16x32_bf16 v[108:111], v[144:147], v[168:171], v[108:111]
	v_mfma_f32_16x16x32_bf16 v[100:103], v[152:155], v[168:171], v[100:103]
	v_mfma_f32_16x16x32_bf16 v[84:87], v[144:147], v[188:191], v[84:87]
	v_mfma_f32_16x16x32_bf16 v[80:83], v[152:155], v[188:191], v[80:83]
	v_mfma_f32_16x16x32_bf16 v[68:71], v[144:147], v[196:199], v[68:71]
	v_mfma_f32_16x16x32_bf16 v[64:67], v[152:155], v[196:199], v[64:67]
	v_mfma_f32_16x16x32_bf16 v[132:135], v[148:151], v[164:167], v[132:135]
	v_mfma_f32_16x16x32_bf16 v[128:131], v[156:159], v[164:167], v[128:131]
	v_mfma_f32_16x16x32_bf16 v[108:111], v[148:151], v[172:175], v[108:111]
	v_mfma_f32_16x16x32_bf16 v[100:103], v[156:159], v[172:175], v[100:103]
	v_mfma_f32_16x16x32_bf16 v[84:87], v[148:151], v[192:195], v[84:87]
	v_mfma_f32_16x16x32_bf16 v[80:83], v[156:159], v[192:195], v[80:83]
	v_mfma_f32_16x16x32_bf16 v[68:71], v[148:151], v[206:209], v[68:71]
	v_mfma_f32_16x16x32_bf16 v[64:67], v[156:159], v[206:209], v[64:67]
	s_setprio 0
	s_barrier
	s_add_i32 s87, s87, s69
	v_lshl_add_u64 v[200:201], s[34:35], 0, v[176:177]
	s_mov_b32 m0, s87
	ds_read_b128 v[160:163], v205 offset:16384
	ds_read_b128 v[164:167], v205 offset:17408
	ds_read_b128 v[168:171], v205 offset:18432
	ds_read_b128 v[172:175], v205 offset:19456
	ds_read_b128 v[188:191], v205 offset:20480
	ds_read_b128 v[192:195], v205 offset:21504
	ds_read_b128 v[196:199], v205 offset:22528
	ds_read_b128 v[206:209], v205 offset:23552
	global_load_lds_dwordx4 v[200:201], off
	s_add_i32 m0, s87, 0x2000
	s_add_u32 s88, s34, 0x200000
	v_lshl_add_u64 v[210:211], s[34:35], 0, v[182:183]
	s_addc_u32 s89, s35, 0
	s_add_i32 s27, s27, s69
	global_load_lds_dwordx4 v[210:211], off
	v_lshl_add_u64 v[212:213], s[88:89], 0, v[176:177]
	s_mov_b32 m0, s27
	v_lshl_add_u64 v[214:215], s[36:37], 0, v[180:181]
	global_load_lds_dwordx4 v[212:213], off
	v_lshl_add_u64 v[212:213], s[88:89], 0, v[182:183]
	s_add_i32 m0, s27, 0x2000
	s_nop 0
	global_load_lds_dwordx4 v[212:213], off
	v_lshl_add_u64 v[212:213], s[36:37], 0, v[178:179]
	s_mov_b32 m0, s29
	s_nop 0
	global_load_lds_dwordx4 v[212:213], off
	s_mov_b32 m0, s76
	s_nop 0
	global_load_lds_dwordx4 v[214:215], off
	s_waitcnt vmcnt(8)
	s_waitcnt lgkmcnt(0)
	s_barrier
; #define PG8_STAGE(bufoff, gbase, voff) do { _Pragma("unroll") for (int _i = 0; _i < 2; ++_i) \
;         __builtin_amdgcn_global_load_lds((const unsigned*)((const char*)(gbase) + (voff)[_i]), (LAS unsigned*)(lds + (bufoff) + ldsw + _i * 8192), 16, 0, 0); } while (0)
; #define PG8_LDA(dst, b, h) do { _Pragma("unroll") for (int m = 0; m < 4; ++m) _Pragma("unroll") for (int k = 0; k < 2; ++k) dst[m][k] = *(const LAS bf16x8*)(lds + PG8_SA(b, h) + aoff + m * 2048 + k * 1024); } while (0)
; #define PG8_LDB(dst, b, h) do { _Pragma("unroll") for (int n = 0; n < 2; ++n) _Pragma("unroll") for (int k = 0; k < 2; ++k) dst[n][k] = *(const LAS bf16x8*)(lds + PG8_SB(b, h) + boff + n * 2048 + k * 1024); } while (0)
; #define PG8_MMA(ai, bj, At, Bt) do { __builtin_amdgcn_s_setprio(1); _Pragma("unroll") for (int m = 0; m < 4; ++m) _Pragma("unroll") for (int n = 0; n < 2; ++n) _Pragma("unroll") for (int k = 0; k < 2; ++k) \
;         acc[ai][bj][m][n] = __builtin_amdgcn_mfma_f32_16x16x32_bf16(Bt[n][k], At[m][k], acc[ai][bj][m][n], 0, 0, 0); __builtin_amdgcn_s_setprio(0); } while (0)
; #define PG8_WAIT_V(n) asm volatile("s_waitcnt vmcnt(" #n ")" ::: "memory")
; #define PG8_WAIT_L(n) asm volatile("s_waitcnt lgkmcnt(" #n ")" ::: "memory")
; #define PG8_BAR __builtin_amdgcn_s_barrier()
; #define PG8_SCHED __builtin_amdgcn_sched_barrier(0)
; template <class Epi>
; DI void gemm_phase(LAS unsigned char* lds, const Gemm g, const Order& S, const Epi& E) {
;     ...
;             PG8_WAIT_V(8); PG8_WAIT_L(0); PG8_BAR; PG8_MMA(1, 0, At, B0); PG8_MMA(1, 1, At, B1); PG8_BAR; PG8_SCHED;
;             PG8_LDB(B0, 1, 0); PG8_LDB(B1, 1, 1); PG8_SCHED; PG8_LDA(At, 1, 0); PG8_STAGE(PG8_SA(0, 1), a2 + hstepA, voffA);
;             PG8_WAIT_V(8); PG8_WAIT_L(0); PG8_BAR; PG8_MMA(0, 0, At, B0); PG8_MMA(0, 1, At, B1); PG8_BAR; PG8_SCHED;
	s_setprio 1
	v_mfma_f32_16x16x32_bf16 v[60:63], v[96:99], v[160:163], v[60:63]
	v_mfma_f32_16x16x32_bf16 v[56:59], v[112:115], v[160:163], v[56:59]
	v_mfma_f32_16x16x32_bf16 v[44:47], v[96:99], v[168:171], v[44:47]
	v_mfma_f32_16x16x32_bf16 v[40:43], v[112:115], v[168:171], v[40:43]
	v_mfma_f32_16x16x32_bf16 v[28:31], v[96:99], v[188:191], v[28:31]
	v_mfma_f32_16x16x32_bf16 v[24:27], v[112:115], v[188:191], v[24:27]
	v_mfma_f32_16x16x32_bf16 v[12:15], v[96:99], v[196:199], v[12:15]
	v_mfma_f32_16x16x32_bf16 v[8:11], v[112:115], v[196:199], v[8:11]
	v_mfma_f32_16x16x32_bf16 v[60:63], v[104:107], v[164:167], v[60:63]
	v_mfma_f32_16x16x32_bf16 v[56:59], v[120:123], v[164:167], v[56:59]
	v_mfma_f32_16x16x32_bf16 v[44:47], v[104:107], v[172:175], v[44:47]
	v_mfma_f32_16x16x32_bf16 v[40:43], v[120:123], v[172:175], v[40:43]
	v_mfma_f32_16x16x32_bf16 v[28:31], v[104:107], v[192:195], v[28:31]
	v_mfma_f32_16x16x32_bf16 v[24:27], v[120:123], v[192:195], v[24:27]
	v_mfma_f32_16x16x32_bf16 v[12:15], v[104:107], v[206:209], v[12:15]
	v_mfma_f32_16x16x32_bf16 v[8:11], v[120:123], v[206:209], v[8:11]
	s_setprio 0
	s_setprio 1
	v_mfma_f32_16x16x32_bf16 v[52:55], v[144:147], v[160:163], v[52:55]
	v_mfma_f32_16x16x32_bf16 v[48:51], v[152:155], v[160:163], v[48:51]
	v_mfma_f32_16x16x32_bf16 v[36:39], v[144:147], v[168:171], v[36:39]
	v_mfma_f32_16x16x32_bf16 v[32:35], v[152:155], v[168:171], v[32:35]
	v_mfma_f32_16x16x32_bf16 v[20:23], v[144:147], v[188:191], v[20:23]
	v_mfma_f32_16x16x32_bf16 v[16:19], v[152:155], v[188:191], v[16:19]
	v_mfma_f32_16x16x32_bf16 v[4:7], v[144:147], v[196:199], v[4:7]
	v_mfma_f32_16x16x32_bf16 v[0:3], v[152:155], v[196:199], v[0:3]
	v_mfma_f32_16x16x32_bf16 v[52:55], v[148:151], v[164:167], v[52:55]
	v_mfma_f32_16x16x32_bf16 v[48:51], v[156:159], v[164:167], v[48:51]
	v_mfma_f32_16x16x32_bf16 v[36:39], v[148:151], v[172:175], v[36:39]
	v_mfma_f32_16x16x32_bf16 v[32:35], v[156:159], v[172:175], v[32:35]
	v_mfma_f32_16x16x32_bf16 v[20:23], v[148:151], v[192:195], v[20:23]
	v_mfma_f32_16x16x32_bf16 v[16:19], v[156:159], v[192:195], v[16:19]
	v_mfma_f32_16x16x32_bf16 v[4:7], v[148:151], v[206:209], v[4:7]
	v_mfma_f32_16x16x32_bf16 v[0:3], v[156:159], v[206:209], v[0:3]
	s_setprio 0
	s_barrier
	s_add_i32 s27, 0, 0x18000
	s_add_i32 s87, 0, 0x1c000
	v_add_u32_e32 v120, s27, v204
	v_add_u32_e32 v156, s87, v204
	ds_read_b128 v[96:99], v120
	ds_read_b128 v[104:107], v120 offset:1024
	ds_read_b128 v[112:115], v120 offset:2048
	ds_read_b128 v[120:123], v120 offset:3072
	ds_read_b128 v[144:147], v156
	ds_read_b128 v[148:151], v156 offset:1024
	ds_read_b128 v[152:155], v156 offset:2048
	ds_read_b128 v[156:159], v156 offset:3072
	s_add_u32 s36, s36, 0x200000
	s_addc_u32 s37, s37, 0
	s_mov_b32 m0, s77
	v_lshl_add_u64 v[216:217], s[36:37], 0, v[178:179]
	ds_read_b128 v[160:163], v205 offset:32768
	ds_read_b128 v[164:167], v205 offset:33792
	ds_read_b128 v[168:171], v205 offset:34816
	ds_read_b128 v[172:175], v205 offset:35840
	ds_read_b128 v[188:191], v205 offset:36864
	ds_read_b128 v[192:195], v205 offset:37888
	ds_read_b128 v[196:199], v205 offset:38912
	ds_read_b128 v[206:209], v205 offset:39936
	global_load_lds_dwordx4 v[216:217], off
	v_lshl_add_u64 v[216:217], s[36:37], 0, v[180:181]
	s_mov_b32 m0, s78
	s_nop 0
	global_load_lds_dwordx4 v[216:217], off
	s_waitcnt vmcnt(8)
	s_waitcnt lgkmcnt(0)
	s_barrier
	s_setprio 1
	v_mfma_f32_16x16x32_bf16 v[136:139], v[96:99], v[160:163], v[136:139]
	v_mfma_f32_16x16x32_bf16 v[140:143], v[112:115], v[160:163], v[140:143]
	v_mfma_f32_16x16x32_bf16 v[124:127], v[96:99], v[168:171], v[124:127]
	v_mfma_f32_16x16x32_bf16 v[116:119], v[112:115], v[168:171], v[116:119]
	v_mfma_f32_16x16x32_bf16 v[92:95], v[96:99], v[188:191], v[92:95]
	v_mfma_f32_16x16x32_bf16 v[88:91], v[112:115], v[188:191], v[88:91]
	v_mfma_f32_16x16x32_bf16 v[76:79], v[96:99], v[196:199], v[76:79]
	v_mfma_f32_16x16x32_bf16 v[72:75], v[112:115], v[196:199], v[72:75]
	v_mfma_f32_16x16x32_bf16 v[136:139], v[104:107], v[164:167], v[136:139]
	v_mfma_f32_16x16x32_bf16 v[140:143], v[120:123], v[164:167], v[140:143]
	v_mfma_f32_16x16x32_bf16 v[124:127], v[104:107], v[172:175], v[124:127]
	v_mfma_f32_16x16x32_bf16 v[116:119], v[120:123], v[172:175], v[116:119]
	v_mfma_f32_16x16x32_bf16 v[92:95], v[104:107], v[192:195], v[92:95]
	v_mfma_f32_16x16x32_bf16 v[88:91], v[120:123], v[192:195], v[88:91]
	v_mfma_f32_16x16x32_bf16 v[76:79], v[104:107], v[206:209], v[76:79]
	v_mfma_f32_16x16x32_bf16 v[72:75], v[120:123], v[206:209], v[72:75]
	s_setprio 0
	s_setprio 1
	v_mfma_f32_16x16x32_bf16 v[132:135], v[144:147], v[160:163], v[132:135]
	v_mfma_f32_16x16x32_bf16 v[128:131], v[152:155], v[160:163], v[128:131]
	v_mfma_f32_16x16x32_bf16 v[108:111], v[144:147], v[168:171], v[108:111]
	v_mfma_f32_16x16x32_bf16 v[100:103], v[152:155], v[168:171], v[100:103]
	v_mfma_f32_16x16x32_bf16 v[84:87], v[144:147], v[188:191], v[84:87]
	v_mfma_f32_16x16x32_bf16 v[80:83], v[152:155], v[188:191], v[80:83]
	v_mfma_f32_16x16x32_bf16 v[68:71], v[144:147], v[196:199], v[68:71]
	v_mfma_f32_16x16x32_bf16 v[64:67], v[152:155], v[196:199], v[64:67]
	v_mfma_f32_16x16x32_bf16 v[132:135], v[148:151], v[164:167], v[132:135]
	v_mfma_f32_16x16x32_bf16 v[128:131], v[156:159], v[164:167], v[128:131]
	v_mfma_f32_16x16x32_bf16 v[108:111], v[148:151], v[172:175], v[108:111]
	v_mfma_f32_16x16x32_bf16 v[100:103], v[156:159], v[172:175], v[100:103]
	v_mfma_f32_16x16x32_bf16 v[84:87], v[148:151], v[192:195], v[84:87]
	v_mfma_f32_16x16x32_bf16 v[80:83], v[156:159], v[192:195], v[80:83]
	v_mfma_f32_16x16x32_bf16 v[68:71], v[148:151], v[206:209], v[68:71]
	v_mfma_f32_16x16x32_bf16 v[64:67], v[156:159], v[206:209], v[64:67]
	s_setprio 0
	s_barrier
; #define PG8_STAGE(bufoff, gbase, voff) do { _Pragma("unroll") for (int _i = 0; _i < 2; ++_i) \
;         __builtin_amdgcn_global_load_lds((const unsigned*)((const char*)(gbase) + (voff)[_i]), (LAS unsigned*)(lds + (bufoff) + ldsw + _i * 8192), 16, 0, 0); } while (0)
; #define PG8_LDA(dst, b, h) do { _Pragma("unroll") for (int m = 0; m < 4; ++m) _Pragma("unroll") for (int k = 0; k < 2; ++k) dst[m][k] = *(const LAS bf16x8*)(lds + PG8_SA(b, h) + aoff + m * 2048 + k * 1024); } while (0)
; #define PG8_MMA(ai, bj, At, Bt) do { __builtin_amdgcn_s_setprio(1); _Pragma("unroll") for (int m = 0; m < 4; ++m) _Pragma("unroll") for (int n = 0; n < 2; ++n) _Pragma("unroll") for (int k = 0; k < 2; ++k) \
;         acc[ai][bj][m][n] = __builtin_amdgcn_mfma_f32_16x16x32_bf16(Bt[n][k], At[m][k], acc[ai][bj][m][n], 0, 0, 0); __builtin_amdgcn_s_setprio(0); } while (0)
; #define PG8_WAIT_V(n) asm volatile("s_waitcnt vmcnt(" #n ")" ::: "memory")
; #define PG8_WAIT_L(n) asm volatile("s_waitcnt lgkmcnt(" #n ")" ::: "memory")
; #define PG8_BAR __builtin_amdgcn_s_barrier()
; #define PG8_SCHED __builtin_amdgcn_sched_barrier(0)
; template <class Epi>
; DI void gemm_phase(LAS unsigned char* lds, const Gemm g, const Order& S, const Epi& E) {
;     ...
;             PG8_LDA(At, 1, 1); PG8_STAGE(PG8_SB(1, 0), b3, voffB); PG8_STAGE(PG8_SB(1, 1), b3 + hstepB, voffB); PG8_STAGE(PG8_SA(1, 0), a3, voffA);
;             PG8_WAIT_V(8); PG8_WAIT_L(0); PG8_BAR; PG8_MMA(1, 0, At, B0); PG8_MMA(1, 1, At, B1); PG8_BAR; PG8_SCHED;
;         }
	s_add_i32 s27, s27, s69
	v_lshl_add_u64 v[200:201], v[200:201], 0, s[56:57]
	s_mov_b32 m0, s27
	ds_read_b128 v[160:163], v205 offset:49152
	ds_read_b128 v[164:167], v205 offset:50176
	ds_read_b128 v[168:171], v205 offset:51200
	ds_read_b128 v[172:175], v205 offset:52224
	ds_read_b128 v[188:191], v205 offset:53248
	ds_read_b128 v[192:195], v205 offset:54272
	ds_read_b128 v[196:199], v205 offset:55296
	ds_read_b128 v[206:209], v205 offset:56320
	global_load_lds_dwordx4 v[200:201], off
	s_add_i32 m0, s27, 0x2000
	s_add_u32 s34, s34, 0x200080
	v_lshl_add_u64 v[200:201], v[210:211], 0, s[56:57]
	s_addc_u32 s35, s35, 0
	s_add_i32 s27, s87, s69
	global_load_lds_dwordx4 v[200:201], off
	v_lshl_add_u64 v[200:201], s[34:35], 0, v[176:177]
	s_mov_b32 m0, s27
	s_nop 0
	global_load_lds_dwordx4 v[200:201], off
	v_lshl_add_u64 v[200:201], s[34:35], 0, v[182:183]
	s_add_i32 m0, s27, 0x2000
	s_nop 0
	global_load_lds_dwordx4 v[200:201], off
	v_lshl_add_u64 v[200:201], v[212:213], 0, s[56:57]
	s_mov_b32 m0, s82
	s_nop 0
	global_load_lds_dwordx4 v[200:201], off
	v_lshl_add_u64 v[200:201], v[214:215], 0, s[56:57]
	s_mov_b32 m0, s83
	s_nop 0
	global_load_lds_dwordx4 v[200:201], off
	s_waitcnt vmcnt(8)
	s_waitcnt lgkmcnt(0)
	s_barrier
	s_setprio 1
	v_mfma_f32_16x16x32_bf16 v[60:63], v[96:99], v[160:163], v[60:63]
	v_mfma_f32_16x16x32_bf16 v[56:59], v[112:115], v[160:163], v[56:59]
	v_mfma_f32_16x16x32_bf16 v[44:47], v[96:99], v[168:171], v[44:47]
	v_mfma_f32_16x16x32_bf16 v[40:43], v[112:115], v[168:171], v[40:43]
	v_mfma_f32_16x16x32_bf16 v[28:31], v[96:99], v[188:191], v[28:31]
	v_mfma_f32_16x16x32_bf16 v[24:27], v[112:115], v[188:191], v[24:27]
	v_mfma_f32_16x16x32_bf16 v[12:15], v[96:99], v[196:199], v[12:15]
	v_mfma_f32_16x16x32_bf16 v[8:11], v[112:115], v[196:199], v[8:11]
	v_mfma_f32_16x16x32_bf16 v[60:63], v[104:107], v[164:167], v[60:63]
	v_mfma_f32_16x16x32_bf16 v[56:59], v[120:123], v[164:167], v[56:59]
	v_mfma_f32_16x16x32_bf16 v[44:47], v[104:107], v[172:175], v[44:47]
	v_mfma_f32_16x16x32_bf16 v[40:43], v[120:123], v[172:175], v[40:43]
	v_mfma_f32_16x16x32_bf16 v[28:31], v[104:107], v[192:195], v[28:31]
	v_mfma_f32_16x16x32_bf16 v[24:27], v[120:123], v[192:195], v[24:27]
	v_mfma_f32_16x16x32_bf16 v[12:15], v[104:107], v[206:209], v[12:15]
	v_mfma_f32_16x16x32_bf16 v[8:11], v[120:123], v[206:209], v[8:11]
	s_setprio 0
	s_setprio 1
	v_mfma_f32_16x16x32_bf16 v[52:55], v[144:147], v[160:163], v[52:55]
	v_mfma_f32_16x16x32_bf16 v[48:51], v[152:155], v[160:163], v[48:51]
	v_mfma_f32_16x16x32_bf16 v[36:39], v[144:147], v[168:171], v[36:39]
	v_mfma_f32_16x16x32_bf16 v[32:35], v[152:155], v[168:171], v[32:35]
	v_mfma_f32_16x16x32_bf16 v[20:23], v[144:147], v[188:191], v[20:23]
	v_mfma_f32_16x16x32_bf16 v[16:19], v[152:155], v[188:191], v[16:19]
	v_mfma_f32_16x16x32_bf16 v[4:7], v[144:147], v[196:199], v[4:7]
	v_mfma_f32_16x16x32_bf16 v[0:3], v[152:155], v[196:199], v[0:3]
	v_mfma_f32_16x16x32_bf16 v[52:55], v[148:151], v[164:167], v[52:55]
	v_mfma_f32_16x16x32_bf16 v[48:51], v[156:159], v[164:167], v[48:51]
	v_mfma_f32_16x16x32_bf16 v[36:39], v[148:151], v[172:175], v[36:39]
	v_mfma_f32_16x16x32_bf16 v[32:35], v[156:159], v[172:175], v[32:35]
	v_mfma_f32_16x16x32_bf16 v[20:23], v[148:151], v[192:195], v[20:23]
	v_mfma_f32_16x16x32_bf16 v[16:19], v[156:159], v[192:195], v[16:19]
	v_mfma_f32_16x16x32_bf16 v[4:7], v[148:151], v[206:209], v[4:7]
	v_mfma_f32_16x16x32_bf16 v[0:3], v[156:159], v[206:209], v[0:3]
	s_setprio 0
	s_barrier
	s_add_u32 s19, s19, 0x100
	s_addc_u32 s21, s21, 0
	s_add_u32 s30, s30, 0x100
	s_addc_u32 s31, s31, 0
	s_cmp_ge_i32 s86, s79
	s_mov_b32 s27, s86
	s_cbranch_scc0 .LBB0_1003

; #define PG8_STAGE(bufoff, gbase, voff) do { _Pragma("unroll") for (int _i = 0; _i < 2; ++_i) \
;         __builtin_amdgcn_global_load_lds((const unsigned*)((const char*)(gbase) + (voff)[_i]), (LAS unsigned*)(lds + (bufoff) + ldsw + _i * 8192), 16, 0, 0); } while (0)
; #define PG8_LDA(dst, b, h) do { _Pragma("unroll") for (int m = 0; m < 4; ++m) _Pragma("unroll") for (int k = 0; k < 2; ++k) dst[m][k] = *(const LAS bf16x8*)(lds + PG8_SA(b, h) + aoff + m * 2048 + k * 1024); } while (0)
; #define PG8_LDB(dst, b, h) do { _Pragma("unroll") for (int n = 0; n < 2; ++n) _Pragma("unroll") for (int k = 0; k < 2; ++k) dst[n][k] = *(const LAS bf16x8*)(lds + PG8_SB(b, h) + boff + n * 2048 + k * 1024); } while (0)
; #define PG8_MMA(ai, bj, At, Bt) do { __builtin_amdgcn_s_setprio(1); _Pragma("unroll") for (int m = 0; m < 4; ++m) _Pragma("unroll") for (int n = 0; n < 2; ++n) _Pragma("unroll") for (int k = 0; k < 2; ++k) \
;         acc[ai][bj][m][n] = __builtin_amdgcn_mfma_f32_16x16x32_bf16(Bt[n][k], At[m][k], acc[ai][bj][m][n], 0, 0, 0); __builtin_amdgcn_s_setprio(0); } while (0)
; #define PG8_WAIT_V(n) asm volatile("s_waitcnt vmcnt(" #n ")" ::: "memory")
; #define PG8_WAIT_L(n) asm volatile("s_waitcnt lgkmcnt(" #n ")" ::: "memory")
; #define PG8_BAR __builtin_amdgcn_s_barrier()
; #define PG8_SCHED __builtin_amdgcn_sched_barrier(0)
; template <class Epi>
; DI void gemm_phase(LAS unsigned char* lds, const Gemm g, const Order& S, const Epi& E) {
;     ...
;         for (int t = 0; t < nt; t += 2) {
;             const bool last = (t == nt - 2);
;             const char* a1 = cA + (size_t)(t + 1) * kstep;
;             const char* a2 = last ? nA : cA + (size_t)(t + 2) * kstep; const char* b2 = last ? nB : cB + (size_t)(t + 2) * kstep;
;             const char* a3 = a2 + kstep; const char* b3 = b2 + kstep;
;             PG8_LDB(B0, 0, 0); PG8_LDB(B1, 0, 1); PG8_SCHED; PG8_LDA(At, 0, 0); PG8_STAGE(PG8_SA(1, 1), a1 + hstepA, voffA);
;             PG8_WAIT_V(8); PG8_WAIT_L(0); PG8_BAR; PG8_MMA(0, 0, At, B0); PG8_MMA(0, 1, At, B1); PG8_BAR; PG8_SCHED;
;             PG8_LDA(At, 0, 1); PG8_STAGE(PG8_SB(0, 0), b2, voffB); PG8_STAGE(PG8_SB(0, 1), b2 + hstepB, voffB); PG8_STAGE(PG8_SA(0, 0), a2, voffA);
;             PG8_WAIT_V(8); PG8_WAIT_L(0); PG8_BAR; PG8_MMA(1, 0, At, B0); PG8_MMA(1, 1, At, B1); PG8_BAR; PG8_SCHED;
.LBB0_1092:
	s_add_i32 s82, s19, 2
	s_add_u32 s26, s24, 0xffe00080
	s_addc_u32 s27, s25, -1
	s_add_i32 s83, 0, 0x10000
	s_cmp_eq_u32 s77, s19
	s_cselect_b32 s29, s21, s27
	s_cselect_b32 s28, s20, s26
	s_cselect_b32 s27, s23, s17
	s_cselect_b32 s26, s22, s15
	s_add_i32 s19, 0, 0x14000
	v_add_u32_e32 v154, s83, v140
	v_add_u32_e32 v170, s19, v140
	ds_read_b128 v[142:145], v154
	ds_read_b128 v[146:149], v154 offset:1024
	ds_read_b128 v[150:153], v154 offset:2048
	ds_read_b128 v[154:157], v154 offset:3072
	ds_read_b128 v[158:161], v170
	ds_read_b128 v[162:165], v170 offset:1024
	ds_read_b128 v[166:169], v170 offset:2048
	ds_read_b128 v[170:173], v170 offset:3072
	v_lshl_add_u64 v[174:175], s[24:25], 0, v[136:137]
	s_add_i32 m0, s64, 0xc000
	ds_read_b128 v[178:181], v141
	ds_read_b128 v[182:185], v141 offset:1024
	ds_read_b128 v[186:189], v141 offset:2048
	ds_read_b128 v[190:193], v141 offset:3072
	ds_read_b128 v[194:197], v141 offset:4096
	ds_read_b128 v[198:201], v141 offset:5120
	ds_read_b128 v[202:205], v141 offset:6144
	ds_read_b128 v[206:209], v141 offset:7168
	global_load_lds_dwordx4 v[174:175], off
	v_lshl_add_u64 v[174:175], s[24:25], 0, v[134:135]
	s_add_i32 m0, s64, 0xe000
	s_nop 0
	global_load_lds_dwordx4 v[174:175], off
	s_waitcnt vmcnt(8)
	s_waitcnt lgkmcnt(0)
	s_barrier
	s_setprio 1
	v_mfma_f32_16x16x32_bf16 v[124:127], v[142:145], v[178:181], v[124:127]
	v_mfma_f32_16x16x32_bf16 v[120:123], v[150:153], v[178:181], v[120:123]
	v_mfma_f32_16x16x32_bf16 v[108:111], v[142:145], v[186:189], v[108:111]
	v_mfma_f32_16x16x32_bf16 v[104:107], v[150:153], v[186:189], v[104:107]
	v_mfma_f32_16x16x32_bf16 v[92:95], v[142:145], v[194:197], v[92:95]
	v_mfma_f32_16x16x32_bf16 v[88:91], v[150:153], v[194:197], v[88:91]
	v_mfma_f32_16x16x32_bf16 v[76:79], v[142:145], v[202:205], v[76:79]
	v_mfma_f32_16x16x32_bf16 v[72:75], v[150:153], v[202:205], v[72:75]
	v_mfma_f32_16x16x32_bf16 v[124:127], v[146:149], v[182:185], v[124:127]
	v_mfma_f32_16x16x32_bf16 v[120:123], v[154:157], v[182:185], v[120:123]
	v_mfma_f32_16x16x32_bf16 v[108:111], v[146:149], v[190:193], v[108:111]
	v_mfma_f32_16x16x32_bf16 v[104:107], v[154:157], v[190:193], v[104:107]
	v_mfma_f32_16x16x32_bf16 v[92:95], v[146:149], v[198:201], v[92:95]
	v_mfma_f32_16x16x32_bf16 v[88:91], v[154:157], v[198:201], v[88:91]
	v_mfma_f32_16x16x32_bf16 v[76:79], v[146:149], v[206:209], v[76:79]
	v_mfma_f32_16x16x32_bf16 v[72:75], v[154:157], v[206:209], v[72:75]
	s_setprio 0
	s_setprio 1
	v_mfma_f32_16x16x32_bf16 v[116:119], v[158:161], v[178:181], v[116:119]
	v_mfma_f32_16x16x32_bf16 v[112:115], v[166:169], v[178:181], v[112:115]
	v_mfma_f32_16x16x32_bf16 v[100:103], v[158:161], v[186:189], v[100:103]
	v_mfma_f32_16x16x32_bf16 v[96:99], v[166:169], v[186:189], v[96:99]
	v_mfma_f32_16x16x32_bf16 v[84:87], v[158:161], v[194:197], v[84:87]
	v_mfma_f32_16x16x32_bf16 v[80:83], v[166:169], v[194:197], v[80:83]
	v_mfma_f32_16x16x32_bf16 v[68:71], v[158:161], v[202:205], v[68:71]
	v_mfma_f32_16x16x32_bf16 v[64:67], v[166:169], v[202:205], v[64:67]
	v_mfma_f32_16x16x32_bf16 v[116:119], v[162:165], v[182:185], v[116:119]
	v_mfma_f32_16x16x32_bf16 v[112:115], v[170:173], v[182:185], v[112:115]
	v_mfma_f32_16x16x32_bf16 v[100:103], v[162:165], v[190:193], v[100:103]
	v_mfma_f32_16x16x32_bf16 v[96:99], v[170:173], v[190:193], v[96:99]
	v_mfma_f32_16x16x32_bf16 v[84:87], v[162:165], v[198:201], v[84:87]
	v_mfma_f32_16x16x32_bf16 v[80:83], v[170:173], v[198:201], v[80:83]
	v_mfma_f32_16x16x32_bf16 v[68:71], v[162:165], v[206:209], v[68:71]
	v_mfma_f32_16x16x32_bf16 v[64:67], v[170:173], v[206:209], v[64:67]
	s_setprio 0
	s_barrier
	s_add_i32 s83, s83, s40
	v_lshl_add_u64 v[174:175], s[26:27], 0, v[176:177]
	s_mov_b32 m0, s83
	ds_read_b128 v[178:181], v141 offset:16384
	ds_read_b128 v[182:185], v141 offset:17408
	ds_read_b128 v[186:189], v141 offset:18432
	ds_read_b128 v[190:193], v141 offset:19456
	ds_read_b128 v[194:197], v141 offset:20480
	ds_read_b128 v[198:201], v141 offset:21504
	ds_read_b128 v[202:205], v141 offset:22528
	ds_read_b128 v[206:209], v141 offset:23552
	global_load_lds_dwordx4 v[174:175], off
	s_add_i32 m0, s83, 0x2000
	s_add_u32 s84, s26, 0x200000
	v_lshl_add_u64 v[210:211], s[26:27], 0, v[128:129]
	s_addc_u32 s85, s27, 0
	s_add_i32 s19, s19, s40
	global_load_lds_dwordx4 v[210:211], off
	v_lshl_add_u64 v[212:213], s[84:85], 0, v[176:177]
	s_mov_b32 m0, s19
	v_lshl_add_u64 v[214:215], s[28:29], 0, v[130:131]
	global_load_lds_dwordx4 v[212:213], off
	v_lshl_add_u64 v[212:213], s[84:85], 0, v[128:129]
	s_add_i32 m0, s19, 0x2000
	s_nop 0
	global_load_lds_dwordx4 v[212:213], off
	v_lshl_add_u64 v[212:213], s[28:29], 0, v[132:133]
	s_mov_b32 m0, s64
	s_nop 0
	global_load_lds_dwordx4 v[212:213], off
	s_mov_b32 m0, s65
	s_nop 0
	global_load_lds_dwordx4 v[214:215], off
	s_waitcnt vmcnt(8)
	s_waitcnt lgkmcnt(0)
	s_barrier
; #define PG8_STAGE(bufoff, gbase, voff) do { _Pragma("unroll") for (int _i = 0; _i < 2; ++_i) \
;         __builtin_amdgcn_global_load_lds((const unsigned*)((const char*)(gbase) + (voff)[_i]), (LAS unsigned*)(lds + (bufoff) + ldsw + _i * 8192), 16, 0, 0); } while (0)
; #define PG8_LDA(dst, b, h) do { _Pragma("unroll") for (int m = 0; m < 4; ++m) _Pragma("unroll") for (int k = 0; k < 2; ++k) dst[m][k] = *(const LAS bf16x8*)(lds + PG8_SA(b, h) + aoff + m * 2048 + k * 1024); } while (0)
; #define PG8_LDB(dst, b, h) do { _Pragma("unroll") for (int n = 0; n < 2; ++n) _Pragma("unroll") for (int k = 0; k < 2; ++k) dst[n][k] = *(const LAS bf16x8*)(lds + PG8_SB(b, h) + boff + n * 2048 + k * 1024); } while (0)
; #define PG8_MMA(ai, bj, At, Bt) do { __builtin_amdgcn_s_setprio(1); _Pragma("unroll") for (int m = 0; m < 4; ++m) _Pragma("unroll") for (int n = 0; n < 2; ++n) _Pragma("unroll") for (int k = 0; k < 2; ++k) \
;         acc[ai][bj][m][n] = __builtin_amdgcn_mfma_f32_16x16x32_bf16(Bt[n][k], At[m][k], acc[ai][bj][m][n], 0, 0, 0); __builtin_amdgcn_s_setprio(0); } while (0)
; #define PG8_WAIT_V(n) asm volatile("s_waitcnt vmcnt(" #n ")" ::: "memory")
; #define PG8_WAIT_L(n) asm volatile("s_waitcnt lgkmcnt(" #n ")" ::: "memory")
; #define PG8_BAR __builtin_amdgcn_s_barrier()
; #define PG8_SCHED __builtin_amdgcn_sched_barrier(0)
; template <class Epi>
; DI void gemm_phase(LAS unsigned char* lds, const Gemm g, const Order& S, const Epi& E) {
;     ...
;             PG8_WAIT_V(8); PG8_WAIT_L(0); PG8_BAR; PG8_MMA(1, 0, At, B0); PG8_MMA(1, 1, At, B1); PG8_BAR; PG8_SCHED;
;             PG8_LDB(B0, 1, 0); PG8_LDB(B1, 1, 1); PG8_SCHED; PG8_LDA(At, 1, 0); PG8_STAGE(PG8_SA(0, 1), a2 + hstepA, voffA);
;             PG8_WAIT_V(8); PG8_WAIT_L(0); PG8_BAR; PG8_MMA(0, 0, At, B0); PG8_MMA(0, 1, At, B1); PG8_BAR; PG8_SCHED;
	s_setprio 1
	v_mfma_f32_16x16x32_bf16 v[60:63], v[142:145], v[178:181], v[60:63]
	v_mfma_f32_16x16x32_bf16 v[56:59], v[150:153], v[178:181], v[56:59]
	v_mfma_f32_16x16x32_bf16 v[44:47], v[142:145], v[186:189], v[44:47]
	v_mfma_f32_16x16x32_bf16 v[40:43], v[150:153], v[186:189], v[40:43]
	v_mfma_f32_16x16x32_bf16 v[28:31], v[142:145], v[194:197], v[28:31]
	v_mfma_f32_16x16x32_bf16 v[24:27], v[150:153], v[194:197], v[24:27]
	v_mfma_f32_16x16x32_bf16 v[12:15], v[142:145], v[202:205], v[12:15]
	v_mfma_f32_16x16x32_bf16 v[8:11], v[150:153], v[202:205], v[8:11]
	v_mfma_f32_16x16x32_bf16 v[60:63], v[146:149], v[182:185], v[60:63]
	v_mfma_f32_16x16x32_bf16 v[56:59], v[154:157], v[182:185], v[56:59]
	v_mfma_f32_16x16x32_bf16 v[44:47], v[146:149], v[190:193], v[44:47]
	v_mfma_f32_16x16x32_bf16 v[40:43], v[154:157], v[190:193], v[40:43]
	v_mfma_f32_16x16x32_bf16 v[28:31], v[146:149], v[198:201], v[28:31]
	v_mfma_f32_16x16x32_bf16 v[24:27], v[154:157], v[198:201], v[24:27]
	v_mfma_f32_16x16x32_bf16 v[12:15], v[146:149], v[206:209], v[12:15]
	v_mfma_f32_16x16x32_bf16 v[8:11], v[154:157], v[206:209], v[8:11]
	s_setprio 0
	s_setprio 1
	v_mfma_f32_16x16x32_bf16 v[52:55], v[158:161], v[178:181], v[52:55]
	v_mfma_f32_16x16x32_bf16 v[48:51], v[166:169], v[178:181], v[48:51]
	v_mfma_f32_16x16x32_bf16 v[36:39], v[158:161], v[186:189], v[36:39]
	v_mfma_f32_16x16x32_bf16 v[32:35], v[166:169], v[186:189], v[32:35]
	v_mfma_f32_16x16x32_bf16 v[20:23], v[158:161], v[194:197], v[20:23]
	v_mfma_f32_16x16x32_bf16 v[16:19], v[166:169], v[194:197], v[16:19]
	v_mfma_f32_16x16x32_bf16 v[4:7], v[158:161], v[202:205], v[4:7]
	v_mfma_f32_16x16x32_bf16 v[0:3], v[166:169], v[202:205], v[0:3]
	v_mfma_f32_16x16x32_bf16 v[52:55], v[162:165], v[182:185], v[52:55]
	v_mfma_f32_16x16x32_bf16 v[48:51], v[170:173], v[182:185], v[48:51]
	v_mfma_f32_16x16x32_bf16 v[36:39], v[162:165], v[190:193], v[36:39]
	v_mfma_f32_16x16x32_bf16 v[32:35], v[170:173], v[190:193], v[32:35]
	v_mfma_f32_16x16x32_bf16 v[20:23], v[162:165], v[198:201], v[20:23]
	v_mfma_f32_16x16x32_bf16 v[16:19], v[170:173], v[198:201], v[16:19]
	v_mfma_f32_16x16x32_bf16 v[4:7], v[162:165], v[206:209], v[4:7]
	v_mfma_f32_16x16x32_bf16 v[0:3], v[170:173], v[206:209], v[0:3]
	s_setprio 0
	s_barrier
	s_add_i32 s19, 0, 0x18000
	s_add_i32 s83, 0, 0x1c000
	v_add_u32_e32 v154, s19, v140
	v_add_u32_e32 v170, s83, v140
	ds_read_b128 v[142:145], v154
	ds_read_b128 v[146:149], v154 offset:1024
	ds_read_b128 v[150:153], v154 offset:2048
	ds_read_b128 v[154:157], v154 offset:3072
	ds_read_b128 v[158:161], v170
	ds_read_b128 v[162:165], v170 offset:1024
	ds_read_b128 v[166:169], v170 offset:2048
	ds_read_b128 v[170:173], v170 offset:3072
	s_add_u32 s28, s28, 0x200000
	s_addc_u32 s29, s29, 0
	s_mov_b32 m0, s68
	v_lshl_add_u64 v[216:217], s[28:29], 0, v[132:133]
	ds_read_b128 v[178:181], v141 offset:32768
	ds_read_b128 v[182:185], v141 offset:33792
	ds_read_b128 v[186:189], v141 offset:34816
	ds_read_b128 v[190:193], v141 offset:35840
	ds_read_b128 v[194:197], v141 offset:36864
	ds_read_b128 v[198:201], v141 offset:37888
	ds_read_b128 v[202:205], v141 offset:38912
	ds_read_b128 v[206:209], v141 offset:39936
	global_load_lds_dwordx4 v[216:217], off
	v_lshl_add_u64 v[216:217], s[28:29], 0, v[130:131]
	s_mov_b32 m0, s69
	s_nop 0
	global_load_lds_dwordx4 v[216:217], off
	s_waitcnt vmcnt(8)
	s_waitcnt lgkmcnt(0)
	s_barrier
	s_setprio 1
	v_mfma_f32_16x16x32_bf16 v[124:127], v[142:145], v[178:181], v[124:127]
	v_mfma_f32_16x16x32_bf16 v[120:123], v[150:153], v[178:181], v[120:123]
	v_mfma_f32_16x16x32_bf16 v[108:111], v[142:145], v[186:189], v[108:111]
	v_mfma_f32_16x16x32_bf16 v[104:107], v[150:153], v[186:189], v[104:107]
	v_mfma_f32_16x16x32_bf16 v[92:95], v[142:145], v[194:197], v[92:95]
	v_mfma_f32_16x16x32_bf16 v[88:91], v[150:153], v[194:197], v[88:91]
	v_mfma_f32_16x16x32_bf16 v[76:79], v[142:145], v[202:205], v[76:79]
	v_mfma_f32_16x16x32_bf16 v[72:75], v[150:153], v[202:205], v[72:75]
	v_mfma_f32_16x16x32_bf16 v[124:127], v[146:149], v[182:185], v[124:127]
	v_mfma_f32_16x16x32_bf16 v[120:123], v[154:157], v[182:185], v[120:123]
	v_mfma_f32_16x16x32_bf16 v[108:111], v[146:149], v[190:193], v[108:111]
	v_mfma_f32_16x16x32_bf16 v[104:107], v[154:157], v[190:193], v[104:107]
	v_mfma_f32_16x16x32_bf16 v[92:95], v[146:149], v[198:201], v[92:95]
	v_mfma_f32_16x16x32_bf16 v[88:91], v[154:157], v[198:201], v[88:91]
	v_mfma_f32_16x16x32_bf16 v[76:79], v[146:149], v[206:209], v[76:79]
	v_mfma_f32_16x16x32_bf16 v[72:75], v[154:157], v[206:209], v[72:75]
	s_setprio 0
	s_setprio 1
	v_mfma_f32_16x16x32_bf16 v[116:119], v[158:161], v[178:181], v[116:119]
	v_mfma_f32_16x16x32_bf16 v[112:115], v[166:169], v[178:181], v[112:115]
	v_mfma_f32_16x16x32_bf16 v[100:103], v[158:161], v[186:189], v[100:103]
	v_mfma_f32_16x16x32_bf16 v[96:99], v[166:169], v[186:189], v[96:99]
	v_mfma_f32_16x16x32_bf16 v[84:87], v[158:161], v[194:197], v[84:87]
	v_mfma_f32_16x16x32_bf16 v[80:83], v[166:169], v[194:197], v[80:83]
	v_mfma_f32_16x16x32_bf16 v[68:71], v[158:161], v[202:205], v[68:71]
	v_mfma_f32_16x16x32_bf16 v[64:67], v[166:169], v[202:205], v[64:67]
	v_mfma_f32_16x16x32_bf16 v[116:119], v[162:165], v[182:185], v[116:119]
	v_mfma_f32_16x16x32_bf16 v[112:115], v[170:173], v[182:185], v[112:115]
	v_mfma_f32_16x16x32_bf16 v[100:103], v[162:165], v[190:193], v[100:103]
	v_mfma_f32_16x16x32_bf16 v[96:99], v[170:173], v[190:193], v[96:99]
	v_mfma_f32_16x16x32_bf16 v[84:87], v[162:165], v[198:201], v[84:87]
	v_mfma_f32_16x16x32_bf16 v[80:83], v[170:173], v[198:201], v[80:83]
	v_mfma_f32_16x16x32_bf16 v[68:71], v[162:165], v[206:209], v[68:71]
	v_mfma_f32_16x16x32_bf16 v[64:67], v[170:173], v[206:209], v[64:67]
	s_setprio 0
	s_barrier
; #define PG8_STAGE(bufoff, gbase, voff) do { _Pragma("unroll") for (int _i = 0; _i < 2; ++_i) \
;         __builtin_amdgcn_global_load_lds((const unsigned*)((const char*)(gbase) + (voff)[_i]), (LAS unsigned*)(lds + (bufoff) + ldsw + _i * 8192), 16, 0, 0); } while (0)
; #define PG8_LDA(dst, b, h) do { _Pragma("unroll") for (int m = 0; m < 4; ++m) _Pragma("unroll") for (int k = 0; k < 2; ++k) dst[m][k] = *(const LAS bf16x8*)(lds + PG8_SA(b, h) + aoff + m * 2048 + k * 1024); } while (0)
; #define PG8_MMA(ai, bj, At, Bt) do { __builtin_amdgcn_s_setprio(1); _Pragma("unroll") for (int m = 0; m < 4; ++m) _Pragma("unroll") for (int n = 0; n < 2; ++n) _Pragma("unroll") for (int k = 0; k < 2; ++k) \
;         acc[ai][bj][m][n] = __builtin_amdgcn_mfma_f32_16x16x32_bf16(Bt[n][k], At[m][k], acc[ai][bj][m][n], 0, 0, 0); __builtin_amdgcn_s_setprio(0); } while (0)
; #define PG8_WAIT_V(n) asm volatile("s_waitcnt vmcnt(" #n ")" ::: "memory")
; #define PG8_WAIT_L(n) asm volatile("s_waitcnt lgkmcnt(" #n ")" ::: "memory")
; #define PG8_BAR __builtin_amdgcn_s_barrier()
; #define PG8_SCHED __builtin_amdgcn_sched_barrier(0)
; template <class Epi>
; DI void gemm_phase(LAS unsigned char* lds, const Gemm g, const Order& S, const Epi& E) {
;     ...
;             PG8_LDA(At, 1, 1); PG8_STAGE(PG8_SB(1, 0), b3, voffB); PG8_STAGE(PG8_SB(1, 1), b3 + hstepB, voffB); PG8_STAGE(PG8_SA(1, 0), a3, voffA);
;             PG8_WAIT_V(8); PG8_WAIT_L(0); PG8_BAR; PG8_MMA(1, 0, At, B0); PG8_MMA(1, 1, At, B1); PG8_BAR; PG8_SCHED;
;         }
	s_add_i32 s19, s19, s40
	v_lshl_add_u64 v[174:175], v[174:175], 0, s[56:57]
	s_mov_b32 m0, s19
	ds_read_b128 v[178:181], v141 offset:49152
	ds_read_b128 v[182:185], v141 offset:50176
	ds_read_b128 v[186:189], v141 offset:51200
	ds_read_b128 v[190:193], v141 offset:52224
	ds_read_b128 v[194:197], v141 offset:53248
	ds_read_b128 v[198:201], v141 offset:54272
	ds_read_b128 v[202:205], v141 offset:55296
	ds_read_b128 v[206:209], v141 offset:56320
	global_load_lds_dwordx4 v[174:175], off
	s_add_i32 m0, s19, 0x2000
	s_add_u32 s26, s26, 0x200080
	v_lshl_add_u64 v[174:175], v[210:211], 0, s[56:57]
	s_addc_u32 s27, s27, 0
	s_add_i32 s19, s83, s40
	global_load_lds_dwordx4 v[174:175], off
	v_lshl_add_u64 v[174:175], s[26:27], 0, v[176:177]
	s_mov_b32 m0, s19
	s_nop 0
	global_load_lds_dwordx4 v[174:175], off
	v_lshl_add_u64 v[174:175], s[26:27], 0, v[128:129]
	s_add_i32 m0, s19, 0x2000
	s_nop 0
	global_load_lds_dwordx4 v[174:175], off
	v_lshl_add_u64 v[174:175], v[212:213], 0, s[56:57]
	s_mov_b32 m0, s75
	s_nop 0
	global_load_lds_dwordx4 v[174:175], off
	v_lshl_add_u64 v[174:175], v[214:215], 0, s[56:57]
	s_mov_b32 m0, s76
	s_nop 0
	global_load_lds_dwordx4 v[174:175], off
	s_waitcnt vmcnt(8)
	s_waitcnt lgkmcnt(0)
	s_barrier
	s_setprio 1
	v_mfma_f32_16x16x32_bf16 v[60:63], v[142:145], v[178:181], v[60:63]
	v_mfma_f32_16x16x32_bf16 v[56:59], v[150:153], v[178:181], v[56:59]
	v_mfma_f32_16x16x32_bf16 v[44:47], v[142:145], v[186:189], v[44:47]
	v_mfma_f32_16x16x32_bf16 v[40:43], v[150:153], v[186:189], v[40:43]
	v_mfma_f32_16x16x32_bf16 v[28:31], v[142:145], v[194:197], v[28:31]
	v_mfma_f32_16x16x32_bf16 v[24:27], v[150:153], v[194:197], v[24:27]
	v_mfma_f32_16x16x32_bf16 v[12:15], v[142:145], v[202:205], v[12:15]
	v_mfma_f32_16x16x32_bf16 v[8:11], v[150:153], v[202:205], v[8:11]
	v_mfma_f32_16x16x32_bf16 v[60:63], v[146:149], v[182:185], v[60:63]
	v_mfma_f32_16x16x32_bf16 v[56:59], v[154:157], v[182:185], v[56:59]
	v_mfma_f32_16x16x32_bf16 v[44:47], v[146:149], v[190:193], v[44:47]
	v_mfma_f32_16x16x32_bf16 v[40:43], v[154:157], v[190:193], v[40:43]
	v_mfma_f32_16x16x32_bf16 v[28:31], v[146:149], v[198:201], v[28:31]
	v_mfma_f32_16x16x32_bf16 v[24:27], v[154:157], v[198:201], v[24:27]
	v_mfma_f32_16x16x32_bf16 v[12:15], v[146:149], v[206:209], v[12:15]
	v_mfma_f32_16x16x32_bf16 v[8:11], v[154:157], v[206:209], v[8:11]
	s_setprio 0
	s_setprio 1
	v_mfma_f32_16x16x32_bf16 v[52:55], v[158:161], v[178:181], v[52:55]
	v_mfma_f32_16x16x32_bf16 v[48:51], v[166:169], v[178:181], v[48:51]
	v_mfma_f32_16x16x32_bf16 v[36:39], v[158:161], v[186:189], v[36:39]
	v_mfma_f32_16x16x32_bf16 v[32:35], v[166:169], v[186:189], v[32:35]
	v_mfma_f32_16x16x32_bf16 v[20:23], v[158:161], v[194:197], v[20:23]
	v_mfma_f32_16x16x32_bf16 v[16:19], v[166:169], v[194:197], v[16:19]
	v_mfma_f32_16x16x32_bf16 v[4:7], v[158:161], v[202:205], v[4:7]
	v_mfma_f32_16x16x32_bf16 v[0:3], v[166:169], v[202:205], v[0:3]
	v_mfma_f32_16x16x32_bf16 v[52:55], v[162:165], v[182:185], v[52:55]
	v_mfma_f32_16x16x32_bf16 v[48:51], v[170:173], v[182:185], v[48:51]
	v_mfma_f32_16x16x32_bf16 v[36:39], v[162:165], v[190:193], v[36:39]
	v_mfma_f32_16x16x32_bf16 v[32:35], v[170:173], v[190:193], v[32:35]
	v_mfma_f32_16x16x32_bf16 v[20:23], v[162:165], v[198:201], v[20:23]
	v_mfma_f32_16x16x32_bf16 v[16:19], v[170:173], v[198:201], v[16:19]
	v_mfma_f32_16x16x32_bf16 v[4:7], v[162:165], v[206:209], v[4:7]
	v_mfma_f32_16x16x32_bf16 v[0:3], v[170:173], v[206:209], v[0:3]
	s_setprio 0
	s_barrier
	s_add_u32 s15, s15, 0x100
	s_addc_u32 s17, s17, 0
	s_add_u32 s24, s24, 0x100
	s_addc_u32 s25, s25, 0
	s_cmp_ge_i32 s82, s72
	s_mov_b32 s19, s82
	s_cbranch_scc0 .LBB0_1092
	s_mov_b32 s82, 0x3a490fdb
	s_mov_b32 s84, 0x3bb504f3
